# weight-conversion item loops (both layers): both 16-load trips issued before the first LDS write (second trip on renamed registers), one memory round trip per item instead of two
# speedup vs baseline: 1.0046x; 1.0046x over previous
.LBB0_15:
	s_lshl_b32 s36, s27, 1
	s_lshl_b32 s37, s28, 1
	v_or_b32_e32 v24, s37, v8
	s_add_i32 s38, s36, 4
	s_add_i32 s39, s37, 4
	s_add_i32 s40, s36, 8
	s_add_i32 s41, s37, 8
	s_add_i32 s42, s36, 12
	s_add_i32 s43, s37, 12
	s_add_i32 s44, s36, 16
	s_add_i32 s45, s37, 16
	s_add_i32 s46, s36, 20
	s_add_i32 s47, s37, 20
	s_add_i32 s48, s36, 24
	s_add_i32 s49, s37, 24
	s_add_i32 s50, s36, 28
	s_add_i32 s51, s37, 28
	v_or_b32_e32 v22, s36, v3
	v_ashrrev_i32_e32 v25, 31, v24
	v_or_b32_e32 v26, s38, v3
	v_or_b32_e32 v28, s39, v8
	v_or_b32_e32 v30, s40, v3
	v_or_b32_e32 v32, s41, v8
	v_or_b32_e32 v34, s42, v3
	v_or_b32_e32 v36, s43, v8
	v_or_b32_e32 v38, s44, v3
	v_or_b32_e32 v40, s45, v8
	v_or_b32_e32 v42, s46, v3
	v_or_b32_e32 v44, s47, v8
	v_or_b32_e32 v46, s48, v3
	v_or_b32_e32 v48, s49, v8
	v_or_b32_e32 v50, s50, v3
	v_or_b32_e32 v52, s51, v8
	v_ashrrev_i32_e32 v23, 31, v22
	v_lshlrev_b64 v[24:25], 12, v[24:25]
	v_ashrrev_i32_e32 v29, 31, v28
	v_ashrrev_i32_e32 v27, 31, v26
	v_ashrrev_i32_e32 v33, 31, v32
	v_ashrrev_i32_e32 v31, 31, v30
	v_ashrrev_i32_e32 v37, 31, v36
	v_ashrrev_i32_e32 v35, 31, v34
	v_ashrrev_i32_e32 v41, 31, v40
	v_ashrrev_i32_e32 v39, 31, v38
	v_ashrrev_i32_e32 v45, 31, v44
	v_ashrrev_i32_e32 v43, 31, v42
	v_ashrrev_i32_e32 v49, 31, v48
	v_ashrrev_i32_e32 v47, 31, v46
	v_ashrrev_i32_e32 v53, 31, v52
	v_ashrrev_i32_e32 v51, 31, v50
	v_lshlrev_b64 v[22:23], 12, v[22:23]
	v_lshl_add_u64 v[24:25], v[12:13], 0, v[24:25]
	v_lshlrev_b64 v[26:27], 12, v[26:27]
	v_lshlrev_b64 v[28:29], 12, v[28:29]
	v_lshlrev_b64 v[30:31], 12, v[30:31]
	v_lshlrev_b64 v[32:33], 12, v[32:33]
	v_lshlrev_b64 v[34:35], 12, v[34:35]
	v_lshlrev_b64 v[36:37], 12, v[36:37]
	v_lshlrev_b64 v[38:39], 12, v[38:39]
	v_lshlrev_b64 v[40:41], 12, v[40:41]
	v_lshlrev_b64 v[42:43], 12, v[42:43]
	v_lshlrev_b64 v[44:45], 12, v[44:45]
	v_lshlrev_b64 v[46:47], 12, v[46:47]
	v_lshlrev_b64 v[48:49], 12, v[48:49]
	v_lshlrev_b64 v[50:51], 12, v[50:51]
	v_lshlrev_b64 v[52:53], 12, v[52:53]
	v_lshl_add_u64 v[22:23], v[12:13], 0, v[22:23]
	v_lshl_add_u64 v[28:29], v[12:13], 0, v[28:29]
	v_lshl_add_u64 v[26:27], v[12:13], 0, v[26:27]
	v_lshl_add_u64 v[32:33], v[12:13], 0, v[32:33]
	v_lshl_add_u64 v[30:31], v[12:13], 0, v[30:31]
	v_lshl_add_u64 v[36:37], v[12:13], 0, v[36:37]
	v_lshl_add_u64 v[34:35], v[12:13], 0, v[34:35]
	v_lshl_add_u64 v[40:41], v[12:13], 0, v[40:41]
	v_lshl_add_u64 v[38:39], v[12:13], 0, v[38:39]
	v_lshl_add_u64 v[44:45], v[12:13], 0, v[44:45]
	v_lshl_add_u64 v[42:43], v[12:13], 0, v[42:43]
	v_lshl_add_u64 v[48:49], v[12:13], 0, v[48:49]
	v_lshl_add_u64 v[46:47], v[12:13], 0, v[46:47]
	v_lshl_add_u64 v[52:53], v[12:13], 0, v[52:53]
	v_lshl_add_u64 v[50:51], v[12:13], 0, v[50:51]
	global_load_dword v11, v[24:25], off
	global_load_dword v14, v[22:23], off
	global_load_dword v21, v[28:29], off
	global_load_dword v54, v[26:27], off
	global_load_dword v55, v[32:33], off
	global_load_dword v56, v[30:31], off
	global_load_dword v57, v[36:37], off
	global_load_dword v58, v[34:35], off
	global_load_dword v59, v[40:41], off
	global_load_dword v60, v[38:39], off
	global_load_dword v61, v[44:45], off
	global_load_dword v62, v[42:43], off
	global_load_dword v63, v[48:49], off
	global_load_dword v64, v[46:47], off
	global_load_dword v65, v[52:53], off
	global_load_dword v66, v[50:51], off
	v_or_b32_e32 v24, s36, v1
	v_or_b32_e32 v22, s37, v4
	s_add_i32 s28, s28, 16
	s_add_i32 s27, s27, 16
	s_add_i32 s29, s29, -16
	v_mad_u64_u32 v[22:23], s[36:37], v22, s31, v[6:7]
	v_mad_u64_u32 v[24:25], s[36:37], v24, s31, v[6:7]
	v_or_b32_e32 v23, s38, v1
	v_or_b32_e32 v25, s39, v4
	v_or_b32_e32 v32, s40, v1
	v_or_b32_e32 v30, s41, v4
	v_or_b32_e32 v36, s42, v1
	v_or_b32_e32 v34, s43, v4
	v_or_b32_e32 v40, s44, v1
	v_or_b32_e32 v38, s45, v4
	v_or_b32_e32 v44, s46, v1
	v_or_b32_e32 v42, s47, v4
	v_or_b32_e32 v48, s48, v1
	v_or_b32_e32 v46, s49, v4
	v_or_b32_e32 v52, s50, v1
	v_or_b32_e32 v50, s51, v4
	s_cmp_lg_u32 s29, 0
	v_mad_u64_u32 v[26:27], s[36:37], v25, s31, v[6:7]
	v_mad_u64_u32 v[28:29], s[36:37], v23, s31, v[6:7]
	v_mad_u64_u32 v[30:31], s[36:37], v30, s31, v[6:7]
	v_mad_u64_u32 v[32:33], s[36:37], v32, s31, v[6:7]
	v_mad_u64_u32 v[34:35], s[36:37], v34, s31, v[6:7]
	v_mad_u64_u32 v[36:37], s[36:37], v36, s31, v[6:7]
	v_mad_u64_u32 v[38:39], s[36:37], v38, s31, v[6:7]
	v_mad_u64_u32 v[40:41], s[36:37], v40, s31, v[6:7]
	v_mad_u64_u32 v[42:43], s[36:37], v42, s31, v[6:7]
	v_mad_u64_u32 v[44:45], s[36:37], v44, s31, v[6:7]
	v_mad_u64_u32 v[46:47], s[36:37], v46, s31, v[6:7]
	v_mad_u64_u32 v[48:49], s[36:37], v48, s31, v[6:7]
	v_mad_u64_u32 v[50:51], s[36:37], v50, s31, v[6:7]
	v_mad_u64_u32 v[52:53], s[36:37], v52, s31, v[6:7]
	s_lshl_b32 s36, s27, 1
	s_lshl_b32 s37, s28, 1
	v_or_b32_e32 v86, s37, v8
	s_add_i32 s38, s36, 4
	s_add_i32 s39, s37, 4
	s_add_i32 s40, s36, 8
	s_add_i32 s41, s37, 8
	s_add_i32 s42, s36, 12
	s_add_i32 s43, s37, 12
	s_add_i32 s44, s36, 16
	s_add_i32 s45, s37, 16
	s_add_i32 s46, s36, 20
	s_add_i32 s47, s37, 20
	s_add_i32 s48, s36, 24
	s_add_i32 s49, s37, 24
	s_add_i32 s50, s36, 28
	s_add_i32 s51, s37, 28
	v_or_b32_e32 v84, s36, v3
	v_ashrrev_i32_e32 v87, 31, v86
	v_or_b32_e32 v88, s38, v3
	v_or_b32_e32 v90, s39, v8
	v_or_b32_e32 v92, s40, v3
	v_or_b32_e32 v94, s41, v8
	v_or_b32_e32 v96, s42, v3
	v_or_b32_e32 v98, s43, v8
	v_or_b32_e32 v100, s44, v3
	v_or_b32_e32 v102, s45, v8
	v_or_b32_e32 v104, s46, v3
	v_or_b32_e32 v106, s47, v8
	v_or_b32_e32 v108, s48, v3
	v_or_b32_e32 v110, s49, v8
	v_or_b32_e32 v112, s50, v3
	v_or_b32_e32 v114, s51, v8
	v_ashrrev_i32_e32 v85, 31, v84
	v_lshlrev_b64 v[86:87], 12, v[86:87]
	v_ashrrev_i32_e32 v91, 31, v90
	v_ashrrev_i32_e32 v89, 31, v88
	v_ashrrev_i32_e32 v95, 31, v94
	v_ashrrev_i32_e32 v93, 31, v92
	v_ashrrev_i32_e32 v99, 31, v98
	v_ashrrev_i32_e32 v97, 31, v96
	v_ashrrev_i32_e32 v103, 31, v102
	v_ashrrev_i32_e32 v101, 31, v100
	v_ashrrev_i32_e32 v107, 31, v106
	v_ashrrev_i32_e32 v105, 31, v104
	v_ashrrev_i32_e32 v111, 31, v110
	v_ashrrev_i32_e32 v109, 31, v108
	v_ashrrev_i32_e32 v115, 31, v114
	v_ashrrev_i32_e32 v113, 31, v112
	v_lshlrev_b64 v[84:85], 12, v[84:85]
	v_lshl_add_u64 v[86:87], v[12:13], 0, v[86:87]
	v_lshlrev_b64 v[88:89], 12, v[88:89]
	v_lshlrev_b64 v[90:91], 12, v[90:91]
	v_lshlrev_b64 v[92:93], 12, v[92:93]
	v_lshlrev_b64 v[94:95], 12, v[94:95]
	v_lshlrev_b64 v[96:97], 12, v[96:97]
	v_lshlrev_b64 v[98:99], 12, v[98:99]
	v_lshlrev_b64 v[100:101], 12, v[100:101]
	v_lshlrev_b64 v[102:103], 12, v[102:103]
	v_lshlrev_b64 v[104:105], 12, v[104:105]
	v_lshlrev_b64 v[106:107], 12, v[106:107]
	v_lshlrev_b64 v[108:109], 12, v[108:109]
	v_lshlrev_b64 v[110:111], 12, v[110:111]
	v_lshlrev_b64 v[112:113], 12, v[112:113]
	v_lshlrev_b64 v[114:115], 12, v[114:115]
	v_lshl_add_u64 v[84:85], v[12:13], 0, v[84:85]
	v_lshl_add_u64 v[90:91], v[12:13], 0, v[90:91]
	v_lshl_add_u64 v[88:89], v[12:13], 0, v[88:89]
	v_lshl_add_u64 v[94:95], v[12:13], 0, v[94:95]
	v_lshl_add_u64 v[92:93], v[12:13], 0, v[92:93]
	v_lshl_add_u64 v[98:99], v[12:13], 0, v[98:99]
	v_lshl_add_u64 v[96:97], v[12:13], 0, v[96:97]
	v_lshl_add_u64 v[102:103], v[12:13], 0, v[102:103]
	v_lshl_add_u64 v[100:101], v[12:13], 0, v[100:101]
	v_lshl_add_u64 v[106:107], v[12:13], 0, v[106:107]
	v_lshl_add_u64 v[104:105], v[12:13], 0, v[104:105]
	v_lshl_add_u64 v[110:111], v[12:13], 0, v[110:111]
	v_lshl_add_u64 v[108:109], v[12:13], 0, v[108:109]
	v_lshl_add_u64 v[114:115], v[12:13], 0, v[114:115]
	v_lshl_add_u64 v[112:113], v[12:13], 0, v[112:113]
	global_load_dword v116, v[86:87], off
	global_load_dword v117, v[84:85], off
	global_load_dword v130, v[90:91], off
	global_load_dword v152, v[88:89], off
	global_load_dword v153, v[94:95], off
	global_load_dword v154, v[92:93], off
	global_load_dword v155, v[98:99], off
	global_load_dword v156, v[96:97], off
	global_load_dword v157, v[102:103], off
	global_load_dword v158, v[100:101], off
	global_load_dword v159, v[106:107], off
	global_load_dword v160, v[104:105], off
	global_load_dword v161, v[110:111], off
	global_load_dword v162, v[108:109], off
	global_load_dword v163, v[114:115], off
	global_load_dword v164, v[112:113], off
	v_or_b32_e32 v86, s36, v1
	v_or_b32_e32 v84, s37, v4
	s_add_i32 s28, s28, 16
	s_add_i32 s27, s27, 16
	s_add_i32 s29, s29, -16
	v_mad_u64_u32 v[84:85], s[36:37], v84, s31, v[6:7]
	v_mad_u64_u32 v[86:87], s[36:37], v86, s31, v[6:7]
	v_or_b32_e32 v85, s38, v1
	v_or_b32_e32 v87, s39, v4
	v_or_b32_e32 v94, s40, v1
	v_or_b32_e32 v92, s41, v4
	v_or_b32_e32 v98, s42, v1
	v_or_b32_e32 v96, s43, v4
	v_or_b32_e32 v102, s44, v1
	v_or_b32_e32 v100, s45, v4
	v_or_b32_e32 v106, s46, v1
	v_or_b32_e32 v104, s47, v4
	v_or_b32_e32 v110, s48, v1
	v_or_b32_e32 v108, s49, v4
	v_or_b32_e32 v114, s50, v1
	v_or_b32_e32 v112, s51, v4
	s_cmp_lg_u32 s29, 0
	v_mad_u64_u32 v[88:89], s[36:37], v87, s31, v[6:7]
	v_mad_u64_u32 v[90:91], s[36:37], v85, s31, v[6:7]
	v_mad_u64_u32 v[92:93], s[36:37], v92, s31, v[6:7]
	v_mad_u64_u32 v[94:95], s[36:37], v94, s31, v[6:7]
	v_mad_u64_u32 v[96:97], s[36:37], v96, s31, v[6:7]
	v_mad_u64_u32 v[98:99], s[36:37], v98, s31, v[6:7]
	v_mad_u64_u32 v[100:101], s[36:37], v100, s31, v[6:7]
	v_mad_u64_u32 v[102:103], s[36:37], v102, s31, v[6:7]
	v_mad_u64_u32 v[104:105], s[36:37], v104, s31, v[6:7]
	v_mad_u64_u32 v[106:107], s[36:37], v106, s31, v[6:7]
	v_mad_u64_u32 v[108:109], s[36:37], v108, s31, v[6:7]
	v_mad_u64_u32 v[110:111], s[36:37], v110, s31, v[6:7]
	v_mad_u64_u32 v[112:113], s[36:37], v112, s31, v[6:7]
	v_mad_u64_u32 v[114:115], s[36:37], v114, s31, v[6:7]
	s_waitcnt vmcnt(31)
	ds_write_b32 v22, v11
	s_waitcnt vmcnt(30)
	ds_write_b32 v24, v14
	s_waitcnt vmcnt(29)
	ds_write_b32 v26, v21
	s_waitcnt vmcnt(28)
	ds_write_b32 v28, v54
	s_waitcnt vmcnt(27)
	ds_write_b32 v30, v55
	s_waitcnt vmcnt(26)
	ds_write_b32 v32, v56
	s_waitcnt vmcnt(25)
	ds_write_b32 v34, v57
	s_waitcnt vmcnt(24)
	ds_write_b32 v36, v58
	s_waitcnt vmcnt(23)
	ds_write_b32 v38, v59
	s_waitcnt vmcnt(22)
	ds_write_b32 v40, v60
	s_waitcnt vmcnt(21)
	ds_write_b32 v42, v61
	s_waitcnt vmcnt(20)
	ds_write_b32 v44, v62
	s_waitcnt vmcnt(19)
	ds_write_b32 v46, v63
	s_waitcnt vmcnt(18)
	ds_write_b32 v48, v64
	s_waitcnt vmcnt(17)
	ds_write_b32 v50, v65
	s_waitcnt vmcnt(16)
	ds_write_b32 v52, v66
	s_waitcnt vmcnt(15)
	ds_write_b32 v84, v116
	s_waitcnt vmcnt(14)
	ds_write_b32 v86, v117
	s_waitcnt vmcnt(13)
	ds_write_b32 v88, v130
	s_waitcnt vmcnt(12)
	ds_write_b32 v90, v152
	s_waitcnt vmcnt(11)
	ds_write_b32 v92, v153
	s_waitcnt vmcnt(10)
	ds_write_b32 v94, v154
	s_waitcnt vmcnt(9)
	ds_write_b32 v96, v155
	s_waitcnt vmcnt(8)
	ds_write_b32 v98, v156
	s_waitcnt vmcnt(7)
	ds_write_b32 v100, v157
	s_waitcnt vmcnt(6)
	ds_write_b32 v102, v158
	s_waitcnt vmcnt(5)
	ds_write_b32 v104, v159
	s_waitcnt vmcnt(4)
	ds_write_b32 v106, v160
	s_waitcnt vmcnt(3)
	ds_write_b32 v108, v161
	s_waitcnt vmcnt(2)
	ds_write_b32 v110, v162
	s_waitcnt vmcnt(1)
	ds_write_b32 v112, v163
	s_waitcnt vmcnt(0)
	ds_write_b32 v114, v164
	v_mov_b32_e32 v14, v117
	v_mov_b32_e32 v21, v130
	v_mov_b32_e32 v44, v106
	v_mov_b32_e32 v45, v107
	v_mov_b32_e32 v46, v108
	v_mov_b32_e32 v47, v109
	v_mov_b32_e32 v48, v110
	v_mov_b32_e32 v49, v111
	v_mov_b32_e32 v50, v112
	v_mov_b32_e32 v51, v113
	v_mov_b32_e32 v52, v114
	v_mov_b32_e32 v53, v115
	v_mov_b32_e32 v54, v152
	v_mov_b32_e32 v55, v153
	v_mov_b32_e32 v56, v154
	v_mov_b32_e32 v57, v155
	v_mov_b32_e32 v58, v156
	v_mov_b32_e32 v59, v157
	v_mov_b32_e32 v60, v158
	v_mov_b32_e32 v61, v159
	s_waitcnt lgkmcnt(0)
	s_lshl_b64 s[28:29], s[8:9], 1
	ds_read2_b32 v[26:27], v16 offset0:33 offset1:41
	ds_read2_b32 v[28:29], v16 offset1:8
	ds_read2_b32 v[30:31], v16 offset0:66 offset1:74
	ds_read2_b32 v[32:33], v16 offset0:99 offset1:107
	ds_read2_b32 v[34:35], v16 offset0:132 offset1:140
	ds_read2_b32 v[36:37], v16 offset0:165 offset1:173
	ds_read2_b32 v[38:39], v16 offset0:198 offset1:206
	ds_read2_b32 v[40:41], v16 offset0:231 offset1:239
	s_add_u32 s24, s24, s28
	s_addc_u32 s25, s25, s29
	v_mov_b32_e32 v11, v9
	v_or_b32_e32 v3, s26, v7
	v_lshl_add_u64 v[12:13], s[24:25], 0, v[10:11]
	v_mul_u32_u24_e32 v3, 0xb00, v3
	v_lshl_add_u64 v[12:13], v[12:13], 0, s[10:11]
	v_lshlrev_b32_e32 v8, 1, v3
	s_waitcnt lgkmcnt(6)
	v_cvt_pk_bf16_f32 v22, v28, v26
	s_waitcnt lgkmcnt(4)
	v_cvt_pk_bf16_f32 v23, v30, v32
	s_waitcnt lgkmcnt(2)
	v_cvt_pk_bf16_f32 v24, v34, v36
	s_waitcnt lgkmcnt(0)
	v_cvt_pk_bf16_f32 v25, v38, v40
	v_lshl_add_u64 v[42:43], v[12:13], 0, v[8:9]
	global_store_dwordx4 v[42:43], v[22:25], off
	v_or_b32_e32 v3, s26, v17
	v_mul_u32_u24_e32 v3, 0xb00, v3
	v_cvt_pk_bf16_f32 v22, v29, v27
	v_cvt_pk_bf16_f32 v23, v31, v33
	v_cvt_pk_bf16_f32 v24, v35, v37
	v_cvt_pk_bf16_f32 v25, v39, v41
	ds_read2_b32 v[28:29], v16 offset0:16 offset1:24
	ds_read2_b32 v[30:31], v16 offset0:49 offset1:57
	ds_read2_b32 v[32:33], v16 offset0:82 offset1:90
	ds_read2_b32 v[34:35], v16 offset0:115 offset1:123
	ds_read2_b32 v[36:37], v16 offset0:148 offset1:156
	ds_read2_b32 v[38:39], v16 offset0:181 offset1:189
	ds_read2_b32 v[40:41], v16 offset0:214 offset1:222
	ds_read2_b32 v[42:43], v16 offset0:247 offset1:255
	v_lshlrev_b32_e32 v8, 1, v3
	v_or_b32_e32 v3, s26, v18
	v_mul_u32_u24_e32 v3, 0xb00, v3
	v_lshl_add_u64 v[26:27], v[12:13], 0, v[8:9]
	v_lshlrev_b32_e32 v8, 1, v3
	v_or_b32_e32 v3, s26, v19
	v_mul_u32_u24_e32 v3, 0xb00, v3
	global_store_dwordx4 v[26:27], v[22:25], off
	v_lshl_add_u64 v[26:27], v[12:13], 0, v[8:9]
	v_lshlrev_b32_e32 v8, 1, v3
	s_waitcnt lgkmcnt(6)
	v_cvt_pk_bf16_f32 v22, v28, v30
	s_waitcnt lgkmcnt(4)
	v_cvt_pk_bf16_f32 v23, v32, v34
	s_waitcnt lgkmcnt(2)
	v_cvt_pk_bf16_f32 v24, v36, v38
	s_waitcnt lgkmcnt(0)
	v_cvt_pk_bf16_f32 v25, v40, v42
	global_store_dwordx4 v[26:27], v[22:25], off
	v_lshl_add_u64 v[12:13], v[12:13], 0, v[8:9]
	s_mov_b64 s[24:25], 0
	v_cvt_pk_bf16_f32 v22, v29, v31
	v_cvt_pk_bf16_f32 v23, v33, v35
	v_cvt_pk_bf16_f32 v24, v37, v39
	v_cvt_pk_bf16_f32 v25, v41, v43
	global_store_dwordx4 v[12:13], v[22:25], off
	s_waitcnt lgkmcnt(0)

.LBB0_19:
	s_lshl_b32 s38, s27, 1
	s_lshl_b32 s39, s28, 1
	v_or_b32_e32 v11, s38, v3
	v_or_b32_e32 v14, s39, v8
	s_add_i32 s40, s38, 4
	s_add_i32 s41, s39, 4
	s_add_i32 s42, s38, 8
	s_add_i32 s43, s39, 8
	s_add_i32 s44, s38, 12
	s_add_i32 s45, s39, 12
	s_add_i32 s46, s38, 16
	s_add_i32 s47, s39, 16
	s_add_i32 s48, s38, 20
	s_add_i32 s49, s39, 20
	s_add_i32 s50, s38, 24
	s_add_i32 s51, s39, 24
	s_add_i32 s52, s38, 28
	s_add_i32 s53, s39, 28
	v_mad_u64_u32 v[22:23], s[36:37], v14, s33, v[12:13]
	v_mad_u64_u32 v[24:25], s[36:37], v11, s33, v[12:13]
	v_or_b32_e32 v11, s40, v3
	v_or_b32_e32 v14, s41, v8
	v_or_b32_e32 v21, s42, v3
	v_or_b32_e32 v30, s43, v8
	v_or_b32_e32 v36, s44, v3
	v_or_b32_e32 v34, s45, v8
	v_or_b32_e32 v40, s46, v3
	v_or_b32_e32 v38, s47, v8
	v_or_b32_e32 v44, s48, v3
	v_or_b32_e32 v42, s49, v8
	v_or_b32_e32 v48, s50, v3
	v_or_b32_e32 v46, s51, v8
	v_or_b32_e32 v52, s52, v3
	v_or_b32_e32 v50, s53, v8
	v_mad_u64_u32 v[26:27], s[36:37], v14, s33, v[12:13]
	v_mad_u64_u32 v[28:29], s[36:37], v11, s33, v[12:13]
	v_mad_u64_u32 v[30:31], s[36:37], v30, s33, v[12:13]
	v_mad_u64_u32 v[32:33], s[36:37], v21, s33, v[12:13]
	v_mad_u64_u32 v[34:35], s[36:37], v34, s33, v[12:13]
	v_mad_u64_u32 v[36:37], s[36:37], v36, s33, v[12:13]
	v_mad_u64_u32 v[38:39], s[36:37], v38, s33, v[12:13]
	v_mad_u64_u32 v[40:41], s[36:37], v40, s33, v[12:13]
	v_mad_u64_u32 v[42:43], s[36:37], v42, s33, v[12:13]
	v_mad_u64_u32 v[44:45], s[36:37], v44, s33, v[12:13]
	v_mad_u64_u32 v[46:47], s[36:37], v46, s33, v[12:13]
	v_mad_u64_u32 v[48:49], s[36:37], v48, s33, v[12:13]
	v_mad_u64_u32 v[50:51], s[36:37], v50, s33, v[12:13]
	v_mad_u64_u32 v[52:53], s[36:37], v52, s33, v[12:13]
	global_load_dword v11, v[22:23], off
	global_load_dword v14, v[24:25], off
	global_load_dword v21, v[26:27], off
	global_load_dword v54, v[28:29], off
	global_load_dword v55, v[30:31], off
	global_load_dword v56, v[32:33], off
	global_load_dword v57, v[34:35], off
	global_load_dword v58, v[36:37], off
	global_load_dword v59, v[38:39], off
	global_load_dword v60, v[40:41], off
	global_load_dword v61, v[42:43], off
	global_load_dword v62, v[44:45], off
	global_load_dword v63, v[46:47], off
	global_load_dword v64, v[48:49], off
	global_load_dword v65, v[50:51], off
	global_load_dword v66, v[52:53], off
	v_or_b32_e32 v24, s38, v1
	v_or_b32_e32 v22, s39, v4
	s_add_i32 s28, s28, 16
	s_add_i32 s27, s27, 16
	s_add_i32 s29, s29, -16
	v_mad_u64_u32 v[22:23], s[36:37], v22, s31, v[6:7]
	v_mad_u64_u32 v[24:25], s[36:37], v24, s31, v[6:7]
	v_or_b32_e32 v23, s40, v1
	v_or_b32_e32 v25, s41, v4
	v_or_b32_e32 v32, s42, v1
	v_or_b32_e32 v30, s43, v4
	v_or_b32_e32 v36, s44, v1
	v_or_b32_e32 v34, s45, v4
	v_or_b32_e32 v40, s46, v1
	v_or_b32_e32 v38, s47, v4
	v_or_b32_e32 v44, s48, v1
	v_or_b32_e32 v42, s49, v4
	v_or_b32_e32 v48, s50, v1
	v_or_b32_e32 v46, s51, v4
	v_or_b32_e32 v52, s52, v1
	v_or_b32_e32 v50, s53, v4
	s_cmp_lg_u32 s29, 0
	v_mad_u64_u32 v[26:27], s[36:37], v25, s31, v[6:7]
	v_mad_u64_u32 v[28:29], s[36:37], v23, s31, v[6:7]
	v_mad_u64_u32 v[30:31], s[36:37], v30, s31, v[6:7]
	v_mad_u64_u32 v[32:33], s[36:37], v32, s31, v[6:7]
	v_mad_u64_u32 v[34:35], s[36:37], v34, s31, v[6:7]
	v_mad_u64_u32 v[36:37], s[36:37], v36, s31, v[6:7]
	v_mad_u64_u32 v[38:39], s[36:37], v38, s31, v[6:7]
	v_mad_u64_u32 v[40:41], s[36:37], v40, s31, v[6:7]
	v_mad_u64_u32 v[42:43], s[36:37], v42, s31, v[6:7]
	v_mad_u64_u32 v[44:45], s[36:37], v44, s31, v[6:7]
	v_mad_u64_u32 v[46:47], s[36:37], v46, s31, v[6:7]
	v_mad_u64_u32 v[48:49], s[36:37], v48, s31, v[6:7]
	v_mad_u64_u32 v[50:51], s[36:37], v50, s31, v[6:7]
	v_mad_u64_u32 v[52:53], s[36:37], v52, s31, v[6:7]
	s_lshl_b32 s38, s27, 1
	s_lshl_b32 s39, s28, 1
	v_or_b32_e32 v116, s38, v3
	v_or_b32_e32 v117, s39, v8
	s_add_i32 s40, s38, 4
	s_add_i32 s41, s39, 4
	s_add_i32 s42, s38, 8
	s_add_i32 s43, s39, 8
	s_add_i32 s44, s38, 12
	s_add_i32 s45, s39, 12
	s_add_i32 s46, s38, 16
	s_add_i32 s47, s39, 16
	s_add_i32 s48, s38, 20
	s_add_i32 s49, s39, 20
	s_add_i32 s50, s38, 24
	s_add_i32 s51, s39, 24
	s_add_i32 s52, s38, 28
	s_add_i32 s53, s39, 28
	v_mad_u64_u32 v[84:85], s[36:37], v117, s33, v[12:13]
	v_mad_u64_u32 v[86:87], s[36:37], v116, s33, v[12:13]
	v_or_b32_e32 v116, s40, v3
	v_or_b32_e32 v117, s41, v8
	v_or_b32_e32 v130, s42, v3
	v_or_b32_e32 v92, s43, v8
	v_or_b32_e32 v98, s44, v3
	v_or_b32_e32 v96, s45, v8
	v_or_b32_e32 v102, s46, v3
	v_or_b32_e32 v100, s47, v8
	v_or_b32_e32 v106, s48, v3
	v_or_b32_e32 v104, s49, v8
	v_or_b32_e32 v110, s50, v3
	v_or_b32_e32 v108, s51, v8
	v_or_b32_e32 v114, s52, v3
	v_or_b32_e32 v112, s53, v8
	v_mad_u64_u32 v[88:89], s[36:37], v117, s33, v[12:13]
	v_mad_u64_u32 v[90:91], s[36:37], v116, s33, v[12:13]
	v_mad_u64_u32 v[92:93], s[36:37], v92, s33, v[12:13]
	v_mad_u64_u32 v[94:95], s[36:37], v130, s33, v[12:13]
	v_mad_u64_u32 v[96:97], s[36:37], v96, s33, v[12:13]
	v_mad_u64_u32 v[98:99], s[36:37], v98, s33, v[12:13]
	v_mad_u64_u32 v[100:101], s[36:37], v100, s33, v[12:13]
	v_mad_u64_u32 v[102:103], s[36:37], v102, s33, v[12:13]
	v_mad_u64_u32 v[104:105], s[36:37], v104, s33, v[12:13]
	v_mad_u64_u32 v[106:107], s[36:37], v106, s33, v[12:13]
	v_mad_u64_u32 v[108:109], s[36:37], v108, s33, v[12:13]
	v_mad_u64_u32 v[110:111], s[36:37], v110, s33, v[12:13]
	v_mad_u64_u32 v[112:113], s[36:37], v112, s33, v[12:13]
	v_mad_u64_u32 v[114:115], s[36:37], v114, s33, v[12:13]
	global_load_dword v116, v[84:85], off
	global_load_dword v117, v[86:87], off
	global_load_dword v130, v[88:89], off
	global_load_dword v152, v[90:91], off
	global_load_dword v153, v[92:93], off
	global_load_dword v154, v[94:95], off
	global_load_dword v155, v[96:97], off
	global_load_dword v156, v[98:99], off
	global_load_dword v157, v[100:101], off
	global_load_dword v158, v[102:103], off
	global_load_dword v159, v[104:105], off
	global_load_dword v160, v[106:107], off
	global_load_dword v161, v[108:109], off
	global_load_dword v162, v[110:111], off
	global_load_dword v163, v[112:113], off
	global_load_dword v164, v[114:115], off
	v_or_b32_e32 v86, s38, v1
	v_or_b32_e32 v84, s39, v4
	s_add_i32 s28, s28, 16
	s_add_i32 s27, s27, 16
	s_add_i32 s29, s29, -16
	v_mad_u64_u32 v[84:85], s[36:37], v84, s31, v[6:7]
	v_mad_u64_u32 v[86:87], s[36:37], v86, s31, v[6:7]
	v_or_b32_e32 v85, s40, v1
	v_or_b32_e32 v87, s41, v4
	v_or_b32_e32 v94, s42, v1
	v_or_b32_e32 v92, s43, v4
	v_or_b32_e32 v98, s44, v1
	v_or_b32_e32 v96, s45, v4
	v_or_b32_e32 v102, s46, v1
	v_or_b32_e32 v100, s47, v4
	v_or_b32_e32 v106, s48, v1
	v_or_b32_e32 v104, s49, v4
	v_or_b32_e32 v110, s50, v1
	v_or_b32_e32 v108, s51, v4
	v_or_b32_e32 v114, s52, v1
	v_or_b32_e32 v112, s53, v4
	s_cmp_lg_u32 s29, 0
	v_mad_u64_u32 v[88:89], s[36:37], v87, s31, v[6:7]
	v_mad_u64_u32 v[90:91], s[36:37], v85, s31, v[6:7]
	v_mad_u64_u32 v[92:93], s[36:37], v92, s31, v[6:7]
	v_mad_u64_u32 v[94:95], s[36:37], v94, s31, v[6:7]
	v_mad_u64_u32 v[96:97], s[36:37], v96, s31, v[6:7]
	v_mad_u64_u32 v[98:99], s[36:37], v98, s31, v[6:7]
	v_mad_u64_u32 v[100:101], s[36:37], v100, s31, v[6:7]
	v_mad_u64_u32 v[102:103], s[36:37], v102, s31, v[6:7]
	v_mad_u64_u32 v[104:105], s[36:37], v104, s31, v[6:7]
	v_mad_u64_u32 v[106:107], s[36:37], v106, s31, v[6:7]
	v_mad_u64_u32 v[108:109], s[36:37], v108, s31, v[6:7]
	v_mad_u64_u32 v[110:111], s[36:37], v110, s31, v[6:7]
	v_mad_u64_u32 v[112:113], s[36:37], v112, s31, v[6:7]
	v_mad_u64_u32 v[114:115], s[36:37], v114, s31, v[6:7]
	s_waitcnt vmcnt(31)
	ds_write_b32 v22, v11
	s_waitcnt vmcnt(30)
	ds_write_b32 v24, v14
	s_waitcnt vmcnt(29)
	ds_write_b32 v26, v21
	s_waitcnt vmcnt(28)
	ds_write_b32 v28, v54
	s_waitcnt vmcnt(27)
	ds_write_b32 v30, v55
	s_waitcnt vmcnt(26)
	ds_write_b32 v32, v56
	s_waitcnt vmcnt(25)
	ds_write_b32 v34, v57
	s_waitcnt vmcnt(24)
	ds_write_b32 v36, v58
	s_waitcnt vmcnt(23)
	ds_write_b32 v38, v59
	s_waitcnt vmcnt(22)
	ds_write_b32 v40, v60
	s_waitcnt vmcnt(21)
	ds_write_b32 v42, v61
	s_waitcnt vmcnt(20)
	ds_write_b32 v44, v62
	s_waitcnt vmcnt(19)
	ds_write_b32 v46, v63
	s_waitcnt vmcnt(18)
	ds_write_b32 v48, v64
	s_waitcnt vmcnt(17)
	ds_write_b32 v50, v65
	s_waitcnt vmcnt(16)
	ds_write_b32 v52, v66
	s_waitcnt vmcnt(15)
	ds_write_b32 v84, v116
	s_waitcnt vmcnt(14)
	ds_write_b32 v86, v117
	s_waitcnt vmcnt(13)
	ds_write_b32 v88, v130
	s_waitcnt vmcnt(12)
	ds_write_b32 v90, v152
	s_waitcnt vmcnt(11)
	ds_write_b32 v92, v153
	s_waitcnt vmcnt(10)
	ds_write_b32 v94, v154
	s_waitcnt vmcnt(9)
	ds_write_b32 v96, v155
	s_waitcnt vmcnt(8)
	ds_write_b32 v98, v156
	s_waitcnt vmcnt(7)
	ds_write_b32 v100, v157
	s_waitcnt vmcnt(6)
	ds_write_b32 v102, v158
	s_waitcnt vmcnt(5)
	ds_write_b32 v104, v159
	s_waitcnt vmcnt(4)
	ds_write_b32 v106, v160
	s_waitcnt vmcnt(3)
	ds_write_b32 v108, v161
	s_waitcnt vmcnt(2)
	ds_write_b32 v110, v162
	s_waitcnt vmcnt(1)
	ds_write_b32 v112, v163
	s_waitcnt vmcnt(0)
	ds_write_b32 v114, v164
	v_mov_b32_e32 v14, v117
	v_mov_b32_e32 v21, v130
	v_mov_b32_e32 v44, v106
	v_mov_b32_e32 v45, v107
	v_mov_b32_e32 v46, v108
	v_mov_b32_e32 v47, v109
	v_mov_b32_e32 v48, v110
	v_mov_b32_e32 v49, v111
	v_mov_b32_e32 v50, v112
	v_mov_b32_e32 v51, v113
	v_mov_b32_e32 v52, v114
	v_mov_b32_e32 v53, v115
	v_mov_b32_e32 v54, v152
	v_mov_b32_e32 v55, v153
	v_mov_b32_e32 v56, v154
	v_mov_b32_e32 v57, v155
	v_mov_b32_e32 v58, v156
	v_mov_b32_e32 v59, v157
	v_mov_b32_e32 v60, v158
	v_mov_b32_e32 v61, v159
	s_waitcnt lgkmcnt(0)
	s_and_b32 s26, 0xffff, s26
	s_lshl_b32 s26, s26, 1
	ds_read2_b32 v[26:27], v16 offset0:33 offset1:41
	ds_read2_b32 v[28:29], v16 offset1:8
	ds_read2_b32 v[30:31], v16 offset0:66 offset1:74
	ds_read2_b32 v[32:33], v16 offset0:99 offset1:107
	ds_read2_b32 v[34:35], v16 offset0:132 offset1:140
	ds_read2_b32 v[36:37], v16 offset0:165 offset1:173
	ds_read2_b32 v[38:39], v16 offset0:198 offset1:206
	ds_read2_b32 v[40:41], v16 offset0:231 offset1:239
	s_add_u32 s24, s24, s26
	s_addc_u32 s25, s25, 0
	v_mov_b32_e32 v11, v9
	v_lshl_add_u64 v[12:13], s[24:25], 0, v[10:11]
	v_or_b32_e32 v3, s8, v7
	v_lshl_add_u64 v[12:13], v[12:13], 0, s[12:13]
	v_lshlrev_b32_e32 v8, 11, v3
	s_waitcnt lgkmcnt(6)
	v_cvt_pk_bf16_f32 v22, v28, v26
	s_waitcnt lgkmcnt(4)
	v_cvt_pk_bf16_f32 v23, v30, v32
	s_waitcnt lgkmcnt(2)
	v_cvt_pk_bf16_f32 v24, v34, v36
	s_waitcnt lgkmcnt(0)
	v_cvt_pk_bf16_f32 v25, v38, v40
	v_lshl_add_u64 v[42:43], v[12:13], 0, v[8:9]
	global_store_dwordx4 v[42:43], v[22:25], off
	v_or_b32_e32 v3, s8, v17
	v_lshlrev_b32_e32 v8, 11, v3
	v_cvt_pk_bf16_f32 v22, v29, v27
	v_cvt_pk_bf16_f32 v23, v31, v33
	v_cvt_pk_bf16_f32 v24, v35, v37
	v_cvt_pk_bf16_f32 v25, v39, v41
	ds_read2_b32 v[28:29], v16 offset0:49 offset1:57
	ds_read2_b32 v[30:31], v16 offset0:16 offset1:24
	ds_read2_b32 v[32:33], v16 offset0:82 offset1:90
	ds_read2_b32 v[34:35], v16 offset0:115 offset1:123
	ds_read2_b32 v[36:37], v16 offset0:148 offset1:156
	ds_read2_b32 v[38:39], v16 offset0:181 offset1:189
	ds_read2_b32 v[40:41], v16 offset0:214 offset1:222
	ds_read2_b32 v[42:43], v16 offset0:247 offset1:255
	v_or_b32_e32 v3, s8, v18
	v_lshl_add_u64 v[26:27], v[12:13], 0, v[8:9]
	v_lshlrev_b32_e32 v8, 11, v3
	v_or_b32_e32 v3, s8, v19
	global_store_dwordx4 v[26:27], v[22:25], off
	v_lshl_add_u64 v[26:27], v[12:13], 0, v[8:9]
	v_lshlrev_b32_e32 v8, 11, v3
	s_waitcnt lgkmcnt(6)
	v_cvt_pk_bf16_f32 v22, v30, v28
	s_waitcnt lgkmcnt(4)
	v_cvt_pk_bf16_f32 v23, v32, v34
	s_waitcnt lgkmcnt(2)
	v_cvt_pk_bf16_f32 v24, v36, v38
	s_waitcnt lgkmcnt(0)
	v_cvt_pk_bf16_f32 v25, v40, v42
	global_store_dwordx4 v[26:27], v[22:25], off
	v_lshl_add_u64 v[12:13], v[12:13], 0, v[8:9]
	s_nop 0
	v_cvt_pk_bf16_f32 v22, v31, v29
	v_cvt_pk_bf16_f32 v23, v33, v35
	v_cvt_pk_bf16_f32 v24, v37, v39
	v_cvt_pk_bf16_f32 v25, v41, v43
	global_store_dwordx4 v[12:13], v[22:25], off
	s_waitcnt lgkmcnt(0)

.LBB0_24:
	s_lshl_b32 s36, s27, 1
	s_lshl_b32 s37, s28, 1
	v_or_b32_e32 v24, s37, v8
	s_add_i32 s38, s36, 4
	s_add_i32 s39, s37, 4
	s_add_i32 s40, s36, 8
	s_add_i32 s41, s37, 8
	s_add_i32 s42, s36, 12
	s_add_i32 s43, s37, 12
	s_add_i32 s44, s36, 16
	s_add_i32 s45, s37, 16
	s_add_i32 s46, s36, 20
	s_add_i32 s47, s37, 20
	s_add_i32 s48, s36, 24
	s_add_i32 s49, s37, 24
	s_add_i32 s50, s36, 28
	s_add_i32 s51, s37, 28
	v_or_b32_e32 v22, s36, v3
	v_ashrrev_i32_e32 v25, 31, v24
	v_or_b32_e32 v26, s38, v3
	v_or_b32_e32 v28, s39, v8
	v_or_b32_e32 v30, s40, v3
	v_or_b32_e32 v32, s41, v8
	v_or_b32_e32 v34, s42, v3
	v_or_b32_e32 v36, s43, v8
	v_or_b32_e32 v38, s44, v3
	v_or_b32_e32 v40, s45, v8
	v_or_b32_e32 v42, s46, v3
	v_or_b32_e32 v44, s47, v8
	v_or_b32_e32 v46, s48, v3
	v_or_b32_e32 v48, s49, v8
	v_or_b32_e32 v50, s50, v3
	v_or_b32_e32 v52, s51, v8
	v_ashrrev_i32_e32 v23, 31, v22
	v_lshlrev_b64 v[24:25], 12, v[24:25]
	v_ashrrev_i32_e32 v29, 31, v28
	v_ashrrev_i32_e32 v27, 31, v26
	v_ashrrev_i32_e32 v33, 31, v32
	v_ashrrev_i32_e32 v31, 31, v30
	v_ashrrev_i32_e32 v37, 31, v36
	v_ashrrev_i32_e32 v35, 31, v34
	v_ashrrev_i32_e32 v41, 31, v40
	v_ashrrev_i32_e32 v39, 31, v38
	v_ashrrev_i32_e32 v45, 31, v44
	v_ashrrev_i32_e32 v43, 31, v42
	v_ashrrev_i32_e32 v49, 31, v48
	v_ashrrev_i32_e32 v47, 31, v46
	v_ashrrev_i32_e32 v53, 31, v52
	v_ashrrev_i32_e32 v51, 31, v50
	v_lshlrev_b64 v[22:23], 12, v[22:23]
	v_lshl_add_u64 v[24:25], v[12:13], 0, v[24:25]
	v_lshlrev_b64 v[26:27], 12, v[26:27]
	v_lshlrev_b64 v[28:29], 12, v[28:29]
	v_lshlrev_b64 v[30:31], 12, v[30:31]
	v_lshlrev_b64 v[32:33], 12, v[32:33]
	v_lshlrev_b64 v[34:35], 12, v[34:35]
	v_lshlrev_b64 v[36:37], 12, v[36:37]
	v_lshlrev_b64 v[38:39], 12, v[38:39]
	v_lshlrev_b64 v[40:41], 12, v[40:41]
	v_lshlrev_b64 v[42:43], 12, v[42:43]
	v_lshlrev_b64 v[44:45], 12, v[44:45]
	v_lshlrev_b64 v[46:47], 12, v[46:47]
	v_lshlrev_b64 v[48:49], 12, v[48:49]
	v_lshlrev_b64 v[50:51], 12, v[50:51]
	v_lshlrev_b64 v[52:53], 12, v[52:53]
	v_lshl_add_u64 v[22:23], v[12:13], 0, v[22:23]
	v_lshl_add_u64 v[28:29], v[12:13], 0, v[28:29]
	v_lshl_add_u64 v[26:27], v[12:13], 0, v[26:27]
	v_lshl_add_u64 v[32:33], v[12:13], 0, v[32:33]
	v_lshl_add_u64 v[30:31], v[12:13], 0, v[30:31]
	v_lshl_add_u64 v[36:37], v[12:13], 0, v[36:37]
	v_lshl_add_u64 v[34:35], v[12:13], 0, v[34:35]
	v_lshl_add_u64 v[40:41], v[12:13], 0, v[40:41]
	v_lshl_add_u64 v[38:39], v[12:13], 0, v[38:39]
	v_lshl_add_u64 v[44:45], v[12:13], 0, v[44:45]
	v_lshl_add_u64 v[42:43], v[12:13], 0, v[42:43]
	v_lshl_add_u64 v[48:49], v[12:13], 0, v[48:49]
	v_lshl_add_u64 v[46:47], v[12:13], 0, v[46:47]
	v_lshl_add_u64 v[52:53], v[12:13], 0, v[52:53]
	v_lshl_add_u64 v[50:51], v[12:13], 0, v[50:51]
	global_load_dword v11, v[24:25], off
	global_load_dword v14, v[22:23], off
	global_load_dword v21, v[28:29], off
	global_load_dword v54, v[26:27], off
	global_load_dword v55, v[32:33], off
	global_load_dword v56, v[30:31], off
	global_load_dword v57, v[36:37], off
	global_load_dword v58, v[34:35], off
	global_load_dword v59, v[40:41], off
	global_load_dword v60, v[38:39], off
	global_load_dword v61, v[44:45], off
	global_load_dword v62, v[42:43], off
	global_load_dword v63, v[48:49], off
	global_load_dword v64, v[46:47], off
	global_load_dword v65, v[52:53], off
	global_load_dword v66, v[50:51], off
	v_or_b32_e32 v24, s36, v1
	v_or_b32_e32 v22, s37, v4
	s_add_i32 s28, s28, 16
	s_add_i32 s27, s27, 16
	s_add_i32 s29, s29, -16
	v_mad_u64_u32 v[22:23], s[36:37], v22, s31, v[6:7]
	v_mad_u64_u32 v[24:25], s[36:37], v24, s31, v[6:7]
	v_or_b32_e32 v23, s38, v1
	v_or_b32_e32 v25, s39, v4
	v_or_b32_e32 v32, s40, v1
	v_or_b32_e32 v30, s41, v4
	v_or_b32_e32 v36, s42, v1
	v_or_b32_e32 v34, s43, v4
	v_or_b32_e32 v40, s44, v1
	v_or_b32_e32 v38, s45, v4
	v_or_b32_e32 v44, s46, v1
	v_or_b32_e32 v42, s47, v4
	v_or_b32_e32 v48, s48, v1
	v_or_b32_e32 v46, s49, v4
	v_or_b32_e32 v52, s50, v1
	v_or_b32_e32 v50, s51, v4
	s_cmp_lg_u32 s29, 0
	v_mad_u64_u32 v[26:27], s[36:37], v25, s31, v[6:7]
	v_mad_u64_u32 v[28:29], s[36:37], v23, s31, v[6:7]
	v_mad_u64_u32 v[30:31], s[36:37], v30, s31, v[6:7]
	v_mad_u64_u32 v[32:33], s[36:37], v32, s31, v[6:7]
	v_mad_u64_u32 v[34:35], s[36:37], v34, s31, v[6:7]
	v_mad_u64_u32 v[36:37], s[36:37], v36, s31, v[6:7]
	v_mad_u64_u32 v[38:39], s[36:37], v38, s31, v[6:7]
	v_mad_u64_u32 v[40:41], s[36:37], v40, s31, v[6:7]
	v_mad_u64_u32 v[42:43], s[36:37], v42, s31, v[6:7]
	v_mad_u64_u32 v[44:45], s[36:37], v44, s31, v[6:7]
	v_mad_u64_u32 v[46:47], s[36:37], v46, s31, v[6:7]
	v_mad_u64_u32 v[48:49], s[36:37], v48, s31, v[6:7]
	v_mad_u64_u32 v[50:51], s[36:37], v50, s31, v[6:7]
	v_mad_u64_u32 v[52:53], s[36:37], v52, s31, v[6:7]
	s_lshl_b32 s36, s27, 1
	s_lshl_b32 s37, s28, 1
	v_or_b32_e32 v86, s37, v8
	s_add_i32 s38, s36, 4
	s_add_i32 s39, s37, 4
	s_add_i32 s40, s36, 8
	s_add_i32 s41, s37, 8
	s_add_i32 s42, s36, 12
	s_add_i32 s43, s37, 12
	s_add_i32 s44, s36, 16
	s_add_i32 s45, s37, 16
	s_add_i32 s46, s36, 20
	s_add_i32 s47, s37, 20
	s_add_i32 s48, s36, 24
	s_add_i32 s49, s37, 24
	s_add_i32 s50, s36, 28
	s_add_i32 s51, s37, 28
	v_or_b32_e32 v84, s36, v3
	v_ashrrev_i32_e32 v87, 31, v86
	v_or_b32_e32 v88, s38, v3
	v_or_b32_e32 v90, s39, v8
	v_or_b32_e32 v92, s40, v3
	v_or_b32_e32 v94, s41, v8
	v_or_b32_e32 v96, s42, v3
	v_or_b32_e32 v98, s43, v8
	v_or_b32_e32 v100, s44, v3
	v_or_b32_e32 v102, s45, v8
	v_or_b32_e32 v104, s46, v3
	v_or_b32_e32 v106, s47, v8
	v_or_b32_e32 v108, s48, v3
	v_or_b32_e32 v110, s49, v8
	v_or_b32_e32 v112, s50, v3
	v_or_b32_e32 v114, s51, v8
	v_ashrrev_i32_e32 v85, 31, v84
	v_lshlrev_b64 v[86:87], 12, v[86:87]
	v_ashrrev_i32_e32 v91, 31, v90
	v_ashrrev_i32_e32 v89, 31, v88
	v_ashrrev_i32_e32 v95, 31, v94
	v_ashrrev_i32_e32 v93, 31, v92
	v_ashrrev_i32_e32 v99, 31, v98
	v_ashrrev_i32_e32 v97, 31, v96
	v_ashrrev_i32_e32 v103, 31, v102
	v_ashrrev_i32_e32 v101, 31, v100
	v_ashrrev_i32_e32 v107, 31, v106
	v_ashrrev_i32_e32 v105, 31, v104
	v_ashrrev_i32_e32 v111, 31, v110
	v_ashrrev_i32_e32 v109, 31, v108
	v_ashrrev_i32_e32 v115, 31, v114
	v_ashrrev_i32_e32 v113, 31, v112
	v_lshlrev_b64 v[84:85], 12, v[84:85]
	v_lshl_add_u64 v[86:87], v[12:13], 0, v[86:87]
	v_lshlrev_b64 v[88:89], 12, v[88:89]
	v_lshlrev_b64 v[90:91], 12, v[90:91]
	v_lshlrev_b64 v[92:93], 12, v[92:93]
	v_lshlrev_b64 v[94:95], 12, v[94:95]
	v_lshlrev_b64 v[96:97], 12, v[96:97]
	v_lshlrev_b64 v[98:99], 12, v[98:99]
	v_lshlrev_b64 v[100:101], 12, v[100:101]
	v_lshlrev_b64 v[102:103], 12, v[102:103]
	v_lshlrev_b64 v[104:105], 12, v[104:105]
	v_lshlrev_b64 v[106:107], 12, v[106:107]
	v_lshlrev_b64 v[108:109], 12, v[108:109]
	v_lshlrev_b64 v[110:111], 12, v[110:111]
	v_lshlrev_b64 v[112:113], 12, v[112:113]
	v_lshlrev_b64 v[114:115], 12, v[114:115]
	v_lshl_add_u64 v[84:85], v[12:13], 0, v[84:85]
	v_lshl_add_u64 v[90:91], v[12:13], 0, v[90:91]
	v_lshl_add_u64 v[88:89], v[12:13], 0, v[88:89]
	v_lshl_add_u64 v[94:95], v[12:13], 0, v[94:95]
	v_lshl_add_u64 v[92:93], v[12:13], 0, v[92:93]
	v_lshl_add_u64 v[98:99], v[12:13], 0, v[98:99]
	v_lshl_add_u64 v[96:97], v[12:13], 0, v[96:97]
	v_lshl_add_u64 v[102:103], v[12:13], 0, v[102:103]
	v_lshl_add_u64 v[100:101], v[12:13], 0, v[100:101]
	v_lshl_add_u64 v[106:107], v[12:13], 0, v[106:107]
	v_lshl_add_u64 v[104:105], v[12:13], 0, v[104:105]
	v_lshl_add_u64 v[110:111], v[12:13], 0, v[110:111]
	v_lshl_add_u64 v[108:109], v[12:13], 0, v[108:109]
	v_lshl_add_u64 v[114:115], v[12:13], 0, v[114:115]
	v_lshl_add_u64 v[112:113], v[12:13], 0, v[112:113]
	global_load_dword v116, v[86:87], off
	global_load_dword v117, v[84:85], off
	global_load_dword v130, v[90:91], off
	global_load_dword v152, v[88:89], off
	global_load_dword v153, v[94:95], off
	global_load_dword v154, v[92:93], off
	global_load_dword v155, v[98:99], off
	global_load_dword v156, v[96:97], off
	global_load_dword v157, v[102:103], off
	global_load_dword v158, v[100:101], off
	global_load_dword v159, v[106:107], off
	global_load_dword v160, v[104:105], off
	global_load_dword v161, v[110:111], off
	global_load_dword v162, v[108:109], off
	global_load_dword v163, v[114:115], off
	global_load_dword v164, v[112:113], off
	v_or_b32_e32 v86, s36, v1
	v_or_b32_e32 v84, s37, v4
	s_add_i32 s28, s28, 16
	s_add_i32 s27, s27, 16
	s_add_i32 s29, s29, -16
	v_mad_u64_u32 v[84:85], s[36:37], v84, s31, v[6:7]
	v_mad_u64_u32 v[86:87], s[36:37], v86, s31, v[6:7]
	v_or_b32_e32 v85, s38, v1
	v_or_b32_e32 v87, s39, v4
	v_or_b32_e32 v94, s40, v1
	v_or_b32_e32 v92, s41, v4
	v_or_b32_e32 v98, s42, v1
	v_or_b32_e32 v96, s43, v4
	v_or_b32_e32 v102, s44, v1
	v_or_b32_e32 v100, s45, v4
	v_or_b32_e32 v106, s46, v1
	v_or_b32_e32 v104, s47, v4
	v_or_b32_e32 v110, s48, v1
	v_or_b32_e32 v108, s49, v4
	v_or_b32_e32 v114, s50, v1
	v_or_b32_e32 v112, s51, v4
	s_cmp_lg_u32 s29, 0
	v_mad_u64_u32 v[88:89], s[36:37], v87, s31, v[6:7]
	v_mad_u64_u32 v[90:91], s[36:37], v85, s31, v[6:7]
	v_mad_u64_u32 v[92:93], s[36:37], v92, s31, v[6:7]
	v_mad_u64_u32 v[94:95], s[36:37], v94, s31, v[6:7]
	v_mad_u64_u32 v[96:97], s[36:37], v96, s31, v[6:7]
	v_mad_u64_u32 v[98:99], s[36:37], v98, s31, v[6:7]
	v_mad_u64_u32 v[100:101], s[36:37], v100, s31, v[6:7]
	v_mad_u64_u32 v[102:103], s[36:37], v102, s31, v[6:7]
	v_mad_u64_u32 v[104:105], s[36:37], v104, s31, v[6:7]
	v_mad_u64_u32 v[106:107], s[36:37], v106, s31, v[6:7]
	v_mad_u64_u32 v[108:109], s[36:37], v108, s31, v[6:7]
	v_mad_u64_u32 v[110:111], s[36:37], v110, s31, v[6:7]
	v_mad_u64_u32 v[112:113], s[36:37], v112, s31, v[6:7]
	v_mad_u64_u32 v[114:115], s[36:37], v114, s31, v[6:7]
	s_waitcnt vmcnt(31)
	ds_write_b32 v22, v11
	s_waitcnt vmcnt(30)
	ds_write_b32 v24, v14
	s_waitcnt vmcnt(29)
	ds_write_b32 v26, v21
	s_waitcnt vmcnt(28)
	ds_write_b32 v28, v54
	s_waitcnt vmcnt(27)
	ds_write_b32 v30, v55
	s_waitcnt vmcnt(26)
	ds_write_b32 v32, v56
	s_waitcnt vmcnt(25)
	ds_write_b32 v34, v57
	s_waitcnt vmcnt(24)
	ds_write_b32 v36, v58
	s_waitcnt vmcnt(23)
	ds_write_b32 v38, v59
	s_waitcnt vmcnt(22)
	ds_write_b32 v40, v60
	s_waitcnt vmcnt(21)
	ds_write_b32 v42, v61
	s_waitcnt vmcnt(20)
	ds_write_b32 v44, v62
	s_waitcnt vmcnt(19)
	ds_write_b32 v46, v63
	s_waitcnt vmcnt(18)
	ds_write_b32 v48, v64
	s_waitcnt vmcnt(17)
	ds_write_b32 v50, v65
	s_waitcnt vmcnt(16)
	ds_write_b32 v52, v66
	s_waitcnt vmcnt(15)
	ds_write_b32 v84, v116
	s_waitcnt vmcnt(14)
	ds_write_b32 v86, v117
	s_waitcnt vmcnt(13)
	ds_write_b32 v88, v130
	s_waitcnt vmcnt(12)
	ds_write_b32 v90, v152
	s_waitcnt vmcnt(11)
	ds_write_b32 v92, v153
	s_waitcnt vmcnt(10)
	ds_write_b32 v94, v154
	s_waitcnt vmcnt(9)
	ds_write_b32 v96, v155
	s_waitcnt vmcnt(8)
	ds_write_b32 v98, v156
	s_waitcnt vmcnt(7)
	ds_write_b32 v100, v157
	s_waitcnt vmcnt(6)
	ds_write_b32 v102, v158
	s_waitcnt vmcnt(5)
	ds_write_b32 v104, v159
	s_waitcnt vmcnt(4)
	ds_write_b32 v106, v160
	s_waitcnt vmcnt(3)
	ds_write_b32 v108, v161
	s_waitcnt vmcnt(2)
	ds_write_b32 v110, v162
	s_waitcnt vmcnt(1)
	ds_write_b32 v112, v163
	s_waitcnt vmcnt(0)
	ds_write_b32 v114, v164
	v_mov_b32_e32 v14, v117
	v_mov_b32_e32 v21, v130
	v_mov_b32_e32 v44, v106
	v_mov_b32_e32 v45, v107
	v_mov_b32_e32 v46, v108
	v_mov_b32_e32 v47, v109
	v_mov_b32_e32 v48, v110
	v_mov_b32_e32 v49, v111
	v_mov_b32_e32 v50, v112
	v_mov_b32_e32 v51, v113
	v_mov_b32_e32 v52, v114
	v_mov_b32_e32 v53, v115
	v_mov_b32_e32 v54, v152
	v_mov_b32_e32 v55, v153
	v_mov_b32_e32 v56, v154
	v_mov_b32_e32 v57, v155
	v_mov_b32_e32 v58, v156
	v_mov_b32_e32 v59, v157
	v_mov_b32_e32 v60, v158
	v_mov_b32_e32 v61, v159
	s_waitcnt lgkmcnt(0)
	s_lshl_b64 s[28:29], s[8:9], 1
	ds_read2_b32 v[26:27], v16 offset0:33 offset1:41
	ds_read2_b32 v[28:29], v16 offset1:8
	ds_read2_b32 v[30:31], v16 offset0:66 offset1:74
	ds_read2_b32 v[32:33], v16 offset0:99 offset1:107
	ds_read2_b32 v[34:35], v16 offset0:132 offset1:140
	ds_read2_b32 v[36:37], v16 offset0:165 offset1:173
	ds_read2_b32 v[38:39], v16 offset0:198 offset1:206
	ds_read2_b32 v[40:41], v16 offset0:231 offset1:239
	s_add_u32 s24, s24, s28
	s_addc_u32 s25, s25, s29
	v_mov_b32_e32 v11, v9
	v_lshl_add_u64 v[12:13], s[24:25], 0, v[10:11]
	v_or_b32_e32 v3, s26, v7
	v_lshl_add_u64 v[12:13], v[12:13], 0, s[14:15]
	v_lshlrev_b32_e32 v8, 11, v3
	s_waitcnt lgkmcnt(6)
	v_cvt_pk_bf16_f32 v22, v28, v26
	s_waitcnt lgkmcnt(4)
	v_cvt_pk_bf16_f32 v23, v30, v32
	s_waitcnt lgkmcnt(2)
	v_cvt_pk_bf16_f32 v24, v34, v36
	s_waitcnt lgkmcnt(0)
	v_cvt_pk_bf16_f32 v25, v38, v40
	v_lshl_add_u64 v[42:43], v[12:13], 0, v[8:9]
	global_store_dwordx4 v[42:43], v[22:25], off
	v_or_b32_e32 v3, s26, v17
	v_lshlrev_b32_e32 v8, 11, v3
	v_cvt_pk_bf16_f32 v22, v29, v27
	v_cvt_pk_bf16_f32 v23, v31, v33
	v_cvt_pk_bf16_f32 v24, v35, v37
	v_cvt_pk_bf16_f32 v25, v39, v41
	ds_read2_b32 v[28:29], v16 offset0:49 offset1:57
	ds_read2_b32 v[30:31], v16 offset0:16 offset1:24
	ds_read2_b32 v[32:33], v16 offset0:82 offset1:90
	ds_read2_b32 v[34:35], v16 offset0:115 offset1:123
	ds_read2_b32 v[36:37], v16 offset0:148 offset1:156
	ds_read2_b32 v[38:39], v16 offset0:181 offset1:189
	ds_read2_b32 v[40:41], v16 offset0:214 offset1:222
	ds_read2_b32 v[42:43], v16 offset0:247 offset1:255
	v_or_b32_e32 v3, s26, v18
	v_lshl_add_u64 v[26:27], v[12:13], 0, v[8:9]
	v_lshlrev_b32_e32 v8, 11, v3
	v_or_b32_e32 v3, s26, v19
	global_store_dwordx4 v[26:27], v[22:25], off
	v_lshl_add_u64 v[26:27], v[12:13], 0, v[8:9]
	v_lshlrev_b32_e32 v8, 11, v3
	s_waitcnt lgkmcnt(6)
	v_cvt_pk_bf16_f32 v22, v30, v28
	s_waitcnt lgkmcnt(4)
	v_cvt_pk_bf16_f32 v23, v32, v34
	s_waitcnt lgkmcnt(2)
	v_cvt_pk_bf16_f32 v24, v36, v38
	s_waitcnt lgkmcnt(0)
	v_cvt_pk_bf16_f32 v25, v40, v42
	global_store_dwordx4 v[26:27], v[22:25], off
	v_lshl_add_u64 v[12:13], v[12:13], 0, v[8:9]
	s_nop 0
	v_cvt_pk_bf16_f32 v22, v31, v29
	v_cvt_pk_bf16_f32 v23, v33, v35
	v_cvt_pk_bf16_f32 v24, v37, v39
	v_cvt_pk_bf16_f32 v25, v41, v43
	global_store_dwordx4 v[12:13], v[22:25], off
	s_waitcnt lgkmcnt(0)

.LBB0_29:
	s_lshl_b32 s37, s28, 1
	s_lshl_b32 s38, s29, 1
	v_or_b32_e32 v8, s38, v14
	s_add_i32 s40, s37, 4
	s_add_i32 s41, s38, 4
	v_mov_b32_e32 v25, v9
	s_add_i32 s43, s38, 8
	v_lshlrev_b64 v[38:39], 12, v[8:9]
	v_or_b32_e32 v24, s40, v3
	v_or_b32_e32 v8, s41, v14
	v_mov_b32_e32 v23, v9
	v_or_b32_e32 v22, s37, v3
	s_add_i32 s45, s38, 12
	v_lshlrev_b64 v[24:25], 12, v[24:25]
	v_lshlrev_b64 v[40:41], 12, v[8:9]
	v_or_b32_e32 v8, s43, v14
	s_add_i32 s42, s37, 8
	s_add_i32 s44, s37, 12
	s_add_i32 s47, s38, 16
	v_lshlrev_b64 v[22:23], 12, v[22:23]
	v_lshl_add_u64 v[38:39], v[12:13], 0, v[38:39]
	v_lshl_add_u64 v[24:25], v[12:13], 0, v[24:25]
	v_lshlrev_b64 v[42:43], 12, v[8:9]
	v_or_b32_e32 v8, s45, v14
	v_mov_b32_e32 v27, v9
	v_mov_b32_e32 v29, v9
	s_add_i32 s49, s38, 20
	v_or_b32_e32 v26, s42, v3
	v_or_b32_e32 v28, s44, v3
	v_lshl_add_u64 v[22:23], v[12:13], 0, v[22:23]
	v_lshl_add_u64 v[40:41], v[12:13], 0, v[40:41]
	global_load_dword v11, v[38:39], off
	global_load_dword v21, v[22:23], off
	global_load_dword v54, v[40:41], off
	global_load_dword v55, v[24:25], off
	v_lshlrev_b64 v[24:25], 12, v[8:9]
	v_or_b32_e32 v8, s47, v14
	s_add_i32 s46, s37, 16
	s_add_i32 s48, s37, 20
	s_add_i32 s51, s38, 24
	v_lshlrev_b64 v[26:27], 12, v[26:27]
	v_lshlrev_b64 v[28:29], 12, v[28:29]
	v_lshl_add_u64 v[22:23], v[12:13], 0, v[42:43]
	v_lshl_add_u64 v[24:25], v[12:13], 0, v[24:25]
	v_lshlrev_b64 v[38:39], 12, v[8:9]
	v_or_b32_e32 v8, s49, v14
	v_mov_b32_e32 v31, v9
	v_mov_b32_e32 v33, v9
	s_add_i32 s50, s37, 24
	s_add_i32 s52, s37, 28
	s_add_i32 s53, s38, 28
	v_or_b32_e32 v30, s46, v3
	v_or_b32_e32 v32, s48, v3
	v_lshl_add_u64 v[26:27], v[12:13], 0, v[26:27]
	v_lshl_add_u64 v[28:29], v[12:13], 0, v[28:29]
	global_load_dword v56, v[22:23], off
	global_load_dword v57, v[26:27], off
	global_load_dword v58, v[24:25], off
	global_load_dword v59, v[28:29], off
	v_lshlrev_b64 v[24:25], 12, v[8:9]
	v_or_b32_e32 v8, s51, v14
	v_mov_b32_e32 v35, v9
	v_mov_b32_e32 v37, v9
	v_or_b32_e32 v34, s50, v3
	v_or_b32_e32 v36, s52, v3
	v_lshlrev_b64 v[30:31], 12, v[30:31]
	v_lshlrev_b64 v[32:33], 12, v[32:33]
	v_lshl_add_u64 v[22:23], v[12:13], 0, v[38:39]
	v_lshl_add_u64 v[24:25], v[12:13], 0, v[24:25]
	v_lshlrev_b64 v[26:27], 12, v[8:9]
	v_or_b32_e32 v8, s53, v14
	v_lshlrev_b64 v[34:35], 12, v[34:35]
	v_lshlrev_b64 v[36:37], 12, v[36:37]
	v_lshl_add_u64 v[30:31], v[12:13], 0, v[30:31]
	v_lshl_add_u64 v[32:33], v[12:13], 0, v[32:33]
	global_load_dword v60, v[22:23], off
	global_load_dword v61, v[30:31], off
	global_load_dword v62, v[24:25], off
	global_load_dword v63, v[32:33], off
	v_lshl_add_u64 v[22:23], v[12:13], 0, v[26:27]
	v_lshlrev_b64 v[24:25], 12, v[8:9]
	v_lshl_add_u64 v[34:35], v[12:13], 0, v[34:35]
	v_lshl_add_u64 v[36:37], v[12:13], 0, v[36:37]
	v_lshl_add_u64 v[24:25], v[12:13], 0, v[24:25]
	global_load_dword v8, v[22:23], off
	global_load_dword v64, v[34:35], off
	global_load_dword v65, v[24:25], off
	global_load_dword v66, v[36:37], off
	v_or_b32_e32 v24, s37, v1
	v_or_b32_e32 v22, s38, v4
	s_add_i32 s29, s29, 16
	s_add_i32 s28, s28, 16
	s_add_i32 s36, s36, -16
	v_mad_u64_u32 v[22:23], s[38:39], v22, s31, v[6:7]
	v_mad_u64_u32 v[24:25], s[38:39], v24, s31, v[6:7]
	v_or_b32_e32 v23, s40, v1
	v_or_b32_e32 v25, s41, v4
	v_or_b32_e32 v32, s42, v1
	v_or_b32_e32 v30, s43, v4
	v_or_b32_e32 v36, s44, v1
	v_or_b32_e32 v34, s45, v4
	v_or_b32_e32 v40, s46, v1
	v_or_b32_e32 v38, s47, v4
	v_or_b32_e32 v44, s48, v1
	v_or_b32_e32 v42, s49, v4
	v_or_b32_e32 v48, s50, v1
	v_or_b32_e32 v46, s51, v4
	v_or_b32_e32 v52, s52, v1
	v_or_b32_e32 v50, s53, v4
	s_cmp_lg_u32 s36, 0
	v_mad_u64_u32 v[26:27], s[38:39], v25, s31, v[6:7]
	v_mad_u64_u32 v[28:29], s[38:39], v23, s31, v[6:7]
	v_mad_u64_u32 v[30:31], s[38:39], v30, s31, v[6:7]
	v_mad_u64_u32 v[32:33], s[38:39], v32, s31, v[6:7]
	v_mad_u64_u32 v[34:35], s[38:39], v34, s31, v[6:7]
	v_mad_u64_u32 v[36:37], s[38:39], v36, s31, v[6:7]
	v_mad_u64_u32 v[38:39], s[38:39], v38, s31, v[6:7]
	v_mad_u64_u32 v[40:41], s[38:39], v40, s31, v[6:7]
	v_mad_u64_u32 v[42:43], s[38:39], v42, s31, v[6:7]
	v_mad_u64_u32 v[44:45], s[38:39], v44, s31, v[6:7]
	v_mad_u64_u32 v[46:47], s[38:39], v46, s31, v[6:7]
	v_mad_u64_u32 v[48:49], s[38:39], v48, s31, v[6:7]
	v_mad_u64_u32 v[50:51], s[38:39], v50, s31, v[6:7]
	v_mad_u64_u32 v[52:53], s[38:39], v52, s31, v[6:7]
	v_mov_b32_e32 v85, v9
	s_lshl_b32 s37, s28, 1
	s_lshl_b32 s38, s29, 1
	v_or_b32_e32 v84, s38, v14
	s_add_i32 s40, s37, 4
	s_add_i32 s41, s38, 4
	v_mov_b32_e32 v89, v85
	s_add_i32 s43, s38, 8
	v_lshlrev_b64 v[102:103], 12, v[84:85]
	v_or_b32_e32 v88, s40, v3
	v_or_b32_e32 v84, s41, v14
	v_mov_b32_e32 v87, v85
	v_or_b32_e32 v86, s37, v3
	s_add_i32 s45, s38, 12
	v_lshlrev_b64 v[88:89], 12, v[88:89]
	v_lshlrev_b64 v[104:105], 12, v[84:85]
	v_or_b32_e32 v84, s43, v14
	s_add_i32 s42, s37, 8
	s_add_i32 s44, s37, 12
	s_add_i32 s47, s38, 16
	v_lshlrev_b64 v[86:87], 12, v[86:87]
	v_lshl_add_u64 v[102:103], v[12:13], 0, v[102:103]
	v_lshl_add_u64 v[88:89], v[12:13], 0, v[88:89]
	v_lshlrev_b64 v[106:107], 12, v[84:85]
	v_or_b32_e32 v84, s45, v14
	v_mov_b32_e32 v91, v85
	v_mov_b32_e32 v93, v85
	s_add_i32 s49, s38, 20
	v_or_b32_e32 v90, s42, v3
	v_or_b32_e32 v92, s44, v3
	v_lshl_add_u64 v[86:87], v[12:13], 0, v[86:87]
	v_lshl_add_u64 v[104:105], v[12:13], 0, v[104:105]
	global_load_dword v130, v[102:103], off
	global_load_dword v152, v[86:87], off
	global_load_dword v153, v[104:105], off
	global_load_dword v154, v[88:89], off
	v_lshlrev_b64 v[88:89], 12, v[84:85]
	v_or_b32_e32 v84, s47, v14
	s_add_i32 s46, s37, 16
	s_add_i32 s48, s37, 20
	s_add_i32 s51, s38, 24
	v_lshlrev_b64 v[90:91], 12, v[90:91]
	v_lshlrev_b64 v[92:93], 12, v[92:93]
	v_lshl_add_u64 v[86:87], v[12:13], 0, v[106:107]
	v_lshl_add_u64 v[88:89], v[12:13], 0, v[88:89]
	v_lshlrev_b64 v[102:103], 12, v[84:85]
	v_or_b32_e32 v84, s49, v14
	v_mov_b32_e32 v95, v85
	v_mov_b32_e32 v97, v85
	s_add_i32 s50, s37, 24
	s_add_i32 s52, s37, 28
	s_add_i32 s53, s38, 28
	v_or_b32_e32 v94, s46, v3
	v_or_b32_e32 v96, s48, v3
	v_lshl_add_u64 v[90:91], v[12:13], 0, v[90:91]
	v_lshl_add_u64 v[92:93], v[12:13], 0, v[92:93]
	global_load_dword v155, v[86:87], off
	global_load_dword v156, v[90:91], off
	global_load_dword v157, v[88:89], off
	global_load_dword v158, v[92:93], off
	v_lshlrev_b64 v[88:89], 12, v[84:85]
	v_or_b32_e32 v84, s51, v14
	v_mov_b32_e32 v99, v85
	v_mov_b32_e32 v101, v85
	v_or_b32_e32 v98, s50, v3
	v_or_b32_e32 v100, s52, v3
	v_lshlrev_b64 v[94:95], 12, v[94:95]
	v_lshlrev_b64 v[96:97], 12, v[96:97]
	v_lshl_add_u64 v[86:87], v[12:13], 0, v[102:103]
	v_lshl_add_u64 v[88:89], v[12:13], 0, v[88:89]
	v_lshlrev_b64 v[90:91], 12, v[84:85]
	v_or_b32_e32 v84, s53, v14
	v_lshlrev_b64 v[98:99], 12, v[98:99]
	v_lshlrev_b64 v[100:101], 12, v[100:101]
	v_lshl_add_u64 v[94:95], v[12:13], 0, v[94:95]
	v_lshl_add_u64 v[96:97], v[12:13], 0, v[96:97]
	global_load_dword v159, v[86:87], off
	global_load_dword v160, v[94:95], off
	global_load_dword v161, v[88:89], off
	global_load_dword v162, v[96:97], off
	v_lshl_add_u64 v[86:87], v[12:13], 0, v[90:91]
	v_lshlrev_b64 v[88:89], 12, v[84:85]
	v_lshl_add_u64 v[98:99], v[12:13], 0, v[98:99]
	v_lshl_add_u64 v[100:101], v[12:13], 0, v[100:101]
	v_lshl_add_u64 v[88:89], v[12:13], 0, v[88:89]
	global_load_dword v84, v[86:87], off
	global_load_dword v163, v[98:99], off
	global_load_dword v164, v[88:89], off
	global_load_dword v165, v[100:101], off
	v_or_b32_e32 v88, s37, v1
	v_or_b32_e32 v86, s38, v4
	s_add_i32 s29, s29, 16
	s_add_i32 s28, s28, 16
	s_add_i32 s36, s36, -16
	v_mad_u64_u32 v[86:87], s[38:39], v86, s31, v[6:7]
	v_mad_u64_u32 v[88:89], s[38:39], v88, s31, v[6:7]
	v_or_b32_e32 v87, s40, v1
	v_or_b32_e32 v89, s41, v4
	v_or_b32_e32 v96, s42, v1
	v_or_b32_e32 v94, s43, v4
	v_or_b32_e32 v100, s44, v1
	v_or_b32_e32 v98, s45, v4
	v_or_b32_e32 v104, s46, v1
	v_or_b32_e32 v102, s47, v4
	v_or_b32_e32 v108, s48, v1
	v_or_b32_e32 v106, s49, v4
	v_or_b32_e32 v112, s50, v1
	v_or_b32_e32 v110, s51, v4
	v_or_b32_e32 v116, s52, v1
	v_or_b32_e32 v114, s53, v4
	s_cmp_lg_u32 s36, 0
	v_mad_u64_u32 v[90:91], s[38:39], v89, s31, v[6:7]
	v_mad_u64_u32 v[92:93], s[38:39], v87, s31, v[6:7]
	v_mad_u64_u32 v[94:95], s[38:39], v94, s31, v[6:7]
	v_mad_u64_u32 v[96:97], s[38:39], v96, s31, v[6:7]
	v_mad_u64_u32 v[98:99], s[38:39], v98, s31, v[6:7]
	v_mad_u64_u32 v[100:101], s[38:39], v100, s31, v[6:7]
	v_mad_u64_u32 v[102:103], s[38:39], v102, s31, v[6:7]
	v_mad_u64_u32 v[104:105], s[38:39], v104, s31, v[6:7]
	v_mad_u64_u32 v[106:107], s[38:39], v106, s31, v[6:7]
	v_mad_u64_u32 v[108:109], s[38:39], v108, s31, v[6:7]
	v_mad_u64_u32 v[110:111], s[38:39], v110, s31, v[6:7]
	v_mad_u64_u32 v[112:113], s[38:39], v112, s31, v[6:7]
	v_mad_u64_u32 v[114:115], s[38:39], v114, s31, v[6:7]
	v_mad_u64_u32 v[116:117], s[38:39], v116, s31, v[6:7]
	s_waitcnt vmcnt(31)
	ds_write_b32 v22, v11
	s_waitcnt vmcnt(30)
	ds_write_b32 v24, v21
	s_waitcnt vmcnt(29)
	ds_write_b32 v26, v54
	s_waitcnt vmcnt(28)
	ds_write_b32 v28, v55
	s_waitcnt vmcnt(27)
	ds_write_b32 v30, v56
	s_waitcnt vmcnt(26)
	ds_write_b32 v32, v57
	s_waitcnt vmcnt(25)
	ds_write_b32 v34, v58
	s_waitcnt vmcnt(24)
	ds_write_b32 v36, v59
	s_waitcnt vmcnt(23)
	ds_write_b32 v38, v60
	s_waitcnt vmcnt(22)
	ds_write_b32 v40, v61
	s_waitcnt vmcnt(21)
	ds_write_b32 v42, v62
	s_waitcnt vmcnt(20)
	ds_write_b32 v44, v63
	s_waitcnt vmcnt(19)
	ds_write_b32 v46, v8
	s_waitcnt vmcnt(18)
	ds_write_b32 v48, v64
	s_waitcnt vmcnt(17)
	ds_write_b32 v50, v65
	s_waitcnt vmcnt(16)
	ds_write_b32 v52, v66
	s_waitcnt vmcnt(15)
	ds_write_b32 v86, v130
	s_waitcnt vmcnt(14)
	ds_write_b32 v88, v152
	s_waitcnt vmcnt(13)
	ds_write_b32 v90, v153
	s_waitcnt vmcnt(12)
	ds_write_b32 v92, v154
	s_waitcnt vmcnt(11)
	ds_write_b32 v94, v155
	s_waitcnt vmcnt(10)
	ds_write_b32 v96, v156
	s_waitcnt vmcnt(9)
	ds_write_b32 v98, v157
	s_waitcnt vmcnt(8)
	ds_write_b32 v100, v158
	s_waitcnt vmcnt(7)
	ds_write_b32 v102, v159
	s_waitcnt vmcnt(6)
	ds_write_b32 v104, v160
	s_waitcnt vmcnt(5)
	ds_write_b32 v106, v161
	s_waitcnt vmcnt(4)
	ds_write_b32 v108, v162
	s_waitcnt vmcnt(3)
	ds_write_b32 v110, v84
	s_waitcnt vmcnt(2)
	ds_write_b32 v112, v163
	s_waitcnt vmcnt(1)
	ds_write_b32 v114, v164
	s_waitcnt vmcnt(0)
	ds_write_b32 v116, v165
	v_mov_b32_e32 v21, v152
	v_mov_b32_e32 v44, v108
	v_mov_b32_e32 v45, v109
	v_mov_b32_e32 v46, v110
	v_mov_b32_e32 v47, v111
	v_mov_b32_e32 v48, v112
	v_mov_b32_e32 v49, v113
	v_mov_b32_e32 v50, v114
	v_mov_b32_e32 v51, v115
	v_mov_b32_e32 v52, v116
	v_mov_b32_e32 v53, v117
	v_mov_b32_e32 v54, v153
	v_mov_b32_e32 v55, v154
	v_mov_b32_e32 v56, v155
	v_mov_b32_e32 v57, v156
	v_mov_b32_e32 v58, v157
	v_mov_b32_e32 v59, v158
	v_mov_b32_e32 v60, v159
	v_mov_b32_e32 v61, v160
	s_lshl_b64 s[28:29], s[8:9], 20
	s_add_u32 s8, s24, s28
	s_waitcnt lgkmcnt(0)
	s_addc_u32 s25, s25, s29
	s_lshl_b32 s24, s27, 1
	ds_read2_b32 v[26:27], v16 offset0:33 offset1:41
	ds_read2_b32 v[28:29], v16 offset1:8
	ds_read2_b32 v[30:31], v16 offset0:66 offset1:74
	ds_read2_b32 v[32:33], v16 offset0:99 offset1:107
	ds_read2_b32 v[34:35], v16 offset0:132 offset1:140
	ds_read2_b32 v[36:37], v16 offset0:165 offset1:173
	ds_read2_b32 v[38:39], v16 offset0:198 offset1:206
	ds_read2_b32 v[40:41], v16 offset0:231 offset1:239
	s_add_u32 s24, s8, s24
	s_addc_u32 s25, s25, 0
	v_mov_b32_e32 v11, v9
	v_lshl_add_u64 v[12:13], s[24:25], 0, v[10:11]
	v_or_b32_e32 v3, s26, v7
	v_lshl_add_u64 v[12:13], v[12:13], 0, s[16:17]
	v_lshlrev_b32_e32 v8, 10, v3
	s_waitcnt lgkmcnt(6)
	v_cvt_pk_bf16_f32 v22, v28, v26
	s_waitcnt lgkmcnt(4)
	v_cvt_pk_bf16_f32 v23, v30, v32
	s_waitcnt lgkmcnt(2)
	v_cvt_pk_bf16_f32 v24, v34, v36
	s_waitcnt lgkmcnt(0)
	v_cvt_pk_bf16_f32 v25, v38, v40
	v_lshl_add_u64 v[42:43], v[12:13], 0, v[8:9]
	global_store_dwordx4 v[42:43], v[22:25], off
	v_or_b32_e32 v3, s26, v17
	v_lshlrev_b32_e32 v8, 10, v3
	v_cvt_pk_bf16_f32 v22, v29, v27
	v_cvt_pk_bf16_f32 v23, v31, v33
	v_cvt_pk_bf16_f32 v24, v35, v37
	v_cvt_pk_bf16_f32 v25, v39, v41
	ds_read2_b32 v[28:29], v16 offset0:49 offset1:57
	ds_read2_b32 v[30:31], v16 offset0:16 offset1:24
	ds_read2_b32 v[32:33], v16 offset0:82 offset1:90
	ds_read2_b32 v[34:35], v16 offset0:115 offset1:123
	ds_read2_b32 v[36:37], v16 offset0:148 offset1:156
	ds_read2_b32 v[38:39], v16 offset0:181 offset1:189
	ds_read2_b32 v[40:41], v16 offset0:214 offset1:222
	ds_read2_b32 v[42:43], v16 offset0:247 offset1:255
	v_or_b32_e32 v3, s26, v18
	v_lshl_add_u64 v[26:27], v[12:13], 0, v[8:9]
	v_lshlrev_b32_e32 v8, 10, v3
	v_or_b32_e32 v3, s26, v19
	global_store_dwordx4 v[26:27], v[22:25], off
	v_lshl_add_u64 v[26:27], v[12:13], 0, v[8:9]
	v_lshlrev_b32_e32 v8, 10, v3
	s_waitcnt lgkmcnt(6)
	v_cvt_pk_bf16_f32 v22, v30, v28
	s_waitcnt lgkmcnt(4)
	v_cvt_pk_bf16_f32 v23, v32, v34
	s_waitcnt lgkmcnt(2)
	v_cvt_pk_bf16_f32 v24, v36, v38
	s_waitcnt lgkmcnt(0)
	v_cvt_pk_bf16_f32 v25, v40, v42
	global_store_dwordx4 v[26:27], v[22:25], off
	v_lshl_add_u64 v[12:13], v[12:13], 0, v[8:9]
	s_nop 0
	v_cvt_pk_bf16_f32 v22, v31, v29
	v_cvt_pk_bf16_f32 v23, v33, v35
	v_cvt_pk_bf16_f32 v24, v37, v39
	v_cvt_pk_bf16_f32 v25, v41, v43
	global_store_dwordx4 v[12:13], v[22:25], off
	s_waitcnt lgkmcnt(0)

.LBB0_34:
	s_lshl_b32 s38, s27, 1
	s_lshl_b32 s39, s28, 1
	v_or_b32_e32 v11, s38, v3
	v_or_b32_e32 v14, s39, v8
	s_add_i32 s40, s38, 4
	s_add_i32 s41, s39, 4
	s_add_i32 s42, s38, 8
	s_add_i32 s43, s39, 8
	s_add_i32 s44, s38, 12
	s_add_i32 s45, s39, 12
	s_add_i32 s46, s38, 16
	s_add_i32 s47, s39, 16
	s_add_i32 s48, s38, 20
	s_add_i32 s49, s39, 20
	s_add_i32 s50, s38, 24
	s_add_i32 s51, s39, 24
	s_add_i32 s52, s38, 28
	s_add_i32 s53, s39, 28
	v_mad_u64_u32 v[22:23], s[36:37], v14, s34, v[12:13]
	v_mad_u64_u32 v[24:25], s[36:37], v11, s34, v[12:13]
	v_or_b32_e32 v11, s40, v3
	v_or_b32_e32 v14, s41, v8
	v_or_b32_e32 v21, s42, v3
	v_or_b32_e32 v30, s43, v8
	v_or_b32_e32 v36, s44, v3
	v_or_b32_e32 v34, s45, v8
	v_or_b32_e32 v40, s46, v3
	v_or_b32_e32 v38, s47, v8
	v_or_b32_e32 v44, s48, v3
	v_or_b32_e32 v42, s49, v8
	v_or_b32_e32 v48, s50, v3
	v_or_b32_e32 v46, s51, v8
	v_or_b32_e32 v52, s52, v3
	v_or_b32_e32 v50, s53, v8
	v_mad_u64_u32 v[26:27], s[36:37], v14, s34, v[12:13]
	v_mad_u64_u32 v[28:29], s[36:37], v11, s34, v[12:13]
	v_mad_u64_u32 v[30:31], s[36:37], v30, s34, v[12:13]
	v_mad_u64_u32 v[32:33], s[36:37], v21, s34, v[12:13]
	v_mad_u64_u32 v[34:35], s[36:37], v34, s34, v[12:13]
	v_mad_u64_u32 v[36:37], s[36:37], v36, s34, v[12:13]
	v_mad_u64_u32 v[38:39], s[36:37], v38, s34, v[12:13]
	v_mad_u64_u32 v[40:41], s[36:37], v40, s34, v[12:13]
	v_mad_u64_u32 v[42:43], s[36:37], v42, s34, v[12:13]
	v_mad_u64_u32 v[44:45], s[36:37], v44, s34, v[12:13]
	v_mad_u64_u32 v[46:47], s[36:37], v46, s34, v[12:13]
	v_mad_u64_u32 v[48:49], s[36:37], v48, s34, v[12:13]
	v_mad_u64_u32 v[50:51], s[36:37], v50, s34, v[12:13]
	v_mad_u64_u32 v[52:53], s[36:37], v52, s34, v[12:13]
	global_load_dword v11, v[22:23], off
	global_load_dword v14, v[24:25], off
	global_load_dword v21, v[26:27], off
	global_load_dword v54, v[28:29], off
	global_load_dword v55, v[30:31], off
	global_load_dword v56, v[32:33], off
	global_load_dword v57, v[34:35], off
	global_load_dword v58, v[36:37], off
	global_load_dword v59, v[38:39], off
	global_load_dword v60, v[40:41], off
	global_load_dword v61, v[42:43], off
	global_load_dword v62, v[44:45], off
	global_load_dword v63, v[46:47], off
	global_load_dword v64, v[48:49], off
	global_load_dword v65, v[50:51], off
	global_load_dword v66, v[52:53], off
	v_or_b32_e32 v24, s38, v1
	v_or_b32_e32 v22, s39, v4
	s_add_i32 s28, s28, 16
	s_add_i32 s27, s27, 16
	s_add_i32 s29, s29, -16
	v_mad_u64_u32 v[22:23], s[36:37], v22, s31, v[6:7]
	v_mad_u64_u32 v[24:25], s[36:37], v24, s31, v[6:7]
	v_or_b32_e32 v23, s40, v1
	v_or_b32_e32 v25, s41, v4
	v_or_b32_e32 v32, s42, v1
	v_or_b32_e32 v30, s43, v4
	v_or_b32_e32 v36, s44, v1
	v_or_b32_e32 v34, s45, v4
	v_or_b32_e32 v40, s46, v1
	v_or_b32_e32 v38, s47, v4
	v_or_b32_e32 v44, s48, v1
	v_or_b32_e32 v42, s49, v4
	v_or_b32_e32 v48, s50, v1
	v_or_b32_e32 v46, s51, v4
	v_or_b32_e32 v52, s52, v1
	v_or_b32_e32 v50, s53, v4
	s_cmp_lg_u32 s29, 0
	v_mad_u64_u32 v[26:27], s[36:37], v25, s31, v[6:7]
	v_mad_u64_u32 v[28:29], s[36:37], v23, s31, v[6:7]
	v_mad_u64_u32 v[30:31], s[36:37], v30, s31, v[6:7]
	v_mad_u64_u32 v[32:33], s[36:37], v32, s31, v[6:7]
	v_mad_u64_u32 v[34:35], s[36:37], v34, s31, v[6:7]
	v_mad_u64_u32 v[36:37], s[36:37], v36, s31, v[6:7]
	v_mad_u64_u32 v[38:39], s[36:37], v38, s31, v[6:7]
	v_mad_u64_u32 v[40:41], s[36:37], v40, s31, v[6:7]
	v_mad_u64_u32 v[42:43], s[36:37], v42, s31, v[6:7]
	v_mad_u64_u32 v[44:45], s[36:37], v44, s31, v[6:7]
	v_mad_u64_u32 v[46:47], s[36:37], v46, s31, v[6:7]
	v_mad_u64_u32 v[48:49], s[36:37], v48, s31, v[6:7]
	v_mad_u64_u32 v[50:51], s[36:37], v50, s31, v[6:7]
	v_mad_u64_u32 v[52:53], s[36:37], v52, s31, v[6:7]
	s_lshl_b32 s38, s27, 1
	s_lshl_b32 s39, s28, 1
	v_or_b32_e32 v116, s38, v3
	v_or_b32_e32 v117, s39, v8
	s_add_i32 s40, s38, 4
	s_add_i32 s41, s39, 4
	s_add_i32 s42, s38, 8
	s_add_i32 s43, s39, 8
	s_add_i32 s44, s38, 12
	s_add_i32 s45, s39, 12
	s_add_i32 s46, s38, 16
	s_add_i32 s47, s39, 16
	s_add_i32 s48, s38, 20
	s_add_i32 s49, s39, 20
	s_add_i32 s50, s38, 24
	s_add_i32 s51, s39, 24
	s_add_i32 s52, s38, 28
	s_add_i32 s53, s39, 28
	v_mad_u64_u32 v[84:85], s[36:37], v117, s34, v[12:13]
	v_mad_u64_u32 v[86:87], s[36:37], v116, s34, v[12:13]
	v_or_b32_e32 v116, s40, v3
	v_or_b32_e32 v117, s41, v8
	v_or_b32_e32 v130, s42, v3
	v_or_b32_e32 v92, s43, v8
	v_or_b32_e32 v98, s44, v3
	v_or_b32_e32 v96, s45, v8
	v_or_b32_e32 v102, s46, v3
	v_or_b32_e32 v100, s47, v8
	v_or_b32_e32 v106, s48, v3
	v_or_b32_e32 v104, s49, v8
	v_or_b32_e32 v110, s50, v3
	v_or_b32_e32 v108, s51, v8
	v_or_b32_e32 v114, s52, v3
	v_or_b32_e32 v112, s53, v8
	v_mad_u64_u32 v[88:89], s[36:37], v117, s34, v[12:13]
	v_mad_u64_u32 v[90:91], s[36:37], v116, s34, v[12:13]
	v_mad_u64_u32 v[92:93], s[36:37], v92, s34, v[12:13]
	v_mad_u64_u32 v[94:95], s[36:37], v130, s34, v[12:13]
	v_mad_u64_u32 v[96:97], s[36:37], v96, s34, v[12:13]
	v_mad_u64_u32 v[98:99], s[36:37], v98, s34, v[12:13]
	v_mad_u64_u32 v[100:101], s[36:37], v100, s34, v[12:13]
	v_mad_u64_u32 v[102:103], s[36:37], v102, s34, v[12:13]
	v_mad_u64_u32 v[104:105], s[36:37], v104, s34, v[12:13]
	v_mad_u64_u32 v[106:107], s[36:37], v106, s34, v[12:13]
	v_mad_u64_u32 v[108:109], s[36:37], v108, s34, v[12:13]
	v_mad_u64_u32 v[110:111], s[36:37], v110, s34, v[12:13]
	v_mad_u64_u32 v[112:113], s[36:37], v112, s34, v[12:13]
	v_mad_u64_u32 v[114:115], s[36:37], v114, s34, v[12:13]
	global_load_dword v116, v[84:85], off
	global_load_dword v117, v[86:87], off
	global_load_dword v130, v[88:89], off
	global_load_dword v152, v[90:91], off
	global_load_dword v153, v[92:93], off
	global_load_dword v154, v[94:95], off
	global_load_dword v155, v[96:97], off
	global_load_dword v156, v[98:99], off
	global_load_dword v157, v[100:101], off
	global_load_dword v158, v[102:103], off
	global_load_dword v159, v[104:105], off
	global_load_dword v160, v[106:107], off
	global_load_dword v161, v[108:109], off
	global_load_dword v162, v[110:111], off
	global_load_dword v163, v[112:113], off
	global_load_dword v164, v[114:115], off
	v_or_b32_e32 v86, s38, v1
	v_or_b32_e32 v84, s39, v4
	s_add_i32 s28, s28, 16
	s_add_i32 s27, s27, 16
	s_add_i32 s29, s29, -16
	v_mad_u64_u32 v[84:85], s[36:37], v84, s31, v[6:7]
	v_mad_u64_u32 v[86:87], s[36:37], v86, s31, v[6:7]
	v_or_b32_e32 v85, s40, v1
	v_or_b32_e32 v87, s41, v4
	v_or_b32_e32 v94, s42, v1
	v_or_b32_e32 v92, s43, v4
	v_or_b32_e32 v98, s44, v1
	v_or_b32_e32 v96, s45, v4
	v_or_b32_e32 v102, s46, v1
	v_or_b32_e32 v100, s47, v4
	v_or_b32_e32 v106, s48, v1
	v_or_b32_e32 v104, s49, v4
	v_or_b32_e32 v110, s50, v1
	v_or_b32_e32 v108, s51, v4
	v_or_b32_e32 v114, s52, v1
	v_or_b32_e32 v112, s53, v4
	s_cmp_lg_u32 s29, 0
	v_mad_u64_u32 v[88:89], s[36:37], v87, s31, v[6:7]
	v_mad_u64_u32 v[90:91], s[36:37], v85, s31, v[6:7]
	v_mad_u64_u32 v[92:93], s[36:37], v92, s31, v[6:7]
	v_mad_u64_u32 v[94:95], s[36:37], v94, s31, v[6:7]
	v_mad_u64_u32 v[96:97], s[36:37], v96, s31, v[6:7]
	v_mad_u64_u32 v[98:99], s[36:37], v98, s31, v[6:7]
	v_mad_u64_u32 v[100:101], s[36:37], v100, s31, v[6:7]
	v_mad_u64_u32 v[102:103], s[36:37], v102, s31, v[6:7]
	v_mad_u64_u32 v[104:105], s[36:37], v104, s31, v[6:7]
	v_mad_u64_u32 v[106:107], s[36:37], v106, s31, v[6:7]
	v_mad_u64_u32 v[108:109], s[36:37], v108, s31, v[6:7]
	v_mad_u64_u32 v[110:111], s[36:37], v110, s31, v[6:7]
	v_mad_u64_u32 v[112:113], s[36:37], v112, s31, v[6:7]
	v_mad_u64_u32 v[114:115], s[36:37], v114, s31, v[6:7]
	s_waitcnt vmcnt(31)
	ds_write_b32 v22, v11
	s_waitcnt vmcnt(30)
	ds_write_b32 v24, v14
	s_waitcnt vmcnt(29)
	ds_write_b32 v26, v21
	s_waitcnt vmcnt(28)
	ds_write_b32 v28, v54
	s_waitcnt vmcnt(27)
	ds_write_b32 v30, v55
	s_waitcnt vmcnt(26)
	ds_write_b32 v32, v56
	s_waitcnt vmcnt(25)
	ds_write_b32 v34, v57
	s_waitcnt vmcnt(24)
	ds_write_b32 v36, v58
	s_waitcnt vmcnt(23)
	ds_write_b32 v38, v59
	s_waitcnt vmcnt(22)
	ds_write_b32 v40, v60
	s_waitcnt vmcnt(21)
	ds_write_b32 v42, v61
	s_waitcnt vmcnt(20)
	ds_write_b32 v44, v62
	s_waitcnt vmcnt(19)
	ds_write_b32 v46, v63
	s_waitcnt vmcnt(18)
	ds_write_b32 v48, v64
	s_waitcnt vmcnt(17)
	ds_write_b32 v50, v65
	s_waitcnt vmcnt(16)
	ds_write_b32 v52, v66
	s_waitcnt vmcnt(15)
	ds_write_b32 v84, v116
	s_waitcnt vmcnt(14)
	ds_write_b32 v86, v117
	s_waitcnt vmcnt(13)
	ds_write_b32 v88, v130
	s_waitcnt vmcnt(12)
	ds_write_b32 v90, v152
	s_waitcnt vmcnt(11)
	ds_write_b32 v92, v153
	s_waitcnt vmcnt(10)
	ds_write_b32 v94, v154
	s_waitcnt vmcnt(9)
	ds_write_b32 v96, v155
	s_waitcnt vmcnt(8)
	ds_write_b32 v98, v156
	s_waitcnt vmcnt(7)
	ds_write_b32 v100, v157
	s_waitcnt vmcnt(6)
	ds_write_b32 v102, v158
	s_waitcnt vmcnt(5)
	ds_write_b32 v104, v159
	s_waitcnt vmcnt(4)
	ds_write_b32 v106, v160
	s_waitcnt vmcnt(3)
	ds_write_b32 v108, v161
	s_waitcnt vmcnt(2)
	ds_write_b32 v110, v162
	s_waitcnt vmcnt(1)
	ds_write_b32 v112, v163
	s_waitcnt vmcnt(0)
	ds_write_b32 v114, v164
	v_mov_b32_e32 v14, v117
	v_mov_b32_e32 v21, v130
	v_mov_b32_e32 v44, v106
	v_mov_b32_e32 v45, v107
	v_mov_b32_e32 v46, v108
	v_mov_b32_e32 v47, v109
	v_mov_b32_e32 v48, v110
	v_mov_b32_e32 v49, v111
	v_mov_b32_e32 v50, v112
	v_mov_b32_e32 v51, v113
	v_mov_b32_e32 v52, v114
	v_mov_b32_e32 v53, v115
	v_mov_b32_e32 v54, v152
	v_mov_b32_e32 v55, v153
	v_mov_b32_e32 v56, v154
	v_mov_b32_e32 v57, v155
	v_mov_b32_e32 v58, v156
	v_mov_b32_e32 v59, v157
	v_mov_b32_e32 v60, v158
	v_mov_b32_e32 v61, v159
	s_waitcnt lgkmcnt(0)
	s_and_b32 s26, 0xffff, s26
	s_lshl_b32 s26, s26, 1
	ds_read2_b32 v[26:27], v16 offset0:33 offset1:41
	ds_read2_b32 v[28:29], v16 offset1:8
	ds_read2_b32 v[30:31], v16 offset0:66 offset1:74
	ds_read2_b32 v[32:33], v16 offset0:99 offset1:107
	ds_read2_b32 v[34:35], v16 offset0:132 offset1:140
	ds_read2_b32 v[36:37], v16 offset0:165 offset1:173
	ds_read2_b32 v[38:39], v16 offset0:198 offset1:206
	ds_read2_b32 v[40:41], v16 offset0:231 offset1:239
	s_add_u32 s24, s24, s26
	s_addc_u32 s25, s25, 0
	v_mov_b32_e32 v11, v9
	v_lshl_add_u64 v[12:13], s[24:25], 0, v[10:11]
	v_or_b32_e32 v3, s8, v7
	v_lshl_add_u64 v[12:13], v[12:13], 0, s[20:21]
	v_lshlrev_b32_e32 v8, 11, v3
	s_waitcnt lgkmcnt(6)
	v_cvt_pk_bf16_f32 v22, v28, v26
	s_waitcnt lgkmcnt(4)
	v_cvt_pk_bf16_f32 v23, v30, v32
	s_waitcnt lgkmcnt(2)
	v_cvt_pk_bf16_f32 v24, v34, v36
	s_waitcnt lgkmcnt(0)
	v_cvt_pk_bf16_f32 v25, v38, v40
	v_lshl_add_u64 v[42:43], v[12:13], 0, v[8:9]
	global_store_dwordx4 v[42:43], v[22:25], off
	v_or_b32_e32 v3, s8, v17
	v_lshlrev_b32_e32 v8, 11, v3
	v_cvt_pk_bf16_f32 v22, v29, v27
	v_cvt_pk_bf16_f32 v23, v31, v33
	v_cvt_pk_bf16_f32 v24, v35, v37
	v_cvt_pk_bf16_f32 v25, v39, v41
	ds_read2_b32 v[28:29], v16 offset0:49 offset1:57
	ds_read2_b32 v[30:31], v16 offset0:16 offset1:24
	ds_read2_b32 v[32:33], v16 offset0:82 offset1:90
	ds_read2_b32 v[34:35], v16 offset0:115 offset1:123
	ds_read2_b32 v[36:37], v16 offset0:148 offset1:156
	ds_read2_b32 v[38:39], v16 offset0:181 offset1:189
	ds_read2_b32 v[40:41], v16 offset0:214 offset1:222
	ds_read2_b32 v[42:43], v16 offset0:247 offset1:255
	v_or_b32_e32 v3, s8, v18
	v_lshl_add_u64 v[26:27], v[12:13], 0, v[8:9]
	v_lshlrev_b32_e32 v8, 11, v3
	v_or_b32_e32 v3, s8, v19
	global_store_dwordx4 v[26:27], v[22:25], off
	v_lshl_add_u64 v[26:27], v[12:13], 0, v[8:9]
	v_lshlrev_b32_e32 v8, 11, v3
	s_waitcnt lgkmcnt(6)
	v_cvt_pk_bf16_f32 v22, v30, v28
	s_waitcnt lgkmcnt(4)
	v_cvt_pk_bf16_f32 v23, v32, v34
	s_waitcnt lgkmcnt(2)
	v_cvt_pk_bf16_f32 v24, v36, v38
	s_waitcnt lgkmcnt(0)
	v_cvt_pk_bf16_f32 v25, v40, v42
	global_store_dwordx4 v[26:27], v[22:25], off
	v_lshl_add_u64 v[12:13], v[12:13], 0, v[8:9]
	s_nop 0
	v_cvt_pk_bf16_f32 v22, v31, v29
	v_cvt_pk_bf16_f32 v23, v33, v35
	v_cvt_pk_bf16_f32 v24, v37, v39
	v_cvt_pk_bf16_f32 v25, v41, v43
	global_store_dwordx4 v[12:13], v[22:25], off
	s_waitcnt lgkmcnt(0)

.LBB0_111:
	s_lshl_b32 s9, s5, 1
	s_lshl_b32 s10, s6, 1
	v_or_b32_e32 v20, s10, v0
	s_add_i32 s11, s9, 4
	s_add_i32 s12, s10, 4
	s_add_i32 s13, s9, 8
	s_add_i32 s14, s10, 8
	s_add_i32 s15, s9, 12
	s_add_i32 s20, s10, 12
	s_add_i32 s21, s9, 16
	s_add_i32 s22, s10, 16
	s_add_i32 s23, s9, 20
	s_add_i32 s24, s10, 20
	s_add_i32 s25, s9, 24
	s_add_i32 s26, s10, 24
	s_add_i32 s27, s9, 28
	s_add_i32 s28, s10, 28
	v_or_b32_e32 v18, s9, v5
	v_ashrrev_i32_e32 v21, 31, v20
	v_or_b32_e32 v22, s11, v5
	v_or_b32_e32 v24, s12, v0
	v_or_b32_e32 v26, s13, v5
	v_or_b32_e32 v28, s14, v0
	v_or_b32_e32 v30, s15, v5
	v_or_b32_e32 v32, s20, v0
	v_or_b32_e32 v34, s21, v5
	v_or_b32_e32 v36, s22, v0
	v_or_b32_e32 v38, s23, v5
	v_or_b32_e32 v40, s24, v0
	v_or_b32_e32 v42, s25, v5
	v_or_b32_e32 v44, s26, v0
	v_or_b32_e32 v46, s27, v5
	v_or_b32_e32 v48, s28, v0
	v_ashrrev_i32_e32 v19, 31, v18
	v_lshlrev_b64 v[20:21], 12, v[20:21]
	v_ashrrev_i32_e32 v25, 31, v24
	v_ashrrev_i32_e32 v23, 31, v22
	v_ashrrev_i32_e32 v29, 31, v28
	v_ashrrev_i32_e32 v27, 31, v26
	v_ashrrev_i32_e32 v33, 31, v32
	v_ashrrev_i32_e32 v31, 31, v30
	v_ashrrev_i32_e32 v37, 31, v36
	v_ashrrev_i32_e32 v35, 31, v34
	v_ashrrev_i32_e32 v41, 31, v40
	v_ashrrev_i32_e32 v39, 31, v38
	v_ashrrev_i32_e32 v45, 31, v44
	v_ashrrev_i32_e32 v43, 31, v42
	v_ashrrev_i32_e32 v49, 31, v48
	v_ashrrev_i32_e32 v47, 31, v46
	v_lshlrev_b64 v[18:19], 12, v[18:19]
	v_lshl_add_u64 v[20:21], v[8:9], 0, v[20:21]
	v_lshlrev_b64 v[22:23], 12, v[22:23]
	v_lshlrev_b64 v[24:25], 12, v[24:25]
	v_lshlrev_b64 v[26:27], 12, v[26:27]
	v_lshlrev_b64 v[28:29], 12, v[28:29]
	v_lshlrev_b64 v[30:31], 12, v[30:31]
	v_lshlrev_b64 v[32:33], 12, v[32:33]
	v_lshlrev_b64 v[34:35], 12, v[34:35]
	v_lshlrev_b64 v[36:37], 12, v[36:37]
	v_lshlrev_b64 v[38:39], 12, v[38:39]
	v_lshlrev_b64 v[40:41], 12, v[40:41]
	v_lshlrev_b64 v[42:43], 12, v[42:43]
	v_lshlrev_b64 v[44:45], 12, v[44:45]
	v_lshlrev_b64 v[46:47], 12, v[46:47]
	v_lshlrev_b64 v[48:49], 12, v[48:49]
	v_lshl_add_u64 v[18:19], v[8:9], 0, v[18:19]
	v_lshl_add_u64 v[24:25], v[8:9], 0, v[24:25]
	v_lshl_add_u64 v[22:23], v[8:9], 0, v[22:23]
	v_lshl_add_u64 v[28:29], v[8:9], 0, v[28:29]
	v_lshl_add_u64 v[26:27], v[8:9], 0, v[26:27]
	v_lshl_add_u64 v[32:33], v[8:9], 0, v[32:33]
	v_lshl_add_u64 v[30:31], v[8:9], 0, v[30:31]
	v_lshl_add_u64 v[36:37], v[8:9], 0, v[36:37]
	v_lshl_add_u64 v[34:35], v[8:9], 0, v[34:35]
	v_lshl_add_u64 v[40:41], v[8:9], 0, v[40:41]
	v_lshl_add_u64 v[38:39], v[8:9], 0, v[38:39]
	v_lshl_add_u64 v[44:45], v[8:9], 0, v[44:45]
	v_lshl_add_u64 v[42:43], v[8:9], 0, v[42:43]
	v_lshl_add_u64 v[48:49], v[8:9], 0, v[48:49]
	v_lshl_add_u64 v[46:47], v[8:9], 0, v[46:47]
	global_load_dword v10, v[20:21], off
	global_load_dword v17, v[18:19], off
	global_load_dword v50, v[24:25], off
	global_load_dword v51, v[22:23], off
	global_load_dword v52, v[28:29], off
	global_load_dword v53, v[26:27], off
	global_load_dword v54, v[32:33], off
	global_load_dword v55, v[30:31], off
	global_load_dword v56, v[36:37], off
	global_load_dword v57, v[34:35], off
	global_load_dword v58, v[40:41], off
	global_load_dword v59, v[38:39], off
	global_load_dword v60, v[44:45], off
	global_load_dword v61, v[42:43], off
	global_load_dword v62, v[48:49], off
	global_load_dword v63, v[46:47], off
	v_or_b32_e32 v20, s9, v3
	v_or_b32_e32 v18, s10, v2
	s_add_i32 s6, s6, 16
	s_add_i32 s5, s5, 16
	s_add_i32 s7, s7, -16
	v_mad_u64_u32 v[18:19], s[18:19], v18, s75, v[4:5]
	v_mad_u64_u32 v[20:21], s[18:19], v20, s75, v[4:5]
	v_or_b32_e32 v19, s11, v3
	v_or_b32_e32 v21, s12, v2
	v_or_b32_e32 v28, s13, v3
	v_or_b32_e32 v26, s14, v2
	v_or_b32_e32 v32, s15, v3
	v_or_b32_e32 v30, s20, v2
	v_or_b32_e32 v36, s21, v3
	v_or_b32_e32 v34, s22, v2
	v_or_b32_e32 v40, s23, v3
	v_or_b32_e32 v38, s24, v2
	v_or_b32_e32 v44, s25, v3
	v_or_b32_e32 v42, s26, v2
	v_or_b32_e32 v48, s27, v3
	v_or_b32_e32 v46, s28, v2
	s_cmp_lg_u32 s7, 0
	v_mad_u64_u32 v[22:23], s[10:11], v21, s75, v[4:5]
	v_mad_u64_u32 v[24:25], s[10:11], v19, s75, v[4:5]
	v_mad_u64_u32 v[26:27], s[10:11], v26, s75, v[4:5]
	v_mad_u64_u32 v[28:29], s[10:11], v28, s75, v[4:5]
	v_mad_u64_u32 v[30:31], s[10:11], v30, s75, v[4:5]
	v_mad_u64_u32 v[32:33], s[10:11], v32, s75, v[4:5]
	v_mad_u64_u32 v[34:35], s[10:11], v34, s75, v[4:5]
	v_mad_u64_u32 v[36:37], s[10:11], v36, s75, v[4:5]
	v_mad_u64_u32 v[38:39], s[10:11], v38, s75, v[4:5]
	v_mad_u64_u32 v[40:41], s[10:11], v40, s75, v[4:5]
	v_mad_u64_u32 v[42:43], s[10:11], v42, s75, v[4:5]
	v_mad_u64_u32 v[44:45], s[10:11], v44, s75, v[4:5]
	v_mad_u64_u32 v[46:47], s[10:11], v46, s75, v[4:5]
	v_mad_u64_u32 v[48:49], s[10:11], v48, s75, v[4:5]
	s_lshl_b32 s9, s5, 1
	s_lshl_b32 s10, s6, 1
	v_or_b32_e32 v102, s10, v0
	s_add_i32 s11, s9, 4
	s_add_i32 s12, s10, 4
	s_add_i32 s13, s9, 8
	s_add_i32 s14, s10, 8
	s_add_i32 s15, s9, 12
	s_add_i32 s20, s10, 12
	s_add_i32 s21, s9, 16
	s_add_i32 s22, s10, 16
	s_add_i32 s23, s9, 20
	s_add_i32 s24, s10, 20
	s_add_i32 s25, s9, 24
	s_add_i32 s26, s10, 24
	s_add_i32 s27, s9, 28
	s_add_i32 s28, s10, 28
	v_or_b32_e32 v100, s9, v5
	v_ashrrev_i32_e32 v103, 31, v102
	v_or_b32_e32 v104, s11, v5
	v_or_b32_e32 v106, s12, v0
	v_or_b32_e32 v108, s13, v5
	v_or_b32_e32 v110, s14, v0
	v_or_b32_e32 v112, s15, v5
	v_or_b32_e32 v114, s20, v0
	v_or_b32_e32 v116, s21, v5
	v_or_b32_e32 v152, s22, v0
	v_or_b32_e32 v154, s23, v5
	v_or_b32_e32 v156, s24, v0
	v_or_b32_e32 v158, s25, v5
	v_or_b32_e32 v160, s26, v0
	v_or_b32_e32 v162, s27, v5
	v_or_b32_e32 v164, s28, v0
	v_ashrrev_i32_e32 v101, 31, v100
	v_lshlrev_b64 v[102:103], 12, v[102:103]
	v_ashrrev_i32_e32 v107, 31, v106
	v_ashrrev_i32_e32 v105, 31, v104
	v_ashrrev_i32_e32 v111, 31, v110
	v_ashrrev_i32_e32 v109, 31, v108
	v_ashrrev_i32_e32 v115, 31, v114
	v_ashrrev_i32_e32 v113, 31, v112
	v_ashrrev_i32_e32 v153, 31, v152
	v_ashrrev_i32_e32 v117, 31, v116
	v_ashrrev_i32_e32 v157, 31, v156
	v_ashrrev_i32_e32 v155, 31, v154
	v_ashrrev_i32_e32 v161, 31, v160
	v_ashrrev_i32_e32 v159, 31, v158
	v_ashrrev_i32_e32 v165, 31, v164
	v_ashrrev_i32_e32 v163, 31, v162
	v_lshlrev_b64 v[100:101], 12, v[100:101]
	v_lshl_add_u64 v[102:103], v[8:9], 0, v[102:103]
	v_lshlrev_b64 v[104:105], 12, v[104:105]
	v_lshlrev_b64 v[106:107], 12, v[106:107]
	v_lshlrev_b64 v[108:109], 12, v[108:109]
	v_lshlrev_b64 v[110:111], 12, v[110:111]
	v_lshlrev_b64 v[112:113], 12, v[112:113]
	v_lshlrev_b64 v[114:115], 12, v[114:115]
	v_lshlrev_b64 v[116:117], 12, v[116:117]
	v_lshlrev_b64 v[152:153], 12, v[152:153]
	v_lshlrev_b64 v[154:155], 12, v[154:155]
	v_lshlrev_b64 v[156:157], 12, v[156:157]
	v_lshlrev_b64 v[158:159], 12, v[158:159]
	v_lshlrev_b64 v[160:161], 12, v[160:161]
	v_lshlrev_b64 v[162:163], 12, v[162:163]
	v_lshlrev_b64 v[164:165], 12, v[164:165]
	v_lshl_add_u64 v[100:101], v[8:9], 0, v[100:101]
	v_lshl_add_u64 v[106:107], v[8:9], 0, v[106:107]
	v_lshl_add_u64 v[104:105], v[8:9], 0, v[104:105]
	v_lshl_add_u64 v[110:111], v[8:9], 0, v[110:111]
	v_lshl_add_u64 v[108:109], v[8:9], 0, v[108:109]
	v_lshl_add_u64 v[114:115], v[8:9], 0, v[114:115]
	v_lshl_add_u64 v[112:113], v[8:9], 0, v[112:113]
	v_lshl_add_u64 v[152:153], v[8:9], 0, v[152:153]
	v_lshl_add_u64 v[116:117], v[8:9], 0, v[116:117]
	v_lshl_add_u64 v[156:157], v[8:9], 0, v[156:157]
	v_lshl_add_u64 v[154:155], v[8:9], 0, v[154:155]
	v_lshl_add_u64 v[160:161], v[8:9], 0, v[160:161]
	v_lshl_add_u64 v[158:159], v[8:9], 0, v[158:159]
	v_lshl_add_u64 v[164:165], v[8:9], 0, v[164:165]
	v_lshl_add_u64 v[162:163], v[8:9], 0, v[162:163]
	global_load_dword v99, v[102:103], off
	global_load_dword v130, v[100:101], off
	global_load_dword v166, v[106:107], off
	global_load_dword v167, v[104:105], off
	global_load_dword v168, v[110:111], off
	global_load_dword v169, v[108:109], off
	global_load_dword v170, v[114:115], off
	global_load_dword v171, v[112:113], off
	global_load_dword v172, v[152:153], off
	global_load_dword v173, v[116:117], off
	global_load_dword v174, v[156:157], off
	global_load_dword v175, v[154:155], off
	global_load_dword v176, v[160:161], off
	global_load_dword v177, v[158:159], off
	global_load_dword v178, v[164:165], off
	global_load_dword v179, v[162:163], off
	v_or_b32_e32 v102, s9, v3
	v_or_b32_e32 v100, s10, v2
	s_add_i32 s6, s6, 16
	s_add_i32 s5, s5, 16
	s_add_i32 s7, s7, -16
	v_mad_u64_u32 v[100:101], s[18:19], v100, s75, v[4:5]
	v_mad_u64_u32 v[102:103], s[18:19], v102, s75, v[4:5]
	v_or_b32_e32 v101, s11, v3
	v_or_b32_e32 v103, s12, v2
	v_or_b32_e32 v110, s13, v3
	v_or_b32_e32 v108, s14, v2
	v_or_b32_e32 v114, s15, v3
	v_or_b32_e32 v112, s20, v2
	v_or_b32_e32 v152, s21, v3
	v_or_b32_e32 v116, s22, v2
	v_or_b32_e32 v156, s23, v3
	v_or_b32_e32 v154, s24, v2
	v_or_b32_e32 v160, s25, v3
	v_or_b32_e32 v158, s26, v2
	v_or_b32_e32 v164, s27, v3
	v_or_b32_e32 v162, s28, v2
	s_cmp_lg_u32 s7, 0
	v_mad_u64_u32 v[104:105], s[10:11], v103, s75, v[4:5]
	v_mad_u64_u32 v[106:107], s[10:11], v101, s75, v[4:5]
	v_mad_u64_u32 v[108:109], s[10:11], v108, s75, v[4:5]
	v_mad_u64_u32 v[110:111], s[10:11], v110, s75, v[4:5]
	v_mad_u64_u32 v[112:113], s[10:11], v112, s75, v[4:5]
	v_mad_u64_u32 v[114:115], s[10:11], v114, s75, v[4:5]
	v_mad_u64_u32 v[116:117], s[10:11], v116, s75, v[4:5]
	v_mad_u64_u32 v[152:153], s[10:11], v152, s75, v[4:5]
	v_mad_u64_u32 v[154:155], s[10:11], v154, s75, v[4:5]
	v_mad_u64_u32 v[156:157], s[10:11], v156, s75, v[4:5]
	v_mad_u64_u32 v[158:159], s[10:11], v158, s75, v[4:5]
	v_mad_u64_u32 v[160:161], s[10:11], v160, s75, v[4:5]
	v_mad_u64_u32 v[162:163], s[10:11], v162, s75, v[4:5]
	v_mad_u64_u32 v[164:165], s[10:11], v164, s75, v[4:5]
	s_waitcnt vmcnt(31)
	ds_write_b32 v18, v10
	s_waitcnt vmcnt(30)
	ds_write_b32 v20, v17
	s_waitcnt vmcnt(29)
	ds_write_b32 v22, v50
	s_waitcnt vmcnt(28)
	ds_write_b32 v24, v51
	s_waitcnt vmcnt(27)
	ds_write_b32 v26, v52
	s_waitcnt vmcnt(26)
	ds_write_b32 v28, v53
	s_waitcnt vmcnt(25)
	ds_write_b32 v30, v54
	s_waitcnt vmcnt(24)
	ds_write_b32 v32, v55
	s_waitcnt vmcnt(23)
	ds_write_b32 v34, v56
	s_waitcnt vmcnt(22)
	ds_write_b32 v36, v57
	s_waitcnt vmcnt(21)
	ds_write_b32 v38, v58
	s_waitcnt vmcnt(20)
	ds_write_b32 v40, v59
	s_waitcnt vmcnt(19)
	ds_write_b32 v42, v60
	s_waitcnt vmcnt(18)
	ds_write_b32 v44, v61
	s_waitcnt vmcnt(17)
	ds_write_b32 v46, v62
	s_waitcnt vmcnt(16)
	ds_write_b32 v48, v63
	s_waitcnt vmcnt(15)
	ds_write_b32 v100, v99
	s_waitcnt vmcnt(14)
	ds_write_b32 v102, v130
	s_waitcnt vmcnt(13)
	ds_write_b32 v104, v166
	s_waitcnt vmcnt(12)
	ds_write_b32 v106, v167
	s_waitcnt vmcnt(11)
	ds_write_b32 v108, v168
	s_waitcnt vmcnt(10)
	ds_write_b32 v110, v169
	s_waitcnt vmcnt(9)
	ds_write_b32 v112, v170
	s_waitcnt vmcnt(8)
	ds_write_b32 v114, v171
	s_waitcnt vmcnt(7)
	ds_write_b32 v116, v172
	s_waitcnt vmcnt(6)
	ds_write_b32 v152, v173
	s_waitcnt vmcnt(5)
	ds_write_b32 v154, v174
	s_waitcnt vmcnt(4)
	ds_write_b32 v156, v175
	s_waitcnt vmcnt(3)
	ds_write_b32 v158, v176
	s_waitcnt vmcnt(2)
	ds_write_b32 v160, v177
	s_waitcnt vmcnt(1)
	ds_write_b32 v162, v178
	s_waitcnt vmcnt(0)
	ds_write_b32 v164, v179
	v_mov_b32_e32 v10, v99
	v_mov_b32_e32 v17, v130
	v_mov_b32_e32 v40, v156
	v_mov_b32_e32 v41, v157
	v_mov_b32_e32 v42, v158
	v_mov_b32_e32 v43, v159
	v_mov_b32_e32 v44, v160
	v_mov_b32_e32 v45, v161
	v_mov_b32_e32 v46, v162
	v_mov_b32_e32 v47, v163
	v_mov_b32_e32 v48, v164
	v_mov_b32_e32 v49, v165
	v_mov_b32_e32 v50, v166
	v_mov_b32_e32 v51, v167
	v_mov_b32_e32 v52, v168
	v_mov_b32_e32 v53, v169
	v_mov_b32_e32 v54, v170
	v_mov_b32_e32 v55, v171
	v_mov_b32_e32 v56, v172
	v_mov_b32_e32 v57, v173
	v_mov_b32_e32 v58, v174
	v_mov_b32_e32 v59, v175
	v_mov_b32_e32 v60, v176
	v_mov_b32_e32 v61, v177
	s_lshl_b64 s[6:7], s[46:47], 1
	s_waitcnt lgkmcnt(0)
	s_add_u32 s2, s2, s6
	s_addc_u32 s3, s3, s7
	v_lshlrev_b32_e32 v0, 1, v6
	ds_read2_b32 v[22:23], v12 offset0:33 offset1:41
	ds_read2_b32 v[24:25], v12 offset1:8
	ds_read2_b32 v[26:27], v12 offset0:66 offset1:74
	ds_read2_b32 v[28:29], v12 offset0:99 offset1:107
	ds_read2_b32 v[30:31], v12 offset0:132 offset1:140
	ds_read2_b32 v[32:33], v12 offset0:165 offset1:173
	ds_read2_b32 v[34:35], v12 offset0:198 offset1:206
	ds_read2_b32 v[36:37], v12 offset0:231 offset1:239
	v_lshl_add_u64 v[8:9], s[2:3], 0, v[0:1]
	v_or_b32_e32 v0, s4, v11
	s_mov_b64 s[2:3], 0x1e00000
	v_mul_u32_u24_e32 v0, 0xb00, v0
	v_lshl_add_u64 v[8:9], v[8:9], 0, s[2:3]
	v_lshlrev_b32_e32 v0, 1, v0
	v_lshl_add_u64 v[38:39], v[8:9], 0, v[0:1]
	v_or_b32_e32 v0, s4, v13
	s_waitcnt lgkmcnt(6)
	v_cvt_pk_bf16_f32 v18, v24, v22
	s_waitcnt lgkmcnt(4)
	v_cvt_pk_bf16_f32 v19, v26, v28
	s_waitcnt lgkmcnt(2)
	v_cvt_pk_bf16_f32 v20, v30, v32
	s_waitcnt lgkmcnt(0)
	v_cvt_pk_bf16_f32 v21, v34, v36
	v_mul_u32_u24_e32 v0, 0xb00, v0
	global_store_dwordx4 v[38:39], v[18:21], off
	v_lshlrev_b32_e32 v0, 1, v0
	v_readlane_b32 s20, v253, 3
	v_cvt_pk_bf16_f32 v18, v25, v23
	v_cvt_pk_bf16_f32 v19, v27, v29
	v_cvt_pk_bf16_f32 v20, v31, v33
	v_cvt_pk_bf16_f32 v21, v35, v37
	v_lshl_add_u64 v[22:23], v[8:9], 0, v[0:1]
	ds_read2_b32 v[24:25], v12 offset0:16 offset1:24
	ds_read2_b32 v[26:27], v12 offset0:49 offset1:57
	ds_read2_b32 v[28:29], v12 offset0:82 offset1:90
	ds_read2_b32 v[30:31], v12 offset0:115 offset1:123
	ds_read2_b32 v[32:33], v12 offset0:148 offset1:156
	ds_read2_b32 v[34:35], v12 offset0:181 offset1:189
	ds_read2_b32 v[36:37], v12 offset0:214 offset1:222
	ds_read2_b32 v[38:39], v12 offset0:247 offset1:255
	v_or_b32_e32 v0, s4, v14
	v_mul_u32_u24_e32 v0, 0xb00, v0
	v_lshlrev_b32_e32 v0, 1, v0
	global_store_dwordx4 v[22:23], v[18:21], off
	v_lshl_add_u64 v[22:23], v[8:9], 0, v[0:1]
	v_or_b32_e32 v0, s4, v15
	v_mul_u32_u24_e32 v0, 0xb00, v0
	s_waitcnt lgkmcnt(6)
	v_cvt_pk_bf16_f32 v18, v24, v26
	s_waitcnt lgkmcnt(4)
	v_cvt_pk_bf16_f32 v19, v28, v30
	s_waitcnt lgkmcnt(2)
	v_cvt_pk_bf16_f32 v20, v32, v34
	s_waitcnt lgkmcnt(0)
	v_cvt_pk_bf16_f32 v21, v36, v38
	v_lshlrev_b32_e32 v0, 1, v0
	global_store_dwordx4 v[22:23], v[18:21], off
	v_lshl_add_u64 v[8:9], v[8:9], 0, v[0:1]
	s_mov_b64 s[2:3], 0
	v_cvt_pk_bf16_f32 v18, v25, v27
	v_cvt_pk_bf16_f32 v19, v29, v31
	v_cvt_pk_bf16_f32 v20, v33, v35
	v_cvt_pk_bf16_f32 v21, v37, v39
	global_store_dwordx4 v[8:9], v[18:21], off
	s_waitcnt lgkmcnt(0)
	v_readlane_b32 s21, v253, 4

.LBB0_115:
	s_lshl_b32 s12, s6, 1
	s_lshl_b32 s13, s7, 1
	v_or_b32_e32 v10, s12, v5
	v_or_b32_e32 v17, s13, v0
	s_add_i32 s14, s12, 4
	s_add_i32 s15, s13, 4
	s_add_i32 s18, s12, 8
	s_add_i32 s19, s13, 8
	s_add_i32 s20, s12, 12
	s_add_i32 s21, s13, 12
	s_add_i32 s22, s12, 16
	s_add_i32 s23, s13, 16
	s_add_i32 s24, s12, 20
	s_add_i32 s25, s13, 20
	s_add_i32 s26, s12, 24
	s_add_i32 s27, s13, 24
	s_add_i32 s28, s12, 28
	s_add_i32 s29, s13, 28
	v_mad_u64_u32 v[18:19], s[10:11], v17, s31, v[8:9]
	v_mad_u64_u32 v[20:21], s[10:11], v10, s31, v[8:9]
	v_or_b32_e32 v10, s14, v5
	v_or_b32_e32 v17, s15, v0
	v_or_b32_e32 v28, s18, v5
	v_or_b32_e32 v26, s19, v0
	v_or_b32_e32 v32, s20, v5
	v_or_b32_e32 v30, s21, v0
	v_or_b32_e32 v36, s22, v5
	v_or_b32_e32 v34, s23, v0
	v_or_b32_e32 v40, s24, v5
	v_or_b32_e32 v38, s25, v0
	v_or_b32_e32 v44, s26, v5
	v_or_b32_e32 v42, s27, v0
	v_or_b32_e32 v48, s28, v5
	v_or_b32_e32 v46, s29, v0
	v_mad_u64_u32 v[22:23], s[10:11], v17, s31, v[8:9]
	v_mad_u64_u32 v[24:25], s[10:11], v10, s31, v[8:9]
	v_mad_u64_u32 v[26:27], s[10:11], v26, s31, v[8:9]
	v_mad_u64_u32 v[28:29], s[10:11], v28, s31, v[8:9]
	v_mad_u64_u32 v[30:31], s[10:11], v30, s31, v[8:9]
	v_mad_u64_u32 v[32:33], s[10:11], v32, s31, v[8:9]
	v_mad_u64_u32 v[34:35], s[10:11], v34, s31, v[8:9]
	v_mad_u64_u32 v[36:37], s[10:11], v36, s31, v[8:9]
	v_mad_u64_u32 v[38:39], s[10:11], v38, s31, v[8:9]
	v_mad_u64_u32 v[40:41], s[10:11], v40, s31, v[8:9]
	v_mad_u64_u32 v[42:43], s[10:11], v42, s31, v[8:9]
	v_mad_u64_u32 v[44:45], s[10:11], v44, s31, v[8:9]
	v_mad_u64_u32 v[46:47], s[10:11], v46, s31, v[8:9]
	v_mad_u64_u32 v[48:49], s[10:11], v48, s31, v[8:9]
	global_load_dword v10, v[18:19], off
	global_load_dword v17, v[20:21], off
	global_load_dword v50, v[22:23], off
	global_load_dword v51, v[24:25], off
	global_load_dword v52, v[26:27], off
	global_load_dword v53, v[28:29], off
	global_load_dword v54, v[30:31], off
	global_load_dword v55, v[32:33], off
	global_load_dword v56, v[34:35], off
	global_load_dword v57, v[36:37], off
	global_load_dword v58, v[38:39], off
	global_load_dword v59, v[40:41], off
	global_load_dword v60, v[42:43], off
	global_load_dword v61, v[44:45], off
	global_load_dword v62, v[46:47], off
	global_load_dword v63, v[48:49], off
	v_or_b32_e32 v20, s12, v3
	v_or_b32_e32 v18, s13, v2
	s_add_i32 s7, s7, 16
	s_add_i32 s6, s6, 16
	s_add_i32 s9, s9, -16
	v_mad_u64_u32 v[18:19], s[10:11], v18, s75, v[4:5]
	v_mad_u64_u32 v[20:21], s[10:11], v20, s75, v[4:5]
	v_or_b32_e32 v19, s14, v3
	v_or_b32_e32 v21, s15, v2
	v_or_b32_e32 v28, s18, v3
	v_or_b32_e32 v26, s19, v2
	v_or_b32_e32 v32, s20, v3
	v_or_b32_e32 v30, s21, v2
	v_or_b32_e32 v36, s22, v3
	v_or_b32_e32 v34, s23, v2
	v_or_b32_e32 v40, s24, v3
	v_or_b32_e32 v38, s25, v2
	v_or_b32_e32 v44, s26, v3
	v_or_b32_e32 v42, s27, v2
	v_or_b32_e32 v48, s28, v3
	v_or_b32_e32 v46, s29, v2
	s_cmp_lg_u32 s9, 0
	v_mad_u64_u32 v[22:23], s[10:11], v21, s75, v[4:5]
	v_mad_u64_u32 v[24:25], s[10:11], v19, s75, v[4:5]
	v_mad_u64_u32 v[26:27], s[10:11], v26, s75, v[4:5]
	v_mad_u64_u32 v[28:29], s[10:11], v28, s75, v[4:5]
	v_mad_u64_u32 v[30:31], s[10:11], v30, s75, v[4:5]
	v_mad_u64_u32 v[32:33], s[10:11], v32, s75, v[4:5]
	v_mad_u64_u32 v[34:35], s[10:11], v34, s75, v[4:5]
	v_mad_u64_u32 v[36:37], s[10:11], v36, s75, v[4:5]
	v_mad_u64_u32 v[38:39], s[10:11], v38, s75, v[4:5]
	v_mad_u64_u32 v[40:41], s[10:11], v40, s75, v[4:5]
	v_mad_u64_u32 v[42:43], s[10:11], v42, s75, v[4:5]
	v_mad_u64_u32 v[44:45], s[10:11], v44, s75, v[4:5]
	v_mad_u64_u32 v[46:47], s[10:11], v46, s75, v[4:5]
	v_mad_u64_u32 v[48:49], s[10:11], v48, s75, v[4:5]
	s_lshl_b32 s12, s6, 1
	s_lshl_b32 s13, s7, 1
	v_or_b32_e32 v99, s12, v5
	v_or_b32_e32 v130, s13, v0
	s_add_i32 s14, s12, 4
	s_add_i32 s15, s13, 4
	s_add_i32 s18, s12, 8
	s_add_i32 s19, s13, 8
	s_add_i32 s20, s12, 12
	s_add_i32 s21, s13, 12
	s_add_i32 s22, s12, 16
	s_add_i32 s23, s13, 16
	s_add_i32 s24, s12, 20
	s_add_i32 s25, s13, 20
	s_add_i32 s26, s12, 24
	s_add_i32 s27, s13, 24
	s_add_i32 s28, s12, 28
	s_add_i32 s29, s13, 28
	v_mad_u64_u32 v[100:101], s[10:11], v130, s31, v[8:9]
	v_mad_u64_u32 v[102:103], s[10:11], v99, s31, v[8:9]
	v_or_b32_e32 v99, s14, v5
	v_or_b32_e32 v130, s15, v0
	v_or_b32_e32 v110, s18, v5
	v_or_b32_e32 v108, s19, v0
	v_or_b32_e32 v114, s20, v5
	v_or_b32_e32 v112, s21, v0
	v_or_b32_e32 v152, s22, v5
	v_or_b32_e32 v116, s23, v0
	v_or_b32_e32 v156, s24, v5
	v_or_b32_e32 v154, s25, v0
	v_or_b32_e32 v160, s26, v5
	v_or_b32_e32 v158, s27, v0
	v_or_b32_e32 v164, s28, v5
	v_or_b32_e32 v162, s29, v0
	v_mad_u64_u32 v[104:105], s[10:11], v130, s31, v[8:9]
	v_mad_u64_u32 v[106:107], s[10:11], v99, s31, v[8:9]
	v_mad_u64_u32 v[108:109], s[10:11], v108, s31, v[8:9]
	v_mad_u64_u32 v[110:111], s[10:11], v110, s31, v[8:9]
	v_mad_u64_u32 v[112:113], s[10:11], v112, s31, v[8:9]
	v_mad_u64_u32 v[114:115], s[10:11], v114, s31, v[8:9]
	v_mad_u64_u32 v[116:117], s[10:11], v116, s31, v[8:9]
	v_mad_u64_u32 v[152:153], s[10:11], v152, s31, v[8:9]
	v_mad_u64_u32 v[154:155], s[10:11], v154, s31, v[8:9]
	v_mad_u64_u32 v[156:157], s[10:11], v156, s31, v[8:9]
	v_mad_u64_u32 v[158:159], s[10:11], v158, s31, v[8:9]
	v_mad_u64_u32 v[160:161], s[10:11], v160, s31, v[8:9]
	v_mad_u64_u32 v[162:163], s[10:11], v162, s31, v[8:9]
	v_mad_u64_u32 v[164:165], s[10:11], v164, s31, v[8:9]
	global_load_dword v99, v[100:101], off
	global_load_dword v130, v[102:103], off
	global_load_dword v166, v[104:105], off
	global_load_dword v167, v[106:107], off
	global_load_dword v168, v[108:109], off
	global_load_dword v169, v[110:111], off
	global_load_dword v170, v[112:113], off
	global_load_dword v171, v[114:115], off
	global_load_dword v172, v[116:117], off
	global_load_dword v173, v[152:153], off
	global_load_dword v174, v[154:155], off
	global_load_dword v175, v[156:157], off
	global_load_dword v176, v[158:159], off
	global_load_dword v177, v[160:161], off
	global_load_dword v178, v[162:163], off
	global_load_dword v179, v[164:165], off
	v_or_b32_e32 v102, s12, v3
	v_or_b32_e32 v100, s13, v2
	s_add_i32 s7, s7, 16
	s_add_i32 s6, s6, 16
	s_add_i32 s9, s9, -16
	v_mad_u64_u32 v[100:101], s[10:11], v100, s75, v[4:5]
	v_mad_u64_u32 v[102:103], s[10:11], v102, s75, v[4:5]
	v_or_b32_e32 v101, s14, v3
	v_or_b32_e32 v103, s15, v2
	v_or_b32_e32 v110, s18, v3
	v_or_b32_e32 v108, s19, v2
	v_or_b32_e32 v114, s20, v3
	v_or_b32_e32 v112, s21, v2
	v_or_b32_e32 v152, s22, v3
	v_or_b32_e32 v116, s23, v2
	v_or_b32_e32 v156, s24, v3
	v_or_b32_e32 v154, s25, v2
	v_or_b32_e32 v160, s26, v3
	v_or_b32_e32 v158, s27, v2
	v_or_b32_e32 v164, s28, v3
	v_or_b32_e32 v162, s29, v2
	s_cmp_lg_u32 s9, 0
	v_mad_u64_u32 v[104:105], s[10:11], v103, s75, v[4:5]
	v_mad_u64_u32 v[106:107], s[10:11], v101, s75, v[4:5]
	v_mad_u64_u32 v[108:109], s[10:11], v108, s75, v[4:5]
	v_mad_u64_u32 v[110:111], s[10:11], v110, s75, v[4:5]
	v_mad_u64_u32 v[112:113], s[10:11], v112, s75, v[4:5]
	v_mad_u64_u32 v[114:115], s[10:11], v114, s75, v[4:5]
	v_mad_u64_u32 v[116:117], s[10:11], v116, s75, v[4:5]
	v_mad_u64_u32 v[152:153], s[10:11], v152, s75, v[4:5]
	v_mad_u64_u32 v[154:155], s[10:11], v154, s75, v[4:5]
	v_mad_u64_u32 v[156:157], s[10:11], v156, s75, v[4:5]
	v_mad_u64_u32 v[158:159], s[10:11], v158, s75, v[4:5]
	v_mad_u64_u32 v[160:161], s[10:11], v160, s75, v[4:5]
	v_mad_u64_u32 v[162:163], s[10:11], v162, s75, v[4:5]
	v_mad_u64_u32 v[164:165], s[10:11], v164, s75, v[4:5]
	s_waitcnt vmcnt(31)
	ds_write_b32 v18, v10
	s_waitcnt vmcnt(30)
	ds_write_b32 v20, v17
	s_waitcnt vmcnt(29)
	ds_write_b32 v22, v50
	s_waitcnt vmcnt(28)
	ds_write_b32 v24, v51
	s_waitcnt vmcnt(27)
	ds_write_b32 v26, v52
	s_waitcnt vmcnt(26)
	ds_write_b32 v28, v53
	s_waitcnt vmcnt(25)
	ds_write_b32 v30, v54
	s_waitcnt vmcnt(24)
	ds_write_b32 v32, v55
	s_waitcnt vmcnt(23)
	ds_write_b32 v34, v56
	s_waitcnt vmcnt(22)
	ds_write_b32 v36, v57
	s_waitcnt vmcnt(21)
	ds_write_b32 v38, v58
	s_waitcnt vmcnt(20)
	ds_write_b32 v40, v59
	s_waitcnt vmcnt(19)
	ds_write_b32 v42, v60
	s_waitcnt vmcnt(18)
	ds_write_b32 v44, v61
	s_waitcnt vmcnt(17)
	ds_write_b32 v46, v62
	s_waitcnt vmcnt(16)
	ds_write_b32 v48, v63
	s_waitcnt vmcnt(15)
	ds_write_b32 v100, v99
	s_waitcnt vmcnt(14)
	ds_write_b32 v102, v130
	s_waitcnt vmcnt(13)
	ds_write_b32 v104, v166
	s_waitcnt vmcnt(12)
	ds_write_b32 v106, v167
	s_waitcnt vmcnt(11)
	ds_write_b32 v108, v168
	s_waitcnt vmcnt(10)
	ds_write_b32 v110, v169
	s_waitcnt vmcnt(9)
	ds_write_b32 v112, v170
	s_waitcnt vmcnt(8)
	ds_write_b32 v114, v171
	s_waitcnt vmcnt(7)
	ds_write_b32 v116, v172
	s_waitcnt vmcnt(6)
	ds_write_b32 v152, v173
	s_waitcnt vmcnt(5)
	ds_write_b32 v154, v174
	s_waitcnt vmcnt(4)
	ds_write_b32 v156, v175
	s_waitcnt vmcnt(3)
	ds_write_b32 v158, v176
	s_waitcnt vmcnt(2)
	ds_write_b32 v160, v177
	s_waitcnt vmcnt(1)
	ds_write_b32 v162, v178
	s_waitcnt vmcnt(0)
	ds_write_b32 v164, v179
	v_mov_b32_e32 v10, v99
	v_mov_b32_e32 v17, v130
	v_mov_b32_e32 v40, v156
	v_mov_b32_e32 v41, v157
	v_mov_b32_e32 v42, v158
	v_mov_b32_e32 v43, v159
	v_mov_b32_e32 v44, v160
	v_mov_b32_e32 v45, v161
	v_mov_b32_e32 v46, v162
	v_mov_b32_e32 v47, v163
	v_mov_b32_e32 v48, v164
	v_mov_b32_e32 v49, v165
	v_mov_b32_e32 v50, v166
	v_mov_b32_e32 v51, v167
	v_mov_b32_e32 v52, v168
	v_mov_b32_e32 v53, v169
	v_mov_b32_e32 v54, v170
	v_mov_b32_e32 v55, v171
	v_mov_b32_e32 v56, v172
	v_mov_b32_e32 v57, v173
	v_mov_b32_e32 v58, v174
	v_mov_b32_e32 v59, v175
	v_mov_b32_e32 v60, v176
	v_mov_b32_e32 v61, v177
	s_waitcnt lgkmcnt(0)
	s_and_b32 s5, 0xffff, s5
	s_lshl_b32 s5, s5, 1
	ds_read2_b32 v[22:23], v12 offset0:33 offset1:41
	ds_read2_b32 v[24:25], v12 offset1:8
	ds_read2_b32 v[26:27], v12 offset0:66 offset1:74
	ds_read2_b32 v[28:29], v12 offset0:99 offset1:107
	ds_read2_b32 v[30:31], v12 offset0:132 offset1:140
	ds_read2_b32 v[32:33], v12 offset0:165 offset1:173
	ds_read2_b32 v[34:35], v12 offset0:198 offset1:206
	ds_read2_b32 v[36:37], v12 offset0:231 offset1:239
	s_add_u32 s2, s2, s5
	s_addc_u32 s3, s3, 0
	v_lshlrev_b32_e32 v0, 1, v6
	v_lshl_add_u64 v[8:9], s[2:3], 0, v[0:1]
	s_mov_b64 s[2:3], 0x1300000
	v_or_b32_e32 v0, s4, v11
	v_lshl_add_u64 v[8:9], v[8:9], 0, s[2:3]
	v_lshlrev_b32_e32 v0, 11, v0
	s_waitcnt lgkmcnt(6)
	v_cvt_pk_bf16_f32 v18, v24, v22
	s_waitcnt lgkmcnt(4)
	v_cvt_pk_bf16_f32 v19, v26, v28
	s_waitcnt lgkmcnt(2)
	v_cvt_pk_bf16_f32 v20, v30, v32
	s_waitcnt lgkmcnt(0)
	v_cvt_pk_bf16_f32 v21, v34, v36
	v_lshl_add_u64 v[38:39], v[8:9], 0, v[0:1]
	global_store_dwordx4 v[38:39], v[18:21], off
	v_or_b32_e32 v0, s4, v13
	v_lshlrev_b32_e32 v0, 11, v0
	v_cvt_pk_bf16_f32 v18, v25, v23
	v_cvt_pk_bf16_f32 v19, v27, v29
	v_cvt_pk_bf16_f32 v20, v31, v33
	v_cvt_pk_bf16_f32 v21, v35, v37
	ds_read2_b32 v[24:25], v12 offset0:49 offset1:57
	ds_read2_b32 v[26:27], v12 offset0:16 offset1:24
	ds_read2_b32 v[28:29], v12 offset0:82 offset1:90
	ds_read2_b32 v[30:31], v12 offset0:115 offset1:123
	ds_read2_b32 v[32:33], v12 offset0:148 offset1:156
	ds_read2_b32 v[34:35], v12 offset0:181 offset1:189
	ds_read2_b32 v[36:37], v12 offset0:214 offset1:222
	ds_read2_b32 v[38:39], v12 offset0:247 offset1:255
	v_lshl_add_u64 v[22:23], v[8:9], 0, v[0:1]
	v_or_b32_e32 v0, s4, v14
	v_lshlrev_b32_e32 v0, 11, v0
	global_store_dwordx4 v[22:23], v[18:21], off
	v_lshl_add_u64 v[22:23], v[8:9], 0, v[0:1]
	v_or_b32_e32 v0, s4, v15
	s_waitcnt lgkmcnt(6)
	v_cvt_pk_bf16_f32 v18, v26, v24
	s_waitcnt lgkmcnt(4)
	v_cvt_pk_bf16_f32 v19, v28, v30
	s_waitcnt lgkmcnt(2)
	v_cvt_pk_bf16_f32 v20, v32, v34
	s_waitcnt lgkmcnt(0)
	v_cvt_pk_bf16_f32 v21, v36, v38
	v_lshlrev_b32_e32 v0, 11, v0
	global_store_dwordx4 v[22:23], v[18:21], off
	v_lshl_add_u64 v[8:9], v[8:9], 0, v[0:1]
	v_readlane_b32 s20, v253, 3
	v_cvt_pk_bf16_f32 v18, v27, v25
	v_cvt_pk_bf16_f32 v19, v29, v31
	v_cvt_pk_bf16_f32 v20, v33, v35
	v_cvt_pk_bf16_f32 v21, v37, v39
	global_store_dwordx4 v[8:9], v[18:21], off
	s_waitcnt lgkmcnt(0)
	v_readlane_b32 s21, v253, 4

.LBB0_120:
	s_lshl_b32 s9, s5, 1
	s_lshl_b32 s10, s6, 1
	v_or_b32_e32 v20, s10, v0
	s_add_i32 s11, s9, 4
	s_add_i32 s12, s10, 4
	s_add_i32 s13, s9, 8
	s_add_i32 s14, s10, 8
	s_add_i32 s15, s9, 12
	s_add_i32 s20, s10, 12
	s_add_i32 s21, s9, 16
	s_add_i32 s22, s10, 16
	s_add_i32 s23, s9, 20
	s_add_i32 s24, s10, 20
	s_add_i32 s25, s9, 24
	s_add_i32 s26, s10, 24
	s_add_i32 s27, s9, 28
	s_add_i32 s28, s10, 28
	v_or_b32_e32 v18, s9, v5
	v_ashrrev_i32_e32 v21, 31, v20
	v_or_b32_e32 v22, s11, v5
	v_or_b32_e32 v24, s12, v0
	v_or_b32_e32 v26, s13, v5
	v_or_b32_e32 v28, s14, v0
	v_or_b32_e32 v30, s15, v5
	v_or_b32_e32 v32, s20, v0
	v_or_b32_e32 v34, s21, v5
	v_or_b32_e32 v36, s22, v0
	v_or_b32_e32 v38, s23, v5
	v_or_b32_e32 v40, s24, v0
	v_or_b32_e32 v42, s25, v5
	v_or_b32_e32 v44, s26, v0
	v_or_b32_e32 v46, s27, v5
	v_or_b32_e32 v48, s28, v0
	v_ashrrev_i32_e32 v19, 31, v18
	v_lshlrev_b64 v[20:21], 12, v[20:21]
	v_ashrrev_i32_e32 v25, 31, v24
	v_ashrrev_i32_e32 v23, 31, v22
	v_ashrrev_i32_e32 v29, 31, v28
	v_ashrrev_i32_e32 v27, 31, v26
	v_ashrrev_i32_e32 v33, 31, v32
	v_ashrrev_i32_e32 v31, 31, v30
	v_ashrrev_i32_e32 v37, 31, v36
	v_ashrrev_i32_e32 v35, 31, v34
	v_ashrrev_i32_e32 v41, 31, v40
	v_ashrrev_i32_e32 v39, 31, v38
	v_ashrrev_i32_e32 v45, 31, v44
	v_ashrrev_i32_e32 v43, 31, v42
	v_ashrrev_i32_e32 v49, 31, v48
	v_ashrrev_i32_e32 v47, 31, v46
	v_lshlrev_b64 v[18:19], 12, v[18:19]
	v_lshl_add_u64 v[20:21], v[8:9], 0, v[20:21]
	v_lshlrev_b64 v[22:23], 12, v[22:23]
	v_lshlrev_b64 v[24:25], 12, v[24:25]
	v_lshlrev_b64 v[26:27], 12, v[26:27]
	v_lshlrev_b64 v[28:29], 12, v[28:29]
	v_lshlrev_b64 v[30:31], 12, v[30:31]
	v_lshlrev_b64 v[32:33], 12, v[32:33]
	v_lshlrev_b64 v[34:35], 12, v[34:35]
	v_lshlrev_b64 v[36:37], 12, v[36:37]
	v_lshlrev_b64 v[38:39], 12, v[38:39]
	v_lshlrev_b64 v[40:41], 12, v[40:41]
	v_lshlrev_b64 v[42:43], 12, v[42:43]
	v_lshlrev_b64 v[44:45], 12, v[44:45]
	v_lshlrev_b64 v[46:47], 12, v[46:47]
	v_lshlrev_b64 v[48:49], 12, v[48:49]
	v_lshl_add_u64 v[18:19], v[8:9], 0, v[18:19]
	v_lshl_add_u64 v[24:25], v[8:9], 0, v[24:25]
	v_lshl_add_u64 v[22:23], v[8:9], 0, v[22:23]
	v_lshl_add_u64 v[28:29], v[8:9], 0, v[28:29]
	v_lshl_add_u64 v[26:27], v[8:9], 0, v[26:27]
	v_lshl_add_u64 v[32:33], v[8:9], 0, v[32:33]
	v_lshl_add_u64 v[30:31], v[8:9], 0, v[30:31]
	v_lshl_add_u64 v[36:37], v[8:9], 0, v[36:37]
	v_lshl_add_u64 v[34:35], v[8:9], 0, v[34:35]
	v_lshl_add_u64 v[40:41], v[8:9], 0, v[40:41]
	v_lshl_add_u64 v[38:39], v[8:9], 0, v[38:39]
	v_lshl_add_u64 v[44:45], v[8:9], 0, v[44:45]
	v_lshl_add_u64 v[42:43], v[8:9], 0, v[42:43]
	v_lshl_add_u64 v[48:49], v[8:9], 0, v[48:49]
	v_lshl_add_u64 v[46:47], v[8:9], 0, v[46:47]
	global_load_dword v10, v[20:21], off
	global_load_dword v17, v[18:19], off
	global_load_dword v50, v[24:25], off
	global_load_dword v51, v[22:23], off
	global_load_dword v52, v[28:29], off
	global_load_dword v53, v[26:27], off
	global_load_dword v54, v[32:33], off
	global_load_dword v55, v[30:31], off
	global_load_dword v56, v[36:37], off
	global_load_dword v57, v[34:35], off
	global_load_dword v58, v[40:41], off
	global_load_dword v59, v[38:39], off
	global_load_dword v60, v[44:45], off
	global_load_dword v61, v[42:43], off
	global_load_dword v62, v[48:49], off
	global_load_dword v63, v[46:47], off
	v_or_b32_e32 v20, s9, v3
	v_or_b32_e32 v18, s10, v2
	s_add_i32 s6, s6, 16
	s_add_i32 s5, s5, 16
	s_add_i32 s7, s7, -16
	v_mad_u64_u32 v[18:19], s[18:19], v18, s75, v[4:5]
	v_mad_u64_u32 v[20:21], s[18:19], v20, s75, v[4:5]
	v_or_b32_e32 v19, s11, v3
	v_or_b32_e32 v21, s12, v2
	v_or_b32_e32 v28, s13, v3
	v_or_b32_e32 v26, s14, v2
	v_or_b32_e32 v32, s15, v3
	v_or_b32_e32 v30, s20, v2
	v_or_b32_e32 v36, s21, v3
	v_or_b32_e32 v34, s22, v2
	v_or_b32_e32 v40, s23, v3
	v_or_b32_e32 v38, s24, v2
	v_or_b32_e32 v44, s25, v3
	v_or_b32_e32 v42, s26, v2
	v_or_b32_e32 v48, s27, v3
	v_or_b32_e32 v46, s28, v2
	s_cmp_lg_u32 s7, 0
	v_mad_u64_u32 v[22:23], s[10:11], v21, s75, v[4:5]
	v_mad_u64_u32 v[24:25], s[10:11], v19, s75, v[4:5]
	v_mad_u64_u32 v[26:27], s[10:11], v26, s75, v[4:5]
	v_mad_u64_u32 v[28:29], s[10:11], v28, s75, v[4:5]
	v_mad_u64_u32 v[30:31], s[10:11], v30, s75, v[4:5]
	v_mad_u64_u32 v[32:33], s[10:11], v32, s75, v[4:5]
	v_mad_u64_u32 v[34:35], s[10:11], v34, s75, v[4:5]
	v_mad_u64_u32 v[36:37], s[10:11], v36, s75, v[4:5]
	v_mad_u64_u32 v[38:39], s[10:11], v38, s75, v[4:5]
	v_mad_u64_u32 v[40:41], s[10:11], v40, s75, v[4:5]
	v_mad_u64_u32 v[42:43], s[10:11], v42, s75, v[4:5]
	v_mad_u64_u32 v[44:45], s[10:11], v44, s75, v[4:5]
	v_mad_u64_u32 v[46:47], s[10:11], v46, s75, v[4:5]
	v_mad_u64_u32 v[48:49], s[10:11], v48, s75, v[4:5]
	s_lshl_b32 s9, s5, 1
	s_lshl_b32 s10, s6, 1
	v_or_b32_e32 v102, s10, v0
	s_add_i32 s11, s9, 4
	s_add_i32 s12, s10, 4
	s_add_i32 s13, s9, 8
	s_add_i32 s14, s10, 8
	s_add_i32 s15, s9, 12
	s_add_i32 s20, s10, 12
	s_add_i32 s21, s9, 16
	s_add_i32 s22, s10, 16
	s_add_i32 s23, s9, 20
	s_add_i32 s24, s10, 20
	s_add_i32 s25, s9, 24
	s_add_i32 s26, s10, 24
	s_add_i32 s27, s9, 28
	s_add_i32 s28, s10, 28
	v_or_b32_e32 v100, s9, v5
	v_ashrrev_i32_e32 v103, 31, v102
	v_or_b32_e32 v104, s11, v5
	v_or_b32_e32 v106, s12, v0
	v_or_b32_e32 v108, s13, v5
	v_or_b32_e32 v110, s14, v0
	v_or_b32_e32 v112, s15, v5
	v_or_b32_e32 v114, s20, v0
	v_or_b32_e32 v116, s21, v5
	v_or_b32_e32 v152, s22, v0
	v_or_b32_e32 v154, s23, v5
	v_or_b32_e32 v156, s24, v0
	v_or_b32_e32 v158, s25, v5
	v_or_b32_e32 v160, s26, v0
	v_or_b32_e32 v162, s27, v5
	v_or_b32_e32 v164, s28, v0
	v_ashrrev_i32_e32 v101, 31, v100
	v_lshlrev_b64 v[102:103], 12, v[102:103]
	v_ashrrev_i32_e32 v107, 31, v106
	v_ashrrev_i32_e32 v105, 31, v104
	v_ashrrev_i32_e32 v111, 31, v110
	v_ashrrev_i32_e32 v109, 31, v108
	v_ashrrev_i32_e32 v115, 31, v114
	v_ashrrev_i32_e32 v113, 31, v112
	v_ashrrev_i32_e32 v153, 31, v152
	v_ashrrev_i32_e32 v117, 31, v116
	v_ashrrev_i32_e32 v157, 31, v156
	v_ashrrev_i32_e32 v155, 31, v154
	v_ashrrev_i32_e32 v161, 31, v160
	v_ashrrev_i32_e32 v159, 31, v158
	v_ashrrev_i32_e32 v165, 31, v164
	v_ashrrev_i32_e32 v163, 31, v162
	v_lshlrev_b64 v[100:101], 12, v[100:101]
	v_lshl_add_u64 v[102:103], v[8:9], 0, v[102:103]
	v_lshlrev_b64 v[104:105], 12, v[104:105]
	v_lshlrev_b64 v[106:107], 12, v[106:107]
	v_lshlrev_b64 v[108:109], 12, v[108:109]
	v_lshlrev_b64 v[110:111], 12, v[110:111]
	v_lshlrev_b64 v[112:113], 12, v[112:113]
	v_lshlrev_b64 v[114:115], 12, v[114:115]
	v_lshlrev_b64 v[116:117], 12, v[116:117]
	v_lshlrev_b64 v[152:153], 12, v[152:153]
	v_lshlrev_b64 v[154:155], 12, v[154:155]
	v_lshlrev_b64 v[156:157], 12, v[156:157]
	v_lshlrev_b64 v[158:159], 12, v[158:159]
	v_lshlrev_b64 v[160:161], 12, v[160:161]
	v_lshlrev_b64 v[162:163], 12, v[162:163]
	v_lshlrev_b64 v[164:165], 12, v[164:165]
	v_lshl_add_u64 v[100:101], v[8:9], 0, v[100:101]
	v_lshl_add_u64 v[106:107], v[8:9], 0, v[106:107]
	v_lshl_add_u64 v[104:105], v[8:9], 0, v[104:105]
	v_lshl_add_u64 v[110:111], v[8:9], 0, v[110:111]
	v_lshl_add_u64 v[108:109], v[8:9], 0, v[108:109]
	v_lshl_add_u64 v[114:115], v[8:9], 0, v[114:115]
	v_lshl_add_u64 v[112:113], v[8:9], 0, v[112:113]
	v_lshl_add_u64 v[152:153], v[8:9], 0, v[152:153]
	v_lshl_add_u64 v[116:117], v[8:9], 0, v[116:117]
	v_lshl_add_u64 v[156:157], v[8:9], 0, v[156:157]
	v_lshl_add_u64 v[154:155], v[8:9], 0, v[154:155]
	v_lshl_add_u64 v[160:161], v[8:9], 0, v[160:161]
	v_lshl_add_u64 v[158:159], v[8:9], 0, v[158:159]
	v_lshl_add_u64 v[164:165], v[8:9], 0, v[164:165]
	v_lshl_add_u64 v[162:163], v[8:9], 0, v[162:163]
	global_load_dword v99, v[102:103], off
	global_load_dword v130, v[100:101], off
	global_load_dword v166, v[106:107], off
	global_load_dword v167, v[104:105], off
	global_load_dword v168, v[110:111], off
	global_load_dword v169, v[108:109], off
	global_load_dword v170, v[114:115], off
	global_load_dword v171, v[112:113], off
	global_load_dword v172, v[152:153], off
	global_load_dword v173, v[116:117], off
	global_load_dword v174, v[156:157], off
	global_load_dword v175, v[154:155], off
	global_load_dword v176, v[160:161], off
	global_load_dword v177, v[158:159], off
	global_load_dword v178, v[164:165], off
	global_load_dword v179, v[162:163], off
	v_or_b32_e32 v102, s9, v3
	v_or_b32_e32 v100, s10, v2
	s_add_i32 s6, s6, 16
	s_add_i32 s5, s5, 16
	s_add_i32 s7, s7, -16
	v_mad_u64_u32 v[100:101], s[18:19], v100, s75, v[4:5]
	v_mad_u64_u32 v[102:103], s[18:19], v102, s75, v[4:5]
	v_or_b32_e32 v101, s11, v3
	v_or_b32_e32 v103, s12, v2
	v_or_b32_e32 v110, s13, v3
	v_or_b32_e32 v108, s14, v2
	v_or_b32_e32 v114, s15, v3
	v_or_b32_e32 v112, s20, v2
	v_or_b32_e32 v152, s21, v3
	v_or_b32_e32 v116, s22, v2
	v_or_b32_e32 v156, s23, v3
	v_or_b32_e32 v154, s24, v2
	v_or_b32_e32 v160, s25, v3
	v_or_b32_e32 v158, s26, v2
	v_or_b32_e32 v164, s27, v3
	v_or_b32_e32 v162, s28, v2
	s_cmp_lg_u32 s7, 0
	v_mad_u64_u32 v[104:105], s[10:11], v103, s75, v[4:5]
	v_mad_u64_u32 v[106:107], s[10:11], v101, s75, v[4:5]
	v_mad_u64_u32 v[108:109], s[10:11], v108, s75, v[4:5]
	v_mad_u64_u32 v[110:111], s[10:11], v110, s75, v[4:5]
	v_mad_u64_u32 v[112:113], s[10:11], v112, s75, v[4:5]
	v_mad_u64_u32 v[114:115], s[10:11], v114, s75, v[4:5]
	v_mad_u64_u32 v[116:117], s[10:11], v116, s75, v[4:5]
	v_mad_u64_u32 v[152:153], s[10:11], v152, s75, v[4:5]
	v_mad_u64_u32 v[154:155], s[10:11], v154, s75, v[4:5]
	v_mad_u64_u32 v[156:157], s[10:11], v156, s75, v[4:5]
	v_mad_u64_u32 v[158:159], s[10:11], v158, s75, v[4:5]
	v_mad_u64_u32 v[160:161], s[10:11], v160, s75, v[4:5]
	v_mad_u64_u32 v[162:163], s[10:11], v162, s75, v[4:5]
	v_mad_u64_u32 v[164:165], s[10:11], v164, s75, v[4:5]
	s_waitcnt vmcnt(31)
	ds_write_b32 v18, v10
	s_waitcnt vmcnt(30)
	ds_write_b32 v20, v17
	s_waitcnt vmcnt(29)
	ds_write_b32 v22, v50
	s_waitcnt vmcnt(28)
	ds_write_b32 v24, v51
	s_waitcnt vmcnt(27)
	ds_write_b32 v26, v52
	s_waitcnt vmcnt(26)
	ds_write_b32 v28, v53
	s_waitcnt vmcnt(25)
	ds_write_b32 v30, v54
	s_waitcnt vmcnt(24)
	ds_write_b32 v32, v55
	s_waitcnt vmcnt(23)
	ds_write_b32 v34, v56
	s_waitcnt vmcnt(22)
	ds_write_b32 v36, v57
	s_waitcnt vmcnt(21)
	ds_write_b32 v38, v58
	s_waitcnt vmcnt(20)
	ds_write_b32 v40, v59
	s_waitcnt vmcnt(19)
	ds_write_b32 v42, v60
	s_waitcnt vmcnt(18)
	ds_write_b32 v44, v61
	s_waitcnt vmcnt(17)
	ds_write_b32 v46, v62
	s_waitcnt vmcnt(16)
	ds_write_b32 v48, v63
	s_waitcnt vmcnt(15)
	ds_write_b32 v100, v99
	s_waitcnt vmcnt(14)
	ds_write_b32 v102, v130
	s_waitcnt vmcnt(13)
	ds_write_b32 v104, v166
	s_waitcnt vmcnt(12)
	ds_write_b32 v106, v167
	s_waitcnt vmcnt(11)
	ds_write_b32 v108, v168
	s_waitcnt vmcnt(10)
	ds_write_b32 v110, v169
	s_waitcnt vmcnt(9)
	ds_write_b32 v112, v170
	s_waitcnt vmcnt(8)
	ds_write_b32 v114, v171
	s_waitcnt vmcnt(7)
	ds_write_b32 v116, v172
	s_waitcnt vmcnt(6)
	ds_write_b32 v152, v173
	s_waitcnt vmcnt(5)
	ds_write_b32 v154, v174
	s_waitcnt vmcnt(4)
	ds_write_b32 v156, v175
	s_waitcnt vmcnt(3)
	ds_write_b32 v158, v176
	s_waitcnt vmcnt(2)
	ds_write_b32 v160, v177
	s_waitcnt vmcnt(1)
	ds_write_b32 v162, v178
	s_waitcnt vmcnt(0)
	ds_write_b32 v164, v179
	v_mov_b32_e32 v10, v99
	v_mov_b32_e32 v17, v130
	v_mov_b32_e32 v40, v156
	v_mov_b32_e32 v41, v157
	v_mov_b32_e32 v42, v158
	v_mov_b32_e32 v43, v159
	v_mov_b32_e32 v44, v160
	v_mov_b32_e32 v45, v161
	v_mov_b32_e32 v46, v162
	v_mov_b32_e32 v47, v163
	v_mov_b32_e32 v48, v164
	v_mov_b32_e32 v49, v165
	v_mov_b32_e32 v50, v166
	v_mov_b32_e32 v51, v167
	v_mov_b32_e32 v52, v168
	v_mov_b32_e32 v53, v169
	v_mov_b32_e32 v54, v170
	v_mov_b32_e32 v55, v171
	v_mov_b32_e32 v56, v172
	v_mov_b32_e32 v57, v173
	v_mov_b32_e32 v58, v174
	v_mov_b32_e32 v59, v175
	v_mov_b32_e32 v60, v176
	v_mov_b32_e32 v61, v177
	s_waitcnt lgkmcnt(0)
	s_lshl_b64 s[6:7], s[46:47], 1
	ds_read2_b32 v[22:23], v12 offset0:33 offset1:41
	ds_read2_b32 v[24:25], v12 offset1:8
	ds_read2_b32 v[26:27], v12 offset0:66 offset1:74
	ds_read2_b32 v[28:29], v12 offset0:99 offset1:107
	ds_read2_b32 v[30:31], v12 offset0:132 offset1:140
	ds_read2_b32 v[32:33], v12 offset0:165 offset1:173
	ds_read2_b32 v[34:35], v12 offset0:198 offset1:206
	ds_read2_b32 v[36:37], v12 offset0:231 offset1:239
	s_add_u32 s2, s2, s6
	s_addc_u32 s3, s3, s7
	v_lshlrev_b32_e32 v0, 1, v6
	v_lshl_add_u64 v[8:9], s[2:3], 0, v[0:1]
	s_mov_b64 s[2:3], 0x1100000
	v_or_b32_e32 v0, s4, v11
	v_lshl_add_u64 v[8:9], v[8:9], 0, s[2:3]
	v_lshlrev_b32_e32 v0, 11, v0
	s_waitcnt lgkmcnt(6)
	v_cvt_pk_bf16_f32 v18, v24, v22
	s_waitcnt lgkmcnt(4)
	v_cvt_pk_bf16_f32 v19, v26, v28
	s_waitcnt lgkmcnt(2)
	v_cvt_pk_bf16_f32 v20, v30, v32
	s_waitcnt lgkmcnt(0)
	v_cvt_pk_bf16_f32 v21, v34, v36
	v_lshl_add_u64 v[38:39], v[8:9], 0, v[0:1]
	global_store_dwordx4 v[38:39], v[18:21], off
	v_or_b32_e32 v0, s4, v13
	v_lshlrev_b32_e32 v0, 11, v0
	v_cvt_pk_bf16_f32 v18, v25, v23
	v_cvt_pk_bf16_f32 v19, v27, v29
	v_cvt_pk_bf16_f32 v20, v31, v33
	v_cvt_pk_bf16_f32 v21, v35, v37
	ds_read2_b32 v[24:25], v12 offset0:49 offset1:57
	ds_read2_b32 v[26:27], v12 offset0:16 offset1:24
	ds_read2_b32 v[28:29], v12 offset0:82 offset1:90
	ds_read2_b32 v[30:31], v12 offset0:115 offset1:123
	ds_read2_b32 v[32:33], v12 offset0:148 offset1:156
	ds_read2_b32 v[34:35], v12 offset0:181 offset1:189
	ds_read2_b32 v[36:37], v12 offset0:214 offset1:222
	ds_read2_b32 v[38:39], v12 offset0:247 offset1:255
	v_lshl_add_u64 v[22:23], v[8:9], 0, v[0:1]
	v_or_b32_e32 v0, s4, v14
	v_lshlrev_b32_e32 v0, 11, v0
	global_store_dwordx4 v[22:23], v[18:21], off
	v_lshl_add_u64 v[22:23], v[8:9], 0, v[0:1]
	v_or_b32_e32 v0, s4, v15
	s_waitcnt lgkmcnt(6)
	v_cvt_pk_bf16_f32 v18, v26, v24
	s_waitcnt lgkmcnt(4)
	v_cvt_pk_bf16_f32 v19, v28, v30
	s_waitcnt lgkmcnt(2)
	v_cvt_pk_bf16_f32 v20, v32, v34
	s_waitcnt lgkmcnt(0)
	v_cvt_pk_bf16_f32 v21, v36, v38
	v_lshlrev_b32_e32 v0, 11, v0
	global_store_dwordx4 v[22:23], v[18:21], off
	v_lshl_add_u64 v[8:9], v[8:9], 0, v[0:1]
	v_readlane_b32 s20, v253, 3
	v_cvt_pk_bf16_f32 v18, v27, v25
	v_cvt_pk_bf16_f32 v19, v29, v31
	v_cvt_pk_bf16_f32 v20, v33, v35
	v_cvt_pk_bf16_f32 v21, v37, v39
	global_store_dwordx4 v[8:9], v[18:21], off
	s_waitcnt lgkmcnt(0)
	v_readlane_b32 s21, v253, 4

.LBB0_125:
	s_lshl_b32 s11, s7, 1
	s_lshl_b32 s10, s6, 1
	v_or_b32_e32 v0, s11, v10
	s_add_i32 s13, s11, 4
	s_add_i32 s12, s10, 4
	s_add_i32 s14, s10, 8
	s_add_i32 s15, s11, 8
	v_lshlrev_b64 v[34:35], 12, v[0:1]
	v_or_b32_e32 v0, s13, v10
	v_mov_b32_e32 v19, v1
	v_mov_b32_e32 v21, v1
	v_mov_b32_e32 v23, v1
	v_or_b32_e32 v18, s10, v5
	s_add_i32 s18, s10, 12
	s_add_i32 s19, s11, 12
	s_add_i32 s20, s10, 16
	s_add_i32 s22, s10, 20
	s_add_i32 s24, s10, 24
	s_add_i32 s26, s10, 28
	v_or_b32_e32 v20, s12, v5
	v_or_b32_e32 v22, s14, v5
	v_lshlrev_b64 v[36:37], 12, v[0:1]
	v_or_b32_e32 v0, s15, v10
	v_mov_b32_e32 v25, v1
	v_mov_b32_e32 v27, v1
	v_mov_b32_e32 v29, v1
	v_mov_b32_e32 v31, v1
	v_mov_b32_e32 v33, v1
	s_add_i32 s21, s11, 16
	v_lshlrev_b64 v[18:19], 12, v[18:19]
	v_or_b32_e32 v24, s18, v5
	v_or_b32_e32 v26, s20, v5
	v_or_b32_e32 v28, s22, v5
	v_or_b32_e32 v30, s24, v5
	v_or_b32_e32 v32, s26, v5
	v_lshl_add_u64 v[34:35], v[8:9], 0, v[34:35]
	v_lshlrev_b64 v[20:21], 12, v[20:21]
	v_lshlrev_b64 v[22:23], 12, v[22:23]
	v_lshlrev_b64 v[38:39], 12, v[0:1]
	v_or_b32_e32 v0, s19, v10
	s_add_i32 s23, s11, 20
	v_lshl_add_u64 v[18:19], v[8:9], 0, v[18:19]
	v_lshlrev_b64 v[24:25], 12, v[24:25]
	v_lshlrev_b64 v[26:27], 12, v[26:27]
	v_lshlrev_b64 v[28:29], 12, v[28:29]
	v_lshlrev_b64 v[30:31], 12, v[30:31]
	v_lshlrev_b64 v[32:33], 12, v[32:33]
	v_lshl_add_u64 v[36:37], v[8:9], 0, v[36:37]
	v_lshl_add_u64 v[20:21], v[8:9], 0, v[20:21]
	v_lshl_add_u64 v[22:23], v[8:9], 0, v[22:23]
	global_load_dword v17, v[34:35], off
	global_load_dword v50, v[18:19], off
	v_lshlrev_b64 v[34:35], 12, v[0:1]
	v_or_b32_e32 v0, s21, v10
	s_add_i32 s25, s11, 24
	v_lshl_add_u64 v[24:25], v[8:9], 0, v[24:25]
	v_lshl_add_u64 v[26:27], v[8:9], 0, v[26:27]
	v_lshl_add_u64 v[28:29], v[8:9], 0, v[28:29]
	v_lshl_add_u64 v[30:31], v[8:9], 0, v[30:31]
	v_lshl_add_u64 v[32:33], v[8:9], 0, v[32:33]
	global_load_dword v51, v[36:37], off
	global_load_dword v52, v[20:21], off
	global_load_dword v53, v[22:23], off
	global_load_dword v54, v[24:25], off
	global_load_dword v55, v[26:27], off
	global_load_dword v56, v[28:29], off
	global_load_dword v57, v[30:31], off
	global_load_dword v58, v[32:33], off
	v_lshl_add_u64 v[20:21], v[8:9], 0, v[34:35]
	v_lshlrev_b64 v[22:23], 12, v[0:1]
	v_or_b32_e32 v0, s23, v10
	s_add_i32 s27, s11, 28
	v_lshl_add_u64 v[18:19], v[8:9], 0, v[38:39]
	global_load_dword v59, v[20:21], off
	global_load_dword v60, v[18:19], off
	v_lshlrev_b64 v[20:21], 12, v[0:1]
	v_or_b32_e32 v0, s25, v10
	v_lshl_add_u64 v[18:19], v[8:9], 0, v[22:23]
	v_lshlrev_b64 v[22:23], 12, v[0:1]
	v_or_b32_e32 v0, s27, v10
	v_lshlrev_b64 v[24:25], 12, v[0:1]
	v_lshl_add_u64 v[24:25], v[8:9], 0, v[24:25]
	v_lshl_add_u64 v[20:21], v[8:9], 0, v[20:21]
	v_lshl_add_u64 v[22:23], v[8:9], 0, v[22:23]
	global_load_dword v0, v[24:25], off
	global_load_dword v61, v[22:23], off
	global_load_dword v62, v[20:21], off
	global_load_dword v63, v[18:19], off
	v_or_b32_e32 v20, s10, v3
	v_or_b32_e32 v18, s11, v2
	s_add_i32 s7, s7, 16
	s_add_i32 s6, s6, 16
	s_add_i32 s9, s9, -16
	v_mad_u64_u32 v[18:19], s[10:11], v18, s75, v[4:5]
	v_mad_u64_u32 v[20:21], s[10:11], v20, s75, v[4:5]
	v_or_b32_e32 v19, s12, v3
	v_or_b32_e32 v21, s13, v2
	v_or_b32_e32 v28, s14, v3
	v_or_b32_e32 v26, s15, v2
	v_or_b32_e32 v32, s18, v3
	v_or_b32_e32 v30, s19, v2
	v_or_b32_e32 v36, s20, v3
	v_or_b32_e32 v34, s21, v2
	v_or_b32_e32 v40, s22, v3
	v_or_b32_e32 v38, s23, v2
	v_or_b32_e32 v44, s24, v3
	v_or_b32_e32 v42, s25, v2
	v_or_b32_e32 v48, s26, v3
	v_or_b32_e32 v46, s27, v2
	s_cmp_lg_u32 s9, 0
	v_mad_u64_u32 v[22:23], s[10:11], v21, s75, v[4:5]
	v_mad_u64_u32 v[24:25], s[10:11], v19, s75, v[4:5]
	v_mad_u64_u32 v[26:27], s[10:11], v26, s75, v[4:5]
	v_mad_u64_u32 v[28:29], s[10:11], v28, s75, v[4:5]
	v_mad_u64_u32 v[30:31], s[10:11], v30, s75, v[4:5]
	v_mad_u64_u32 v[32:33], s[10:11], v32, s75, v[4:5]
	v_mad_u64_u32 v[34:35], s[10:11], v34, s75, v[4:5]
	v_mad_u64_u32 v[36:37], s[10:11], v36, s75, v[4:5]
	v_mad_u64_u32 v[38:39], s[10:11], v38, s75, v[4:5]
	v_mad_u64_u32 v[40:41], s[10:11], v40, s75, v[4:5]
	v_mad_u64_u32 v[42:43], s[10:11], v42, s75, v[4:5]
	v_mad_u64_u32 v[44:45], s[10:11], v44, s75, v[4:5]
	v_mad_u64_u32 v[46:47], s[10:11], v46, s75, v[4:5]
	v_mad_u64_u32 v[48:49], s[10:11], v48, s75, v[4:5]
	v_mov_b32_e32 v101, v1
	s_lshl_b32 s11, s7, 1
	s_lshl_b32 s10, s6, 1
	v_or_b32_e32 v100, s11, v10
	s_add_i32 s13, s11, 4
	s_add_i32 s12, s10, 4
	s_add_i32 s14, s10, 8
	s_add_i32 s15, s11, 8
	v_lshlrev_b64 v[152:153], 12, v[100:101]
	v_or_b32_e32 v100, s13, v10
	v_mov_b32_e32 v103, v101
	v_mov_b32_e32 v105, v101
	v_mov_b32_e32 v107, v101
	v_or_b32_e32 v102, s10, v5
	s_add_i32 s18, s10, 12
	s_add_i32 s19, s11, 12
	s_add_i32 s20, s10, 16
	s_add_i32 s22, s10, 20
	s_add_i32 s24, s10, 24
	s_add_i32 s26, s10, 28
	v_or_b32_e32 v104, s12, v5
	v_or_b32_e32 v106, s14, v5
	v_lshlrev_b64 v[154:155], 12, v[100:101]
	v_or_b32_e32 v100, s15, v10
	v_mov_b32_e32 v109, v101
	v_mov_b32_e32 v111, v101
	v_mov_b32_e32 v113, v101
	v_mov_b32_e32 v115, v101
	v_mov_b32_e32 v117, v101
	s_add_i32 s21, s11, 16
	v_lshlrev_b64 v[102:103], 12, v[102:103]
	v_or_b32_e32 v108, s18, v5
	v_or_b32_e32 v110, s20, v5
	v_or_b32_e32 v112, s22, v5
	v_or_b32_e32 v114, s24, v5
	v_or_b32_e32 v116, s26, v5
	v_lshl_add_u64 v[152:153], v[8:9], 0, v[152:153]
	v_lshlrev_b64 v[104:105], 12, v[104:105]
	v_lshlrev_b64 v[106:107], 12, v[106:107]
	v_lshlrev_b64 v[156:157], 12, v[100:101]
	v_or_b32_e32 v100, s19, v10
	s_add_i32 s23, s11, 20
	v_lshl_add_u64 v[102:103], v[8:9], 0, v[102:103]
	v_lshlrev_b64 v[108:109], 12, v[108:109]
	v_lshlrev_b64 v[110:111], 12, v[110:111]
	v_lshlrev_b64 v[112:113], 12, v[112:113]
	v_lshlrev_b64 v[114:115], 12, v[114:115]
	v_lshlrev_b64 v[116:117], 12, v[116:117]
	v_lshl_add_u64 v[154:155], v[8:9], 0, v[154:155]
	v_lshl_add_u64 v[104:105], v[8:9], 0, v[104:105]
	v_lshl_add_u64 v[106:107], v[8:9], 0, v[106:107]
	global_load_dword v99, v[152:153], off
	global_load_dword v130, v[102:103], off
	v_lshlrev_b64 v[152:153], 12, v[100:101]
	v_or_b32_e32 v100, s21, v10
	s_add_i32 s25, s11, 24
	v_lshl_add_u64 v[108:109], v[8:9], 0, v[108:109]
	v_lshl_add_u64 v[110:111], v[8:9], 0, v[110:111]
	v_lshl_add_u64 v[112:113], v[8:9], 0, v[112:113]
	v_lshl_add_u64 v[114:115], v[8:9], 0, v[114:115]
	v_lshl_add_u64 v[116:117], v[8:9], 0, v[116:117]
	global_load_dword v168, v[154:155], off
	global_load_dword v169, v[104:105], off
	global_load_dword v170, v[106:107], off
	global_load_dword v171, v[108:109], off
	global_load_dword v172, v[110:111], off
	global_load_dword v173, v[112:113], off
	global_load_dword v174, v[114:115], off
	global_load_dword v175, v[116:117], off
	v_lshl_add_u64 v[104:105], v[8:9], 0, v[152:153]
	v_lshlrev_b64 v[106:107], 12, v[100:101]
	v_or_b32_e32 v100, s23, v10
	s_add_i32 s27, s11, 28
	v_lshl_add_u64 v[102:103], v[8:9], 0, v[156:157]
	global_load_dword v176, v[104:105], off
	global_load_dword v177, v[102:103], off
	v_lshlrev_b64 v[104:105], 12, v[100:101]
	v_or_b32_e32 v100, s25, v10
	v_lshl_add_u64 v[102:103], v[8:9], 0, v[106:107]
	v_lshlrev_b64 v[106:107], 12, v[100:101]
	v_or_b32_e32 v100, s27, v10
	v_lshlrev_b64 v[108:109], 12, v[100:101]
	v_lshl_add_u64 v[108:109], v[8:9], 0, v[108:109]
	v_lshl_add_u64 v[104:105], v[8:9], 0, v[104:105]
	v_lshl_add_u64 v[106:107], v[8:9], 0, v[106:107]
	global_load_dword v100, v[108:109], off
	global_load_dword v178, v[106:107], off
	global_load_dword v179, v[104:105], off
	global_load_dword v180, v[102:103], off
	v_or_b32_e32 v104, s10, v3
	v_or_b32_e32 v102, s11, v2
	s_add_i32 s7, s7, 16
	s_add_i32 s6, s6, 16
	s_add_i32 s9, s9, -16
	v_mad_u64_u32 v[102:103], s[10:11], v102, s75, v[4:5]
	v_mad_u64_u32 v[104:105], s[10:11], v104, s75, v[4:5]
	v_or_b32_e32 v103, s12, v3
	v_or_b32_e32 v105, s13, v2
	v_or_b32_e32 v112, s14, v3
	v_or_b32_e32 v110, s15, v2
	v_or_b32_e32 v116, s18, v3
	v_or_b32_e32 v114, s19, v2
	v_or_b32_e32 v154, s20, v3
	v_or_b32_e32 v152, s21, v2
	v_or_b32_e32 v158, s22, v3
	v_or_b32_e32 v156, s23, v2
	v_or_b32_e32 v162, s24, v3
	v_or_b32_e32 v160, s25, v2
	v_or_b32_e32 v166, s26, v3
	v_or_b32_e32 v164, s27, v2
	s_cmp_lg_u32 s9, 0
	v_mad_u64_u32 v[106:107], s[10:11], v105, s75, v[4:5]
	v_mad_u64_u32 v[108:109], s[10:11], v103, s75, v[4:5]
	v_mad_u64_u32 v[110:111], s[10:11], v110, s75, v[4:5]
	v_mad_u64_u32 v[112:113], s[10:11], v112, s75, v[4:5]
	v_mad_u64_u32 v[114:115], s[10:11], v114, s75, v[4:5]
	v_mad_u64_u32 v[116:117], s[10:11], v116, s75, v[4:5]
	v_mad_u64_u32 v[152:153], s[10:11], v152, s75, v[4:5]
	v_mad_u64_u32 v[154:155], s[10:11], v154, s75, v[4:5]
	v_mad_u64_u32 v[156:157], s[10:11], v156, s75, v[4:5]
	v_mad_u64_u32 v[158:159], s[10:11], v158, s75, v[4:5]
	v_mad_u64_u32 v[160:161], s[10:11], v160, s75, v[4:5]
	v_mad_u64_u32 v[162:163], s[10:11], v162, s75, v[4:5]
	v_mad_u64_u32 v[164:165], s[10:11], v164, s75, v[4:5]
	v_mad_u64_u32 v[166:167], s[10:11], v166, s75, v[4:5]
	s_waitcnt vmcnt(31)
	ds_write_b32 v18, v17
	s_waitcnt vmcnt(30)
	ds_write_b32 v20, v50
	s_waitcnt vmcnt(29)
	ds_write_b32 v22, v51
	s_waitcnt vmcnt(28)
	ds_write_b32 v24, v52
	s_waitcnt vmcnt(20)
	ds_write_b32 v26, v60
	ds_write_b32 v28, v53
	ds_write_b32 v30, v59
	ds_write_b32 v32, v54
	s_waitcnt vmcnt(16)
	ds_write_b32 v34, v63
	ds_write_b32 v36, v55
	ds_write_b32 v38, v62
	ds_write_b32 v40, v56
	ds_write_b32 v42, v61
	ds_write_b32 v44, v57
	ds_write_b32 v46, v0
	ds_write_b32 v48, v58
	s_waitcnt vmcnt(15)
	ds_write_b32 v102, v99
	s_waitcnt vmcnt(14)
	ds_write_b32 v104, v130
	s_waitcnt vmcnt(13)
	ds_write_b32 v106, v168
	s_waitcnt vmcnt(12)
	ds_write_b32 v108, v169
	s_waitcnt vmcnt(4)
	ds_write_b32 v110, v177
	ds_write_b32 v112, v170
	ds_write_b32 v114, v176
	ds_write_b32 v116, v171
	s_waitcnt vmcnt(0)
	ds_write_b32 v152, v180
	ds_write_b32 v154, v172
	ds_write_b32 v156, v179
	ds_write_b32 v158, v173
	ds_write_b32 v160, v178
	ds_write_b32 v162, v174
	ds_write_b32 v164, v100
	ds_write_b32 v166, v175
	v_mov_b32_e32 v17, v99
	v_mov_b32_e32 v40, v158
	v_mov_b32_e32 v41, v159
	v_mov_b32_e32 v42, v160
	v_mov_b32_e32 v43, v161
	v_mov_b32_e32 v44, v162
	v_mov_b32_e32 v45, v163
	v_mov_b32_e32 v46, v164
	v_mov_b32_e32 v47, v165
	v_mov_b32_e32 v48, v166
	v_mov_b32_e32 v49, v167
	v_mov_b32_e32 v50, v130
	v_mov_b32_e32 v51, v168
	v_mov_b32_e32 v52, v169
	v_mov_b32_e32 v53, v170
	v_mov_b32_e32 v54, v171
	v_mov_b32_e32 v55, v172
	v_mov_b32_e32 v56, v173
	v_mov_b32_e32 v57, v174
	v_mov_b32_e32 v58, v175
	v_mov_b32_e32 v59, v176
	v_mov_b32_e32 v60, v177
	v_mov_b32_e32 v61, v178
	s_lshl_b64 s[6:7], s[46:47], 20
	s_add_u32 s2, s2, s6
	s_waitcnt lgkmcnt(0)
	s_addc_u32 s3, s3, s7
	s_lshl_b32 s5, s5, 1
	ds_read2_b32 v[22:23], v12 offset0:33 offset1:41
	ds_read2_b32 v[24:25], v12 offset1:8
	ds_read2_b32 v[26:27], v12 offset0:66 offset1:74
	ds_read2_b32 v[28:29], v12 offset0:99 offset1:107
	ds_read2_b32 v[30:31], v12 offset0:132 offset1:140
	ds_read2_b32 v[32:33], v12 offset0:165 offset1:173
	ds_read2_b32 v[34:35], v12 offset0:198 offset1:206
	ds_read2_b32 v[36:37], v12 offset0:231 offset1:239
	s_add_u32 s2, s2, s5
	s_addc_u32 s3, s3, 0
	v_lshlrev_b32_e32 v0, 1, v6
	v_lshl_add_u64 v[8:9], s[2:3], 0, v[0:1]
	s_mov_b64 s[2:3], 0xe00000
	v_or_b32_e32 v0, s4, v11
	v_lshl_add_u64 v[8:9], v[8:9], 0, s[2:3]
	v_lshlrev_b32_e32 v0, 10, v0
	s_waitcnt lgkmcnt(6)
	v_cvt_pk_bf16_f32 v18, v24, v22
	s_waitcnt lgkmcnt(4)
	v_cvt_pk_bf16_f32 v19, v26, v28
	s_waitcnt lgkmcnt(2)
	v_cvt_pk_bf16_f32 v20, v30, v32
	s_waitcnt lgkmcnt(0)
	v_cvt_pk_bf16_f32 v21, v34, v36
	v_lshl_add_u64 v[38:39], v[8:9], 0, v[0:1]
	global_store_dwordx4 v[38:39], v[18:21], off
	v_or_b32_e32 v0, s4, v13
	v_lshlrev_b32_e32 v0, 10, v0
	v_cvt_pk_bf16_f32 v18, v25, v23
	v_cvt_pk_bf16_f32 v19, v27, v29
	v_cvt_pk_bf16_f32 v20, v31, v33
	v_cvt_pk_bf16_f32 v21, v35, v37
	ds_read2_b32 v[24:25], v12 offset0:49 offset1:57
	ds_read2_b32 v[26:27], v12 offset0:16 offset1:24
	ds_read2_b32 v[28:29], v12 offset0:82 offset1:90
	ds_read2_b32 v[30:31], v12 offset0:115 offset1:123
	ds_read2_b32 v[32:33], v12 offset0:148 offset1:156
	ds_read2_b32 v[34:35], v12 offset0:181 offset1:189
	ds_read2_b32 v[36:37], v12 offset0:214 offset1:222
	ds_read2_b32 v[38:39], v12 offset0:247 offset1:255
	v_lshl_add_u64 v[22:23], v[8:9], 0, v[0:1]
	v_or_b32_e32 v0, s4, v14
	v_lshlrev_b32_e32 v0, 10, v0
	global_store_dwordx4 v[22:23], v[18:21], off
	v_lshl_add_u64 v[22:23], v[8:9], 0, v[0:1]
	v_or_b32_e32 v0, s4, v15
	s_waitcnt lgkmcnt(6)
	v_cvt_pk_bf16_f32 v18, v26, v24
	s_waitcnt lgkmcnt(4)
	v_cvt_pk_bf16_f32 v19, v28, v30
	s_waitcnt lgkmcnt(2)
	v_cvt_pk_bf16_f32 v20, v32, v34
	s_waitcnt lgkmcnt(0)
	v_cvt_pk_bf16_f32 v21, v36, v38
	v_lshlrev_b32_e32 v0, 10, v0
	global_store_dwordx4 v[22:23], v[18:21], off
	v_lshl_add_u64 v[8:9], v[8:9], 0, v[0:1]
	v_readlane_b32 s20, v253, 3
	v_cvt_pk_bf16_f32 v18, v27, v25
	v_cvt_pk_bf16_f32 v19, v29, v31
	v_cvt_pk_bf16_f32 v20, v33, v35
	v_cvt_pk_bf16_f32 v21, v37, v39
	global_store_dwordx4 v[8:9], v[18:21], off
	s_waitcnt lgkmcnt(0)
	v_readlane_b32 s21, v253, 4

.LBB0_130:
	s_lshl_b32 s12, s6, 1
	s_lshl_b32 s13, s7, 1
	v_or_b32_e32 v10, s12, v5
	v_or_b32_e32 v17, s13, v0
	s_add_i32 s14, s12, 4
	s_add_i32 s15, s13, 4
	s_add_i32 s18, s12, 8
	s_add_i32 s19, s13, 8
	s_add_i32 s20, s12, 12
	s_add_i32 s21, s13, 12
	s_add_i32 s22, s12, 16
	s_add_i32 s23, s13, 16
	s_add_i32 s24, s12, 20
	s_add_i32 s25, s13, 20
	s_add_i32 s26, s12, 24
	s_add_i32 s27, s13, 24
	s_add_i32 s28, s12, 28
	s_add_i32 s29, s13, 28
	v_mad_u64_u32 v[18:19], s[10:11], v17, s36, v[8:9]
	v_mad_u64_u32 v[20:21], s[10:11], v10, s36, v[8:9]
	v_or_b32_e32 v10, s14, v5
	v_or_b32_e32 v17, s15, v0
	v_or_b32_e32 v28, s18, v5
	v_or_b32_e32 v26, s19, v0
	v_or_b32_e32 v32, s20, v5
	v_or_b32_e32 v30, s21, v0
	v_or_b32_e32 v36, s22, v5
	v_or_b32_e32 v34, s23, v0
	v_or_b32_e32 v40, s24, v5
	v_or_b32_e32 v38, s25, v0
	v_or_b32_e32 v44, s26, v5
	v_or_b32_e32 v42, s27, v0
	v_or_b32_e32 v48, s28, v5
	v_or_b32_e32 v46, s29, v0
	v_mad_u64_u32 v[22:23], s[10:11], v17, s36, v[8:9]
	v_mad_u64_u32 v[24:25], s[10:11], v10, s36, v[8:9]
	v_mad_u64_u32 v[26:27], s[10:11], v26, s36, v[8:9]
	v_mad_u64_u32 v[28:29], s[10:11], v28, s36, v[8:9]
	v_mad_u64_u32 v[30:31], s[10:11], v30, s36, v[8:9]
	v_mad_u64_u32 v[32:33], s[10:11], v32, s36, v[8:9]
	v_mad_u64_u32 v[34:35], s[10:11], v34, s36, v[8:9]
	v_mad_u64_u32 v[36:37], s[10:11], v36, s36, v[8:9]
	v_mad_u64_u32 v[38:39], s[10:11], v38, s36, v[8:9]
	v_mad_u64_u32 v[40:41], s[10:11], v40, s36, v[8:9]
	v_mad_u64_u32 v[42:43], s[10:11], v42, s36, v[8:9]
	v_mad_u64_u32 v[44:45], s[10:11], v44, s36, v[8:9]
	v_mad_u64_u32 v[46:47], s[10:11], v46, s36, v[8:9]
	v_mad_u64_u32 v[48:49], s[10:11], v48, s36, v[8:9]
	global_load_dword v10, v[18:19], off
	global_load_dword v17, v[20:21], off
	global_load_dword v50, v[22:23], off
	global_load_dword v51, v[24:25], off
	global_load_dword v52, v[26:27], off
	global_load_dword v53, v[28:29], off
	global_load_dword v54, v[30:31], off
	global_load_dword v55, v[32:33], off
	global_load_dword v56, v[34:35], off
	global_load_dword v57, v[36:37], off
	global_load_dword v58, v[38:39], off
	global_load_dword v59, v[40:41], off
	global_load_dword v60, v[42:43], off
	global_load_dword v61, v[44:45], off
	global_load_dword v62, v[46:47], off
	global_load_dword v63, v[48:49], off
	v_or_b32_e32 v20, s12, v3
	v_or_b32_e32 v18, s13, v2
	s_add_i32 s7, s7, 16
	s_add_i32 s6, s6, 16
	s_add_i32 s9, s9, -16
	v_mad_u64_u32 v[18:19], s[10:11], v18, s75, v[4:5]
	v_mad_u64_u32 v[20:21], s[10:11], v20, s75, v[4:5]
	v_or_b32_e32 v19, s14, v3
	v_or_b32_e32 v21, s15, v2
	v_or_b32_e32 v28, s18, v3
	v_or_b32_e32 v26, s19, v2
	v_or_b32_e32 v32, s20, v3
	v_or_b32_e32 v30, s21, v2
	v_or_b32_e32 v36, s22, v3
	v_or_b32_e32 v34, s23, v2
	v_or_b32_e32 v40, s24, v3
	v_or_b32_e32 v38, s25, v2
	v_or_b32_e32 v44, s26, v3
	v_or_b32_e32 v42, s27, v2
	v_or_b32_e32 v48, s28, v3
	v_or_b32_e32 v46, s29, v2
	s_cmp_lg_u32 s9, 0
	v_mad_u64_u32 v[22:23], s[10:11], v21, s75, v[4:5]
	v_mad_u64_u32 v[24:25], s[10:11], v19, s75, v[4:5]
	v_mad_u64_u32 v[26:27], s[10:11], v26, s75, v[4:5]
	v_mad_u64_u32 v[28:29], s[10:11], v28, s75, v[4:5]
	v_mad_u64_u32 v[30:31], s[10:11], v30, s75, v[4:5]
	v_mad_u64_u32 v[32:33], s[10:11], v32, s75, v[4:5]
	v_mad_u64_u32 v[34:35], s[10:11], v34, s75, v[4:5]
	v_mad_u64_u32 v[36:37], s[10:11], v36, s75, v[4:5]
	v_mad_u64_u32 v[38:39], s[10:11], v38, s75, v[4:5]
	v_mad_u64_u32 v[40:41], s[10:11], v40, s75, v[4:5]
	v_mad_u64_u32 v[42:43], s[10:11], v42, s75, v[4:5]
	v_mad_u64_u32 v[44:45], s[10:11], v44, s75, v[4:5]
	v_mad_u64_u32 v[46:47], s[10:11], v46, s75, v[4:5]
	v_mad_u64_u32 v[48:49], s[10:11], v48, s75, v[4:5]
	s_lshl_b32 s12, s6, 1
	s_lshl_b32 s13, s7, 1
	v_or_b32_e32 v99, s12, v5
	v_or_b32_e32 v130, s13, v0
	s_add_i32 s14, s12, 4
	s_add_i32 s15, s13, 4
	s_add_i32 s18, s12, 8
	s_add_i32 s19, s13, 8
	s_add_i32 s20, s12, 12
	s_add_i32 s21, s13, 12
	s_add_i32 s22, s12, 16
	s_add_i32 s23, s13, 16
	s_add_i32 s24, s12, 20
	s_add_i32 s25, s13, 20
	s_add_i32 s26, s12, 24
	s_add_i32 s27, s13, 24
	s_add_i32 s28, s12, 28
	s_add_i32 s29, s13, 28
	v_mad_u64_u32 v[100:101], s[10:11], v130, s36, v[8:9]
	v_mad_u64_u32 v[102:103], s[10:11], v99, s36, v[8:9]
	v_or_b32_e32 v99, s14, v5
	v_or_b32_e32 v130, s15, v0
	v_or_b32_e32 v110, s18, v5
	v_or_b32_e32 v108, s19, v0
	v_or_b32_e32 v114, s20, v5
	v_or_b32_e32 v112, s21, v0
	v_or_b32_e32 v152, s22, v5
	v_or_b32_e32 v116, s23, v0
	v_or_b32_e32 v156, s24, v5
	v_or_b32_e32 v154, s25, v0
	v_or_b32_e32 v160, s26, v5
	v_or_b32_e32 v158, s27, v0
	v_or_b32_e32 v164, s28, v5
	v_or_b32_e32 v162, s29, v0
	v_mad_u64_u32 v[104:105], s[10:11], v130, s36, v[8:9]
	v_mad_u64_u32 v[106:107], s[10:11], v99, s36, v[8:9]
	v_mad_u64_u32 v[108:109], s[10:11], v108, s36, v[8:9]
	v_mad_u64_u32 v[110:111], s[10:11], v110, s36, v[8:9]
	v_mad_u64_u32 v[112:113], s[10:11], v112, s36, v[8:9]
	v_mad_u64_u32 v[114:115], s[10:11], v114, s36, v[8:9]
	v_mad_u64_u32 v[116:117], s[10:11], v116, s36, v[8:9]
	v_mad_u64_u32 v[152:153], s[10:11], v152, s36, v[8:9]
	v_mad_u64_u32 v[154:155], s[10:11], v154, s36, v[8:9]
	v_mad_u64_u32 v[156:157], s[10:11], v156, s36, v[8:9]
	v_mad_u64_u32 v[158:159], s[10:11], v158, s36, v[8:9]
	v_mad_u64_u32 v[160:161], s[10:11], v160, s36, v[8:9]
	v_mad_u64_u32 v[162:163], s[10:11], v162, s36, v[8:9]
	v_mad_u64_u32 v[164:165], s[10:11], v164, s36, v[8:9]
	global_load_dword v99, v[100:101], off
	global_load_dword v130, v[102:103], off
	global_load_dword v166, v[104:105], off
	global_load_dword v167, v[106:107], off
	global_load_dword v168, v[108:109], off
	global_load_dword v169, v[110:111], off
	global_load_dword v170, v[112:113], off
	global_load_dword v171, v[114:115], off
	global_load_dword v172, v[116:117], off
	global_load_dword v173, v[152:153], off
	global_load_dword v174, v[154:155], off
	global_load_dword v175, v[156:157], off
	global_load_dword v176, v[158:159], off
	global_load_dword v177, v[160:161], off
	global_load_dword v178, v[162:163], off
	global_load_dword v179, v[164:165], off
	v_or_b32_e32 v102, s12, v3
	v_or_b32_e32 v100, s13, v2
	s_add_i32 s7, s7, 16
	s_add_i32 s6, s6, 16
	s_add_i32 s9, s9, -16
	v_mad_u64_u32 v[100:101], s[10:11], v100, s75, v[4:5]
	v_mad_u64_u32 v[102:103], s[10:11], v102, s75, v[4:5]
	v_or_b32_e32 v101, s14, v3
	v_or_b32_e32 v103, s15, v2
	v_or_b32_e32 v110, s18, v3
	v_or_b32_e32 v108, s19, v2
	v_or_b32_e32 v114, s20, v3
	v_or_b32_e32 v112, s21, v2
	v_or_b32_e32 v152, s22, v3
	v_or_b32_e32 v116, s23, v2
	v_or_b32_e32 v156, s24, v3
	v_or_b32_e32 v154, s25, v2
	v_or_b32_e32 v160, s26, v3
	v_or_b32_e32 v158, s27, v2
	v_or_b32_e32 v164, s28, v3
	v_or_b32_e32 v162, s29, v2
	s_cmp_lg_u32 s9, 0
	v_mad_u64_u32 v[104:105], s[10:11], v103, s75, v[4:5]
	v_mad_u64_u32 v[106:107], s[10:11], v101, s75, v[4:5]
	v_mad_u64_u32 v[108:109], s[10:11], v108, s75, v[4:5]
	v_mad_u64_u32 v[110:111], s[10:11], v110, s75, v[4:5]
	v_mad_u64_u32 v[112:113], s[10:11], v112, s75, v[4:5]
	v_mad_u64_u32 v[114:115], s[10:11], v114, s75, v[4:5]
	v_mad_u64_u32 v[116:117], s[10:11], v116, s75, v[4:5]
	v_mad_u64_u32 v[152:153], s[10:11], v152, s75, v[4:5]
	v_mad_u64_u32 v[154:155], s[10:11], v154, s75, v[4:5]
	v_mad_u64_u32 v[156:157], s[10:11], v156, s75, v[4:5]
	v_mad_u64_u32 v[158:159], s[10:11], v158, s75, v[4:5]
	v_mad_u64_u32 v[160:161], s[10:11], v160, s75, v[4:5]
	v_mad_u64_u32 v[162:163], s[10:11], v162, s75, v[4:5]
	v_mad_u64_u32 v[164:165], s[10:11], v164, s75, v[4:5]
	s_waitcnt vmcnt(31)
	ds_write_b32 v18, v10
	s_waitcnt vmcnt(30)
	ds_write_b32 v20, v17
	s_waitcnt vmcnt(29)
	ds_write_b32 v22, v50
	s_waitcnt vmcnt(28)
	ds_write_b32 v24, v51
	s_waitcnt vmcnt(27)
	ds_write_b32 v26, v52
	s_waitcnt vmcnt(26)
	ds_write_b32 v28, v53
	s_waitcnt vmcnt(25)
	ds_write_b32 v30, v54
	s_waitcnt vmcnt(24)
	ds_write_b32 v32, v55
	s_waitcnt vmcnt(23)
	ds_write_b32 v34, v56
	s_waitcnt vmcnt(22)
	ds_write_b32 v36, v57
	s_waitcnt vmcnt(21)
	ds_write_b32 v38, v58
	s_waitcnt vmcnt(20)
	ds_write_b32 v40, v59
	s_waitcnt vmcnt(19)
	ds_write_b32 v42, v60
	s_waitcnt vmcnt(18)
	ds_write_b32 v44, v61
	s_waitcnt vmcnt(17)
	ds_write_b32 v46, v62
	s_waitcnt vmcnt(16)
	ds_write_b32 v48, v63
	s_waitcnt vmcnt(15)
	ds_write_b32 v100, v99
	s_waitcnt vmcnt(14)
	ds_write_b32 v102, v130
	s_waitcnt vmcnt(13)
	ds_write_b32 v104, v166
	s_waitcnt vmcnt(12)
	ds_write_b32 v106, v167
	s_waitcnt vmcnt(11)
	ds_write_b32 v108, v168
	s_waitcnt vmcnt(10)
	ds_write_b32 v110, v169
	s_waitcnt vmcnt(9)
	ds_write_b32 v112, v170
	s_waitcnt vmcnt(8)
	ds_write_b32 v114, v171
	s_waitcnt vmcnt(7)
	ds_write_b32 v116, v172
	s_waitcnt vmcnt(6)
	ds_write_b32 v152, v173
	s_waitcnt vmcnt(5)
	ds_write_b32 v154, v174
	s_waitcnt vmcnt(4)
	ds_write_b32 v156, v175
	s_waitcnt vmcnt(3)
	ds_write_b32 v158, v176
	s_waitcnt vmcnt(2)
	ds_write_b32 v160, v177
	s_waitcnt vmcnt(1)
	ds_write_b32 v162, v178
	s_waitcnt vmcnt(0)
	ds_write_b32 v164, v179
	v_mov_b32_e32 v10, v99
	v_mov_b32_e32 v17, v130
	v_mov_b32_e32 v40, v156
	v_mov_b32_e32 v41, v157
	v_mov_b32_e32 v42, v158
	v_mov_b32_e32 v43, v159
	v_mov_b32_e32 v44, v160
	v_mov_b32_e32 v45, v161
	v_mov_b32_e32 v46, v162
	v_mov_b32_e32 v47, v163
	v_mov_b32_e32 v48, v164
	v_mov_b32_e32 v49, v165
	v_mov_b32_e32 v50, v166
	v_mov_b32_e32 v51, v167
	v_mov_b32_e32 v52, v168
	v_mov_b32_e32 v53, v169
	v_mov_b32_e32 v54, v170
	v_mov_b32_e32 v55, v171
	v_mov_b32_e32 v56, v172
	v_mov_b32_e32 v57, v173
	v_mov_b32_e32 v58, v174
	v_mov_b32_e32 v59, v175
	v_mov_b32_e32 v60, v176
	v_mov_b32_e32 v61, v177
	s_waitcnt lgkmcnt(0)
	s_and_b32 s5, 0xffff, s5
	s_lshl_b32 s5, s5, 1
	ds_read2_b32 v[22:23], v12 offset0:33 offset1:41
	ds_read2_b32 v[24:25], v12 offset1:8
	ds_read2_b32 v[26:27], v12 offset0:66 offset1:74
	ds_read2_b32 v[28:29], v12 offset0:99 offset1:107
	ds_read2_b32 v[30:31], v12 offset0:132 offset1:140
	ds_read2_b32 v[32:33], v12 offset0:165 offset1:173
	ds_read2_b32 v[34:35], v12 offset0:198 offset1:206
	ds_read2_b32 v[36:37], v12 offset0:231 offset1:239
	s_add_u32 s2, s2, s5
	s_addc_u32 s3, s3, 0
	v_lshlrev_b32_e32 v0, 1, v6
	v_lshl_add_u64 v[8:9], s[2:3], 0, v[0:1]
	s_mov_b64 s[2:3], 0x800000
	v_or_b32_e32 v0, s4, v11
	v_lshl_add_u64 v[8:9], v[8:9], 0, s[2:3]
	v_lshlrev_b32_e32 v0, 11, v0
	s_waitcnt lgkmcnt(6)
	v_cvt_pk_bf16_f32 v18, v24, v22
	s_waitcnt lgkmcnt(4)
	v_cvt_pk_bf16_f32 v19, v26, v28
	s_waitcnt lgkmcnt(2)
	v_cvt_pk_bf16_f32 v20, v30, v32
	s_waitcnt lgkmcnt(0)
	v_cvt_pk_bf16_f32 v21, v34, v36
	v_lshl_add_u64 v[38:39], v[8:9], 0, v[0:1]
	global_store_dwordx4 v[38:39], v[18:21], off
	v_or_b32_e32 v0, s4, v13
	v_lshlrev_b32_e32 v0, 11, v0
	v_cvt_pk_bf16_f32 v18, v25, v23
	v_cvt_pk_bf16_f32 v19, v27, v29
	v_cvt_pk_bf16_f32 v20, v31, v33
	v_cvt_pk_bf16_f32 v21, v35, v37
	ds_read2_b32 v[24:25], v12 offset0:49 offset1:57
	ds_read2_b32 v[26:27], v12 offset0:16 offset1:24
	ds_read2_b32 v[28:29], v12 offset0:82 offset1:90
	ds_read2_b32 v[30:31], v12 offset0:115 offset1:123
	ds_read2_b32 v[32:33], v12 offset0:148 offset1:156
	ds_read2_b32 v[34:35], v12 offset0:181 offset1:189
	ds_read2_b32 v[36:37], v12 offset0:214 offset1:222
	ds_read2_b32 v[38:39], v12 offset0:247 offset1:255
	v_lshl_add_u64 v[22:23], v[8:9], 0, v[0:1]
	v_or_b32_e32 v0, s4, v14
	v_lshlrev_b32_e32 v0, 11, v0
	global_store_dwordx4 v[22:23], v[18:21], off
	v_lshl_add_u64 v[22:23], v[8:9], 0, v[0:1]
	v_or_b32_e32 v0, s4, v15
	s_waitcnt lgkmcnt(6)
	v_cvt_pk_bf16_f32 v18, v26, v24
	s_waitcnt lgkmcnt(4)
	v_cvt_pk_bf16_f32 v19, v28, v30
	s_waitcnt lgkmcnt(2)
	v_cvt_pk_bf16_f32 v20, v32, v34
	s_waitcnt lgkmcnt(0)
	v_cvt_pk_bf16_f32 v21, v36, v38
	v_lshlrev_b32_e32 v0, 11, v0
	global_store_dwordx4 v[22:23], v[18:21], off
	v_lshl_add_u64 v[8:9], v[8:9], 0, v[0:1]
	v_readlane_b32 s20, v253, 3
	v_cvt_pk_bf16_f32 v18, v27, v25
	v_cvt_pk_bf16_f32 v19, v29, v31
	v_cvt_pk_bf16_f32 v20, v33, v35
	v_cvt_pk_bf16_f32 v21, v37, v39
	global_store_dwordx4 v[8:9], v[18:21], off
	s_waitcnt lgkmcnt(0)
	v_readlane_b32 s21, v253, 4
